# v8 + nt on the once-read f32 weight loads of both weight-conversion loops
# speedup vs baseline: 1.0018x; 1.0018x over previous
.LBB0_32:
	s_cmpk_gt_i32 s47, 0x15ff
	s_mov_b64 s[8:9], -1
	s_cbranch_scc0 .LBB0_50
	s_cmpk_gt_u32 s47, 0x20ff
	s_cbranch_scc0 .LBB0_47
	s_cmpk_gt_u32 s47, 0x2cff
	s_cbranch_scc0 .LBB0_44
	s_cmpk_gt_u32 s47, 0x30ff
	s_cbranch_scc0 .LBB0_41
	s_cmpk_gt_u32 s47, 0x46ff
	s_cbranch_scc0 .LBB0_38
	s_load_dwordx2 s[10:11], s[16:17], 0x98
	s_add_i32 s8, s20, 0xffee4000
	s_and_b32 s9, s22, 0x1fc0
	s_and_b32 s8, s8, 0x7c0
	s_add_i32 s6, s47, 0xffffb900
	v_add_u32_e32 v6, s9, v5
	s_lshl_b32 s9, s8, 2
	s_waitcnt lgkmcnt(0)
	s_add_u32 s10, s10, s9
	s_addc_u32 s11, s11, 0
	v_ashrrev_i32_e32 v7, 31, v6
	v_lshl_add_u64 v[46:47], s[10:11], 0, v[2:3]
	v_lshlrev_b64 v[6:7], 13, v[6:7]
	v_lshl_add_u64 v[6:7], v[46:47], 0, v[6:7]
	v_add_co_u32_e32 v50, vcc, s25, v6
	v_add_u32_e32 v45, 0x400, v10
	s_nop 0
	v_addc_co_u32_e32 v51, vcc, 0, v7, vcc
	v_add_co_u32_e32 v54, vcc, s26, v6
	global_load_dwordx4 v[46:49], v[6:7], off nt
	s_nop 0
	global_load_dwordx4 v[50:53], v[50:51], off nt
	v_addc_co_u32_e32 v55, vcc, 0, v7, vcc
	v_add_co_u32_e32 v58, vcc, s27, v6
	s_lshr_b32 s6, s6, 5
	s_nop 0
	v_addc_co_u32_e32 v59, vcc, 0, v7, vcc
	v_add_co_u32_e32 v62, vcc, s28, v6
	global_load_dwordx4 v[54:57], v[54:55], off nt
	s_nop 0
	global_load_dwordx4 v[58:61], v[58:59], off nt
	v_addc_co_u32_e32 v63, vcc, 0, v7, vcc
	v_add_co_u32_e32 v66, vcc, s29, v6
	s_nop 1
	v_addc_co_u32_e32 v67, vcc, 0, v7, vcc
	v_add_co_u32_e32 v70, vcc, s30, v6
	global_load_dwordx4 v[62:65], v[62:63], off nt
	s_nop 0
	global_load_dwordx4 v[66:69], v[66:67], off nt
	v_addc_co_u32_e32 v71, vcc, 0, v7, vcc
	v_add_co_u32_e32 v74, vcc, s31, v6
	s_nop 1
	v_addc_co_u32_e32 v75, vcc, 0, v7, vcc
	v_add_co_u32_e32 v78, vcc, s33, v6
	global_load_dwordx4 v[70:73], v[70:71], off nt
	s_nop 0
	global_load_dwordx4 v[74:77], v[74:75], off nt
	v_addc_co_u32_e32 v79, vcc, 0, v7, vcc
	v_add_co_u32_e32 v82, vcc, s34, v6
	s_nop 1
	v_addc_co_u32_e32 v83, vcc, 0, v7, vcc
	v_add_co_u32_e32 v86, vcc, s35, v6
	global_load_dwordx4 v[78:81], v[78:79], off nt
	s_nop 0
	global_load_dwordx4 v[82:85], v[82:83], off nt
	v_addc_co_u32_e32 v87, vcc, 0, v7, vcc
	v_add_co_u32_e32 v90, vcc, s36, v6
	s_nop 1
	v_addc_co_u32_e32 v91, vcc, 0, v7, vcc
	global_load_dwordx4 v[86:89], v[86:87], off nt
	s_nop 0
	global_load_dwordx4 v[90:93], v[90:91], off nt
	v_add_co_u32_e32 v94, vcc, s37, v6
	s_nop 1
	v_addc_co_u32_e32 v95, vcc, 0, v7, vcc
	global_load_dwordx4 v[94:97], v[94:95], off nt
	v_add_co_u32_e32 v98, vcc, s38, v6
	s_nop 1
	v_addc_co_u32_e32 v99, vcc, 0, v7, vcc
	global_load_dwordx4 v[98:101], v[98:99], off nt
	v_add_co_u32_e32 v102, vcc, s39, v6
	s_nop 1
	v_addc_co_u32_e32 v103, vcc, 0, v7, vcc
	global_load_dwordx4 v[102:105], v[102:103], off nt
	v_add_co_u32_e32 v6, vcc, s40, v6
	s_nop 1
	v_addc_co_u32_e32 v7, vcc, 0, v7, vcc
	global_load_dwordx4 v[106:109], v[6:7], off nt
	v_add_u32_e32 v6, 0x2498, v8
	s_waitcnt vmcnt(15)
	ds_write2_b32 v8, v46, v47 offset1:1
	ds_write2_b32 v8, v48, v49 offset0:2 offset1:3
	s_waitcnt vmcnt(14)
	ds_write2_b32 v26, v50, v51 offset1:1
	ds_write2_b32 v27, v52, v53 offset1:1
	s_waitcnt vmcnt(13)
	ds_write2_b32 v28, v54, v55 offset1:1
	ds_write2_b32 v29, v56, v57 offset1:1
	s_waitcnt vmcnt(12)
	ds_write2_b32 v30, v58, v59 offset1:1
	ds_write2_b32 v31, v60, v61 offset1:1
	s_waitcnt vmcnt(11)
	ds_write2_b32 v32, v62, v63 offset1:1
	ds_write2_b32 v33, v64, v65 offset1:1
	s_waitcnt vmcnt(10)
	ds_write2_b32 v34, v66, v67 offset1:1
	ds_write2_b32 v35, v68, v69 offset1:1
	s_waitcnt vmcnt(9)
	ds_write2_b32 v36, v70, v71 offset1:1
	ds_write2_b32 v37, v72, v73 offset1:1
	s_waitcnt vmcnt(8)
	ds_write2_b32 v38, v74, v75 offset1:1
	ds_write2_b32 v39, v76, v77 offset1:1
	s_waitcnt vmcnt(7)
	ds_write2_b32 v40, v78, v79 offset1:1
	ds_write2_b32 v41, v80, v81 offset1:1
	s_waitcnt vmcnt(6)
	ds_write2_b32 v42, v82, v83 offset1:1
	ds_write2_b32 v6, v84, v85 offset1:1
	v_add_u32_e32 v6, 0x28a0, v8
	v_mov_b32_e32 v67, v3
	v_mov_b32_e32 v69, v3
	s_waitcnt vmcnt(5)
	ds_write2_b32 v6, v86, v87 offset1:1
	v_add_u32_e32 v6, 0x28a8, v8
	ds_write2_b32 v6, v88, v89 offset1:1
	v_add_u32_e32 v6, 0x2cb0, v8
	s_waitcnt vmcnt(4)
	ds_write2_b32 v6, v90, v91 offset1:1
	v_add_u32_e32 v6, 0x2cb8, v8
	ds_write2_b32 v6, v92, v93 offset1:1
	v_add_u32_e32 v6, 0x30c0, v8
	s_waitcnt vmcnt(3)
	ds_write2_b32 v6, v94, v95 offset1:1
	v_add_u32_e32 v6, 0x30c8, v8
	ds_write2_b32 v6, v96, v97 offset1:1
	v_add_u32_e32 v6, 0x34d0, v8
	s_waitcnt vmcnt(2)
	ds_write2_b32 v6, v98, v99 offset1:1
	v_add_u32_e32 v6, 0x34d8, v8
	ds_write2_b32 v6, v100, v101 offset1:1
	v_add_u32_e32 v6, 0x38e0, v8
	s_waitcnt vmcnt(1)
	ds_write2_b32 v6, v102, v103 offset1:1
	v_add_u32_e32 v6, 0x38e8, v8
	ds_write2_b32 v6, v104, v105 offset1:1
	v_add_u32_e32 v6, 0x3cf0, v8
	s_waitcnt vmcnt(0)
	ds_write2_b32 v6, v106, v107 offset1:1
	v_add_u32_e32 v6, 0x3cf8, v8
	ds_write2_b32 v6, v108, v109 offset1:1
	s_waitcnt lgkmcnt(0)
	ds_read2_b32 v[50:51], v10 offset1:8
	ds_read2_b32 v[52:53], v10 offset0:65 offset1:73
	ds_read2_b32 v[54:55], v10 offset0:130 offset1:138
	ds_read2_b32 v[56:57], v10 offset0:195 offset1:203
	ds_read2_b32 v[58:59], v45 offset0:4 offset1:12
	s_waitcnt lgkmcnt(4)
	v_bfe_u32 v6, v50, 16, 1
	v_add3_u32 v6, v50, v6, s41
	s_waitcnt lgkmcnt(3)
	v_bfe_u32 v7, v52, 16, 1
	v_lshrrev_b32_e32 v6, 16, v6
	v_add3_u32 v7, v52, v7, s41
	ds_read2_b32 v[60:61], v45 offset0:69 offset1:77
	v_and_or_b32 v46, v7, s42, v6
	s_waitcnt lgkmcnt(3)
	v_bfe_u32 v6, v54, 16, 1
	v_add3_u32 v6, v54, v6, s41
	s_waitcnt lgkmcnt(2)
	v_bfe_u32 v7, v56, 16, 1
	ds_read2_b32 v[62:63], v45 offset0:134 offset1:142
	v_lshrrev_b32_e32 v6, 16, v6
	v_add3_u32 v7, v56, v7, s41
	ds_read2_b32 v[64:65], v45 offset0:199 offset1:207
	v_and_or_b32 v47, v7, s42, v6
	s_waitcnt lgkmcnt(3)
	v_bfe_u32 v6, v58, 16, 1
	v_add3_u32 v6, v58, v6, s41
	s_waitcnt lgkmcnt(2)
	v_bfe_u32 v7, v60, 16, 1
	v_lshrrev_b32_e32 v6, 16, v6
	v_add3_u32 v7, v60, v7, s41
	v_and_or_b32 v48, v7, s42, v6
	s_waitcnt lgkmcnt(1)
	v_bfe_u32 v6, v62, 16, 1
	v_add3_u32 v6, v62, v6, s41
	s_waitcnt lgkmcnt(0)
	v_bfe_u32 v7, v64, 16, 1
	v_lshrrev_b32_e32 v6, 16, v6
	v_add3_u32 v7, v64, v7, s41
	v_add_u32_e32 v50, s8, v9
	v_and_or_b32 v49, v7, s42, v6
	v_lshrrev_b32_e32 v6, 8, v50
	v_mul_i32_i24_e32 v6, 0x58, v6
	v_ashrrev_i32_e32 v7, 31, v6
	v_lshl_add_u64 v[6:7], v[6:7], 0, s[6:7]
	v_lshlrev_b64 v[6:7], 15, v[6:7]
	v_lshlrev_b32_e32 v50, 7, v50
	v_lshl_add_u64 v[6:7], s[0:1], 0, v[6:7]
	v_and_b32_e32 v66, 0x7f80, v50
	v_lshl_add_u64 v[66:67], v[6:7], 0, v[66:67]
	v_lshlrev_b32_e32 v6, 1, v4
	v_mov_b32_e32 v7, v3
	v_lshl_add_u64 v[66:67], v[66:67], 0, v[6:7]
	global_store_dwordx4 v[66:67], v[46:49], off
	v_bfe_u32 v50, v65, 16, 1
	v_add3_u32 v50, v65, v50, s41
	v_bfe_u32 v46, v51, 16, 1
	v_add3_u32 v46, v51, v46, s41
	v_bfe_u32 v47, v53, 16, 1
	v_lshrrev_b32_e32 v46, 16, v46
	v_add3_u32 v47, v53, v47, s41
	v_and_or_b32 v46, v47, s42, v46
	v_bfe_u32 v47, v55, 16, 1
	v_add3_u32 v47, v55, v47, s41
	v_bfe_u32 v48, v57, 16, 1
	v_lshrrev_b32_e32 v47, 16, v47
	v_add3_u32 v48, v57, v48, s41
	v_and_or_b32 v47, v48, s42, v47
	v_bfe_u32 v48, v59, 16, 1
	v_add3_u32 v48, v59, v48, s41
	v_bfe_u32 v49, v61, 16, 1
	v_lshrrev_b32_e32 v48, 16, v48
	v_add3_u32 v49, v61, v49, s41
	v_and_or_b32 v48, v49, s42, v48
	v_bfe_u32 v49, v63, 16, 1
	v_add3_u32 v49, v63, v49, s41
	v_lshrrev_b32_e32 v49, 16, v49
	v_add_u32_e32 v52, s8, v11
	v_and_or_b32 v49, v50, s42, v49
	v_lshrrev_b32_e32 v50, 8, v52
	v_mul_i32_i24_e32 v50, 0x58, v50
	v_ashrrev_i32_e32 v51, 31, v50
	v_lshl_add_u64 v[50:51], v[50:51], 0, s[6:7]
	v_lshlrev_b64 v[50:51], 15, v[50:51]
	v_lshlrev_b32_e32 v52, 7, v52
	v_lshl_add_u64 v[50:51], s[0:1], 0, v[50:51]
	v_and_b32_e32 v52, 0x7f80, v52
	v_mov_b32_e32 v53, v3
	v_lshl_add_u64 v[50:51], v[50:51], 0, v[52:53]
	ds_read2_b32 v[54:55], v10 offset0:16 offset1:24
	v_lshl_add_u64 v[50:51], v[50:51], 0, v[6:7]
	global_store_dwordx4 v[50:51], v[46:49], off
	ds_read2_b32 v[50:51], v10 offset0:81 offset1:89
	ds_read2_b32 v[52:53], v10 offset0:146 offset1:154
	ds_read2_b32 v[56:57], v10 offset0:211 offset1:219
	s_waitcnt lgkmcnt(3)
	v_bfe_u32 v46, v54, 16, 1
	v_add3_u32 v46, v54, v46, s41
	s_waitcnt lgkmcnt(2)
	v_bfe_u32 v47, v50, 16, 1
	ds_read2_b32 v[58:59], v45 offset0:20 offset1:28
	v_lshrrev_b32_e32 v46, 16, v46
	v_add3_u32 v47, v50, v47, s41
	ds_read2_b32 v[60:61], v45 offset0:85 offset1:93
	v_and_or_b32 v46, v47, s42, v46
	s_waitcnt lgkmcnt(3)
	v_bfe_u32 v47, v52, 16, 1
	v_add3_u32 v47, v52, v47, s41
	s_waitcnt lgkmcnt(2)
	v_bfe_u32 v48, v56, 16, 1
	ds_read2_b32 v[62:63], v45 offset0:150 offset1:158
	v_lshrrev_b32_e32 v47, 16, v47
	v_add3_u32 v48, v56, v48, s41
	ds_read2_b32 v[64:65], v45 offset0:215 offset1:223
	v_and_or_b32 v47, v48, s42, v47
	s_waitcnt lgkmcnt(3)
	v_bfe_u32 v48, v58, 16, 1
	v_add3_u32 v48, v58, v48, s41
	s_waitcnt lgkmcnt(2)
	v_bfe_u32 v49, v60, 16, 1
	v_lshrrev_b32_e32 v48, 16, v48
	v_add3_u32 v49, v60, v49, s41
	v_and_or_b32 v48, v49, s42, v48
	s_waitcnt lgkmcnt(1)
	v_bfe_u32 v49, v62, 16, 1
	v_add3_u32 v49, v62, v49, s41
	s_waitcnt lgkmcnt(0)
	v_bfe_u32 v50, v64, 16, 1
	v_lshrrev_b32_e32 v49, 16, v49
	v_add3_u32 v50, v64, v50, s41
	v_and_or_b32 v49, v50, s42, v49
	v_add_u32_e32 v50, s8, v12
	v_lshrrev_b32_e32 v52, 8, v50
	v_mul_i32_i24_e32 v66, 0x58, v52
	v_ashrrev_i32_e32 v67, 31, v66
	v_lshl_add_u64 v[66:67], v[66:67], 0, s[6:7]
	v_lshlrev_b64 v[66:67], 15, v[66:67]
	v_lshlrev_b32_e32 v50, 7, v50
	v_lshl_add_u64 v[66:67], s[0:1], 0, v[66:67]
	v_and_b32_e32 v68, 0x7f80, v50
	v_lshl_add_u64 v[66:67], v[66:67], 0, v[68:69]
	v_lshl_add_u64 v[66:67], v[66:67], 0, v[6:7]
	global_store_dwordx4 v[66:67], v[46:49], off
	v_bfe_u32 v50, v65, 16, 1
	v_add3_u32 v50, v65, v50, s41
	v_bfe_u32 v46, v55, 16, 1
	v_add3_u32 v46, v55, v46, s41
	v_bfe_u32 v47, v51, 16, 1
	v_lshrrev_b32_e32 v46, 16, v46
	v_add3_u32 v47, v51, v47, s41
	v_and_or_b32 v46, v47, s42, v46
	v_bfe_u32 v47, v53, 16, 1
	v_add3_u32 v47, v53, v47, s41
	v_bfe_u32 v48, v57, 16, 1
	v_lshrrev_b32_e32 v47, 16, v47
	v_add3_u32 v48, v57, v48, s41
	v_and_or_b32 v47, v48, s42, v47
	v_bfe_u32 v48, v59, 16, 1
	v_add3_u32 v48, v59, v48, s41
	v_bfe_u32 v49, v61, 16, 1
	v_lshrrev_b32_e32 v48, 16, v48
	v_add3_u32 v49, v61, v49, s41
	v_and_or_b32 v48, v49, s42, v48
	v_bfe_u32 v49, v63, 16, 1
	v_add3_u32 v49, v63, v49, s41
	v_lshrrev_b32_e32 v49, 16, v49
	v_add_u32_e32 v52, s8, v13
	v_and_or_b32 v49, v50, s42, v49
	v_lshrrev_b32_e32 v50, 8, v52
	v_mul_i32_i24_e32 v50, 0x58, v50
	v_ashrrev_i32_e32 v51, 31, v50
	v_lshl_add_u64 v[50:51], v[50:51], 0, s[6:7]
	v_lshlrev_b64 v[50:51], 15, v[50:51]
	v_lshlrev_b32_e32 v52, 7, v52
	v_lshl_add_u64 v[50:51], s[0:1], 0, v[50:51]
	v_and_b32_e32 v52, 0x7f80, v52
	v_mov_b32_e32 v53, v3
	v_lshl_add_u64 v[50:51], v[50:51], 0, v[52:53]
	ds_read2_b32 v[54:55], v10 offset0:32 offset1:40
	v_lshl_add_u64 v[50:51], v[50:51], 0, v[6:7]
	global_store_dwordx4 v[50:51], v[46:49], off
	ds_read2_b32 v[50:51], v10 offset0:97 offset1:105
	ds_read2_b32 v[52:53], v10 offset0:162 offset1:170
	ds_read2_b32 v[56:57], v10 offset0:227 offset1:235
	s_waitcnt lgkmcnt(3)
	v_bfe_u32 v46, v54, 16, 1
	v_add3_u32 v46, v54, v46, s41
	s_waitcnt lgkmcnt(2)
	v_bfe_u32 v47, v50, 16, 1
	ds_read2_b32 v[58:59], v45 offset0:36 offset1:44
	v_lshrrev_b32_e32 v46, 16, v46
	v_add3_u32 v47, v50, v47, s41
	ds_read2_b32 v[60:61], v45 offset0:101 offset1:109
	v_and_or_b32 v46, v47, s42, v46
	s_waitcnt lgkmcnt(3)
	v_bfe_u32 v47, v52, 16, 1
	v_add3_u32 v47, v52, v47, s41
	s_waitcnt lgkmcnt(2)
	v_bfe_u32 v48, v56, 16, 1
	ds_read2_b32 v[62:63], v45 offset0:166 offset1:174
	v_lshrrev_b32_e32 v47, 16, v47
	v_add3_u32 v48, v56, v48, s41
	ds_read2_b32 v[64:65], v45 offset0:231 offset1:239
	v_and_or_b32 v47, v48, s42, v47
	s_waitcnt lgkmcnt(3)
	v_bfe_u32 v48, v58, 16, 1
	v_add3_u32 v48, v58, v48, s41
	s_waitcnt lgkmcnt(2)
	v_bfe_u32 v49, v60, 16, 1
	v_lshrrev_b32_e32 v48, 16, v48
	v_add3_u32 v49, v60, v49, s41
	v_and_or_b32 v48, v49, s42, v48
	s_waitcnt lgkmcnt(1)
	v_bfe_u32 v49, v62, 16, 1
	v_add3_u32 v49, v62, v49, s41
	s_waitcnt lgkmcnt(0)
	v_bfe_u32 v50, v64, 16, 1
	v_lshrrev_b32_e32 v49, 16, v49
	v_add3_u32 v50, v64, v50, s41
	v_and_or_b32 v49, v50, s42, v49
	v_add_u32_e32 v50, s8, v14
	v_lshrrev_b32_e32 v52, 8, v50
	v_mul_i32_i24_e32 v66, 0x58, v52
	v_ashrrev_i32_e32 v67, 31, v66
	v_lshl_add_u64 v[66:67], v[66:67], 0, s[6:7]
	v_lshlrev_b64 v[66:67], 15, v[66:67]
	v_lshlrev_b32_e32 v50, 7, v50
	v_lshl_add_u64 v[66:67], s[0:1], 0, v[66:67]
	v_and_b32_e32 v68, 0x7f80, v50
	v_lshl_add_u64 v[66:67], v[66:67], 0, v[68:69]
	v_lshl_add_u64 v[66:67], v[66:67], 0, v[6:7]
	global_store_dwordx4 v[66:67], v[46:49], off
	v_bfe_u32 v50, v65, 16, 1
	v_add3_u32 v50, v65, v50, s41
	v_bfe_u32 v46, v55, 16, 1
	v_add3_u32 v46, v55, v46, s41
	v_bfe_u32 v47, v51, 16, 1
	v_lshrrev_b32_e32 v46, 16, v46
	v_add3_u32 v47, v51, v47, s41
	v_and_or_b32 v46, v47, s42, v46
	v_bfe_u32 v47, v53, 16, 1
	v_add3_u32 v47, v53, v47, s41
	v_bfe_u32 v48, v57, 16, 1
	v_lshrrev_b32_e32 v47, 16, v47
	v_add3_u32 v48, v57, v48, s41
	v_and_or_b32 v47, v48, s42, v47
	v_bfe_u32 v48, v59, 16, 1
	v_add3_u32 v48, v59, v48, s41
	v_bfe_u32 v49, v61, 16, 1
	v_lshrrev_b32_e32 v48, 16, v48
	v_add3_u32 v49, v61, v49, s41
	v_and_or_b32 v48, v49, s42, v48
	v_bfe_u32 v49, v63, 16, 1
	v_add3_u32 v49, v63, v49, s41
	v_lshrrev_b32_e32 v49, 16, v49
	v_add_u32_e32 v52, s8, v15
	v_and_or_b32 v49, v50, s42, v49
	v_lshrrev_b32_e32 v50, 8, v52
	v_mul_i32_i24_e32 v50, 0x58, v50
	v_ashrrev_i32_e32 v51, 31, v50
	v_lshl_add_u64 v[50:51], v[50:51], 0, s[6:7]
	v_lshlrev_b64 v[50:51], 15, v[50:51]
	v_lshlrev_b32_e32 v52, 7, v52
	v_lshl_add_u64 v[50:51], s[0:1], 0, v[50:51]
	v_and_b32_e32 v52, 0x7f80, v52
	v_mov_b32_e32 v53, v3
	v_lshl_add_u64 v[50:51], v[50:51], 0, v[52:53]
	ds_read2_b32 v[54:55], v10 offset0:48 offset1:56
	v_lshl_add_u64 v[50:51], v[50:51], 0, v[6:7]
	global_store_dwordx4 v[50:51], v[46:49], off
	ds_read2_b32 v[50:51], v10 offset0:113 offset1:121
	ds_read2_b32 v[52:53], v10 offset0:178 offset1:186
	ds_read2_b32 v[56:57], v10 offset0:243 offset1:251
	s_waitcnt lgkmcnt(3)
	v_bfe_u32 v46, v54, 16, 1
	v_add3_u32 v46, v54, v46, s41
	s_waitcnt lgkmcnt(2)
	v_bfe_u32 v47, v50, 16, 1
	ds_read2_b32 v[58:59], v45 offset0:52 offset1:60
	v_lshrrev_b32_e32 v46, 16, v46
	v_add3_u32 v47, v50, v47, s41
	ds_read2_b32 v[60:61], v45 offset0:117 offset1:125
	v_and_or_b32 v46, v47, s42, v46
	s_waitcnt lgkmcnt(3)
	v_bfe_u32 v47, v52, 16, 1
	ds_read2_b32 v[62:63], v45 offset0:182 offset1:190
	v_add3_u32 v47, v52, v47, s41
	s_waitcnt lgkmcnt(3)
	v_bfe_u32 v48, v56, 16, 1
	ds_read2_b32 v[64:65], v45 offset0:247 offset1:255
	v_lshrrev_b32_e32 v47, 16, v47
	v_add3_u32 v48, v56, v48, s41
	v_and_or_b32 v47, v48, s42, v47
	s_waitcnt lgkmcnt(3)
	v_bfe_u32 v48, v58, 16, 1
	v_add3_u32 v48, v58, v48, s41
	s_waitcnt lgkmcnt(2)
	v_bfe_u32 v49, v60, 16, 1
	v_lshrrev_b32_e32 v48, 16, v48
	v_add3_u32 v49, v60, v49, s41
	s_waitcnt lgkmcnt(1)
	v_bfe_u32 v45, v62, 16, 1
	v_and_or_b32 v48, v49, s42, v48
	v_add3_u32 v45, v62, v45, s41
	s_waitcnt lgkmcnt(0)
	v_bfe_u32 v49, v64, 16, 1
	v_lshrrev_b32_e32 v45, 16, v45
	v_add3_u32 v49, v64, v49, s41
	v_and_or_b32 v49, v49, s42, v45
	v_add_u32_e32 v45, s8, v16
	v_lshrrev_b32_e32 v50, 8, v45
	v_mul_i32_i24_e32 v66, 0x58, v50
	v_ashrrev_i32_e32 v67, 31, v66
	v_lshl_add_u64 v[66:67], v[66:67], 0, s[6:7]
	v_lshlrev_b64 v[66:67], 15, v[66:67]
	v_lshlrev_b32_e32 v45, 7, v45
	v_lshl_add_u64 v[66:67], s[0:1], 0, v[66:67]
	v_and_b32_e32 v68, 0x7f80, v45
	v_lshl_add_u64 v[66:67], v[66:67], 0, v[68:69]
	v_lshl_add_u64 v[66:67], v[66:67], 0, v[6:7]
	v_bfe_u32 v45, v55, 16, 1
	global_store_dwordx4 v[66:67], v[46:49], off
	v_add3_u32 v45, v55, v45, s41
	v_lshrrev_b32_e32 v45, 16, v45
	v_bfe_u32 v46, v51, 16, 1
	v_add3_u32 v46, v51, v46, s41
	v_and_or_b32 v46, v46, s42, v45
	v_bfe_u32 v45, v53, 16, 1
	v_add3_u32 v45, v53, v45, s41
	v_bfe_u32 v47, v57, 16, 1
	v_lshrrev_b32_e32 v45, 16, v45
	v_add3_u32 v47, v57, v47, s41
	v_and_or_b32 v47, v47, s42, v45
	v_bfe_u32 v45, v59, 16, 1
	v_add3_u32 v45, v59, v45, s41
	v_bfe_u32 v48, v61, 16, 1
	v_lshrrev_b32_e32 v45, 16, v45
	v_add3_u32 v48, v61, v48, s41
	v_and_or_b32 v48, v48, s42, v45
	v_bfe_u32 v45, v63, 16, 1
	v_add3_u32 v45, v63, v45, s41
	v_bfe_u32 v49, v65, 16, 1
	v_lshrrev_b32_e32 v45, 16, v45
	v_add3_u32 v49, v65, v49, s41
	v_and_or_b32 v49, v49, s42, v45
	v_add_u32_e32 v45, s8, v17
	v_lshrrev_b32_e32 v50, 8, v45
	v_mul_i32_i24_e32 v50, 0x58, v50
	v_ashrrev_i32_e32 v51, 31, v50
	v_lshl_add_u64 v[50:51], v[50:51], 0, s[6:7]
	v_lshlrev_b64 v[50:51], 15, v[50:51]
	v_lshlrev_b32_e32 v45, 7, v45
	v_lshl_add_u64 v[50:51], s[0:1], 0, v[50:51]
	v_and_b32_e32 v52, 0x7f80, v45
	v_mov_b32_e32 v53, v3
	v_lshl_add_u64 v[50:51], v[50:51], 0, v[52:53]
	v_lshl_add_u64 v[6:7], v[50:51], 0, v[6:7]
	global_store_dwordx4 v[6:7], v[46:49], off
	s_waitcnt lgkmcnt(0)
	s_mov_b64 s[8:9], 0
.LBB0_38:
	s_andn2_b64 vcc, exec, s[8:9]
	s_cbranch_vccnz .LBB0_40
	s_add_i32 s6, s47, 0xcf00
	s_and_b32 s10, s6, 0xffff
	s_mul_i32 s10, s10, 0xba2f
	s_lshr_b32 s10, s10, 23
	s_load_dwordx2 s[8:9], s[16:17], 0x90
	s_mul_i32 s11, s10, 0xb0
	s_sub_i32 s6, s6, s11
	s_lshl_b32 s6, s6, 6
	s_and_b32 s6, s6, 0xffc0
	s_lshl_b32 s11, s6, 2
	s_waitcnt lgkmcnt(0)
	s_add_u32 s8, s8, s11
	v_lshl_add_u32 v45, s10, 6, v5
	s_addc_u32 s9, s9, 0
	v_lshl_add_u64 v[6:7], s[8:9], 0, v[2:3]
	v_add_u32_e32 v48, 4, v45
	v_add_u32_e32 v54, 8, v45
	v_add_u32_e32 v56, 12, v45
	v_add_u32_e32 v62, 16, v45
	v_add_u32_e32 v64, 20, v45
	v_add_u32_e32 v70, 24, v45
	v_add_u32_e32 v72, 28, v45
	v_add_u32_e32 v82, 36, v45
	v_mad_i64_i32 v[46:47], s[8:9], v45, s43, v[6:7]
	v_mad_i64_i32 v[50:51], s[8:9], v48, s43, v[6:7]
	v_mad_i64_i32 v[54:55], s[8:9], v54, s43, v[6:7]
	v_mad_i64_i32 v[58:59], s[8:9], v56, s43, v[6:7]
	v_mad_i64_i32 v[62:63], s[8:9], v62, s43, v[6:7]
	v_mad_i64_i32 v[66:67], s[8:9], v64, s43, v[6:7]
	v_mad_i64_i32 v[70:71], s[8:9], v70, s43, v[6:7]
	v_mad_i64_i32 v[74:75], s[8:9], v72, s43, v[6:7]
	v_mad_i64_i32 v[82:83], s[8:9], v82, s43, v[6:7]
	v_add_u32_e32 v86, 40, v45
	global_load_dwordx4 v[46:49], v[46:47], off nt
	s_nop 0
	global_load_dwordx4 v[50:53], v[50:51], off nt
	s_nop 0
	global_load_dwordx4 v[54:57], v[54:55], off nt
	s_nop 0
	global_load_dwordx4 v[58:61], v[58:59], off nt
	s_nop 0
	global_load_dwordx4 v[62:65], v[62:63], off nt
	s_nop 0
	global_load_dwordx4 v[66:69], v[66:67], off nt
	s_nop 0
	global_load_dwordx4 v[70:73], v[70:71], off nt
	s_nop 0
	global_load_dwordx4 v[74:77], v[74:75], off nt
	v_mad_i64_i32 v[86:87], s[8:9], v86, s43, v[6:7]
	global_load_dwordx4 v[82:85], v[82:83], off nt
	v_add_u32_e32 v90, 44, v45
	global_load_dwordx4 v[86:89], v[86:87], off nt
	v_mad_i64_i32 v[90:91], s[8:9], v90, s43, v[6:7]
	global_load_dwordx4 v[90:93], v[90:91], off nt
	v_add_u32_e32 v94, 48, v45
	v_mad_i64_i32 v[94:95], s[8:9], v94, s43, v[6:7]
	global_load_dwordx4 v[94:97], v[94:95], off nt
	v_add_u32_e32 v98, 52, v45
	v_mad_i64_i32 v[98:99], s[8:9], v98, s43, v[6:7]
	global_load_dwordx4 v[98:101], v[98:99], off nt
	v_add_u32_e32 v102, 56, v45
	v_mad_i64_i32 v[102:103], s[8:9], v102, s43, v[6:7]
	v_add_u32_e32 v78, 32, v45
	global_load_dwordx4 v[102:105], v[102:103], off nt
	v_add_u32_e32 v45, 60, v45
	v_mad_i64_i32 v[78:79], s[8:9], v78, s43, v[6:7]
	v_mad_i64_i32 v[6:7], s[8:9], v45, s43, v[6:7]
	global_load_dwordx4 v[78:81], v[78:79], off nt
	v_add_u32_e32 v45, 0x400, v10
	global_load_dwordx4 v[106:109], v[6:7], off nt
	v_add_u32_e32 v6, 0x2498, v8
	s_lshl_b32 s8, s10, 15
	s_add_u32 s8, s14, s8
	s_addc_u32 s9, s15, 0
	s_waitcnt vmcnt(15)
	ds_write2_b32 v8, v46, v47 offset1:1
	ds_write2_b32 v8, v48, v49 offset0:2 offset1:3
	s_waitcnt vmcnt(14)
	ds_write2_b32 v26, v50, v51 offset1:1
	ds_write2_b32 v27, v52, v53 offset1:1
	s_waitcnt vmcnt(13)
	ds_write2_b32 v28, v54, v55 offset1:1
	ds_write2_b32 v29, v56, v57 offset1:1
	s_waitcnt vmcnt(12)
	ds_write2_b32 v30, v58, v59 offset1:1
	ds_write2_b32 v31, v60, v61 offset1:1
	s_waitcnt vmcnt(11)
	ds_write2_b32 v32, v62, v63 offset1:1
	ds_write2_b32 v33, v64, v65 offset1:1
	s_waitcnt vmcnt(10)
	ds_write2_b32 v34, v66, v67 offset1:1
	ds_write2_b32 v35, v68, v69 offset1:1
	s_waitcnt vmcnt(9)
	ds_write2_b32 v36, v70, v71 offset1:1
	ds_write2_b32 v37, v72, v73 offset1:1
	s_waitcnt vmcnt(8)
	ds_write2_b32 v38, v74, v75 offset1:1
	ds_write2_b32 v39, v76, v77 offset1:1
	s_waitcnt vmcnt(1)
	ds_write2_b32 v40, v78, v79 offset1:1
	ds_write2_b32 v41, v80, v81 offset1:1
	ds_write2_b32 v42, v82, v83 offset1:1
	ds_write2_b32 v6, v84, v85 offset1:1
	v_add_u32_e32 v6, 0x28a0, v8
	ds_write2_b32 v6, v86, v87 offset1:1
	v_add_u32_e32 v6, 0x28a8, v8
	ds_write2_b32 v6, v88, v89 offset1:1
	v_add_u32_e32 v6, 0x2cb0, v8
	ds_write2_b32 v6, v90, v91 offset1:1
	v_add_u32_e32 v6, 0x2cb8, v8
	ds_write2_b32 v6, v92, v93 offset1:1
	v_add_u32_e32 v6, 0x30c0, v8
	ds_write2_b32 v6, v94, v95 offset1:1
	v_add_u32_e32 v6, 0x30c8, v8
	ds_write2_b32 v6, v96, v97 offset1:1
	v_add_u32_e32 v6, 0x34d0, v8
	ds_write2_b32 v6, v98, v99 offset1:1
	v_add_u32_e32 v6, 0x34d8, v8
	ds_write2_b32 v6, v100, v101 offset1:1
	v_add_u32_e32 v6, 0x38e0, v8
	ds_write2_b32 v6, v102, v103 offset1:1
	v_add_u32_e32 v6, 0x38e8, v8
	ds_write2_b32 v6, v104, v105 offset1:1
	v_add_u32_e32 v6, 0x3cf0, v8
	s_waitcnt vmcnt(0)
	ds_write2_b32 v6, v106, v107 offset1:1
	v_add_u32_e32 v6, 0x3cf8, v8
	ds_write2_b32 v6, v108, v109 offset1:1
	s_waitcnt lgkmcnt(0)
	ds_read2_b32 v[50:51], v10 offset1:8
	ds_read2_b32 v[52:53], v10 offset0:65 offset1:73
	ds_read2_b32 v[54:55], v10 offset0:130 offset1:138
	ds_read2_b32 v[56:57], v10 offset0:195 offset1:203
	ds_read2_b32 v[58:59], v45 offset0:4 offset1:12
	s_waitcnt lgkmcnt(4)
	v_bfe_u32 v6, v50, 16, 1
	v_add3_u32 v6, v50, v6, s41
	s_waitcnt lgkmcnt(3)
	v_bfe_u32 v7, v52, 16, 1
	v_lshrrev_b32_e32 v6, 16, v6
	v_add3_u32 v7, v52, v7, s41
	ds_read2_b32 v[60:61], v45 offset0:69 offset1:77
	v_and_or_b32 v46, v7, s42, v6
	s_waitcnt lgkmcnt(3)
	v_bfe_u32 v6, v54, 16, 1
	v_add3_u32 v6, v54, v6, s41
	s_waitcnt lgkmcnt(2)
	v_bfe_u32 v7, v56, 16, 1
	ds_read2_b32 v[62:63], v45 offset0:134 offset1:142
	v_lshrrev_b32_e32 v6, 16, v6
	v_add3_u32 v7, v56, v7, s41
	ds_read2_b32 v[64:65], v45 offset0:199 offset1:207
	v_and_or_b32 v47, v7, s42, v6
	s_waitcnt lgkmcnt(3)
	v_bfe_u32 v6, v58, 16, 1
	v_add3_u32 v6, v58, v6, s41
	s_waitcnt lgkmcnt(2)
	v_bfe_u32 v7, v60, 16, 1
	v_lshrrev_b32_e32 v6, 16, v6
	v_add3_u32 v7, v60, v7, s41
	v_and_or_b32 v48, v7, s42, v6
	s_waitcnt lgkmcnt(1)
	v_bfe_u32 v6, v62, 16, 1
	v_add3_u32 v6, v62, v6, s41
	s_waitcnt lgkmcnt(0)
	v_bfe_u32 v7, v64, 16, 1
	v_lshrrev_b32_e32 v6, 16, v6
	v_add3_u32 v7, v64, v7, s41
	v_and_or_b32 v49, v7, s42, v6
	v_add_u32_e32 v6, s6, v9
	v_cmp_lt_i32_e32 vcc, s24, v6
	v_mov_b32_e32 v67, v3
	v_mov_b32_e32 v69, v3
	v_cndmask_b32_e32 v7, 0, v43, vcc
	v_add_u32_e32 v7, v7, v6
	v_cndmask_b32_e32 v50, 0, v44, vcc
	v_and_or_b32 v50, v6, s44, v50
	v_ashrrev_i32_e32 v6, 7, v7
	v_ashrrev_i32_e32 v7, 31, v6
	v_lshlrev_b64 v[6:7], 20, v[6:7]
	v_lshl_add_u64 v[6:7], s[8:9], 0, v[6:7]
	v_lshlrev_b32_e32 v66, 7, v50
	v_lshl_add_u64 v[66:67], v[6:7], 0, v[66:67]
	v_lshlrev_b32_e32 v6, 1, v4
	v_mov_b32_e32 v7, v3
	v_lshl_add_u64 v[66:67], v[66:67], 0, v[6:7]
	global_store_dwordx4 v[66:67], v[46:49], off
	v_bfe_u32 v50, v65, 16, 1
	v_add3_u32 v50, v65, v50, s41
	v_bfe_u32 v46, v51, 16, 1
	v_add3_u32 v46, v51, v46, s41
	v_bfe_u32 v47, v53, 16, 1
	v_lshrrev_b32_e32 v46, 16, v46
	v_add3_u32 v47, v53, v47, s41
	v_and_or_b32 v46, v47, s42, v46
	v_bfe_u32 v47, v55, 16, 1
	v_add3_u32 v47, v55, v47, s41
	v_bfe_u32 v48, v57, 16, 1
	v_lshrrev_b32_e32 v47, 16, v47
	v_add3_u32 v48, v57, v48, s41
	v_and_or_b32 v47, v48, s42, v47
	v_bfe_u32 v48, v59, 16, 1
	v_add3_u32 v48, v59, v48, s41
	v_bfe_u32 v49, v61, 16, 1
	v_lshrrev_b32_e32 v48, 16, v48
	v_add3_u32 v49, v61, v49, s41
	v_and_or_b32 v48, v49, s42, v48
	v_bfe_u32 v49, v63, 16, 1
	v_add3_u32 v49, v63, v49, s41
	v_lshrrev_b32_e32 v49, 16, v49
	v_and_or_b32 v49, v50, s42, v49
	v_add_u32_e32 v50, s6, v11
	v_cmp_lt_i32_e32 vcc, s24, v50
	v_mov_b32_e32 v53, v3
	ds_read2_b32 v[54:55], v10 offset0:16 offset1:24
	v_cndmask_b32_e32 v51, 0, v43, vcc
	v_add_u32_e32 v51, v51, v50
	v_cndmask_b32_e32 v52, 0, v44, vcc
	v_and_or_b32 v52, v50, s44, v52
	v_ashrrev_i32_e32 v50, 7, v51
	v_ashrrev_i32_e32 v51, 31, v50
	v_lshlrev_b64 v[50:51], 20, v[50:51]
	v_lshl_add_u64 v[50:51], s[8:9], 0, v[50:51]
	v_lshlrev_b32_e32 v52, 7, v52
	v_lshl_add_u64 v[50:51], v[50:51], 0, v[52:53]
	v_lshl_add_u64 v[50:51], v[50:51], 0, v[6:7]
	global_store_dwordx4 v[50:51], v[46:49], off
	ds_read2_b32 v[50:51], v10 offset0:81 offset1:89
	ds_read2_b32 v[52:53], v10 offset0:146 offset1:154
	ds_read2_b32 v[56:57], v10 offset0:211 offset1:219
	s_waitcnt lgkmcnt(3)
	v_bfe_u32 v46, v54, 16, 1
	v_add3_u32 v46, v54, v46, s41
	s_waitcnt lgkmcnt(2)
	v_bfe_u32 v47, v50, 16, 1
	ds_read2_b32 v[58:59], v45 offset0:20 offset1:28
	v_lshrrev_b32_e32 v46, 16, v46
	v_add3_u32 v47, v50, v47, s41
	ds_read2_b32 v[60:61], v45 offset0:85 offset1:93
	v_and_or_b32 v46, v47, s42, v46
	s_waitcnt lgkmcnt(3)
	v_bfe_u32 v47, v52, 16, 1
	v_add3_u32 v47, v52, v47, s41
	s_waitcnt lgkmcnt(2)
	v_bfe_u32 v48, v56, 16, 1
	ds_read2_b32 v[62:63], v45 offset0:150 offset1:158
	v_lshrrev_b32_e32 v47, 16, v47
	v_add3_u32 v48, v56, v48, s41
	ds_read2_b32 v[64:65], v45 offset0:215 offset1:223
	v_and_or_b32 v47, v48, s42, v47
	s_waitcnt lgkmcnt(3)
	v_bfe_u32 v48, v58, 16, 1
	v_add3_u32 v48, v58, v48, s41
	s_waitcnt lgkmcnt(2)
	v_bfe_u32 v49, v60, 16, 1
	v_lshrrev_b32_e32 v48, 16, v48
	v_add3_u32 v49, v60, v49, s41
	v_and_or_b32 v48, v49, s42, v48
	s_waitcnt lgkmcnt(1)
	v_bfe_u32 v49, v62, 16, 1
	v_add3_u32 v49, v62, v49, s41
	s_waitcnt lgkmcnt(0)
	v_bfe_u32 v50, v64, 16, 1
	v_lshrrev_b32_e32 v49, 16, v49
	v_add3_u32 v50, v64, v50, s41
	v_and_or_b32 v49, v50, s42, v49
	v_add_u32_e32 v50, s6, v12
	v_cmp_lt_i32_e32 vcc, s24, v50
	s_nop 1
	v_cndmask_b32_e32 v52, 0, v43, vcc
	v_add_u32_e32 v52, v52, v50
	v_ashrrev_i32_e32 v66, 7, v52
	v_cndmask_b32_e32 v54, 0, v44, vcc
	v_ashrrev_i32_e32 v67, 31, v66
	v_and_or_b32 v50, v50, s44, v54
	v_lshlrev_b64 v[66:67], 20, v[66:67]
	v_lshl_add_u64 v[66:67], s[8:9], 0, v[66:67]
	v_lshlrev_b32_e32 v68, 7, v50
	v_lshl_add_u64 v[66:67], v[66:67], 0, v[68:69]
	v_lshl_add_u64 v[66:67], v[66:67], 0, v[6:7]
	global_store_dwordx4 v[66:67], v[46:49], off
	v_bfe_u32 v50, v65, 16, 1
	v_add3_u32 v50, v65, v50, s41
	v_bfe_u32 v46, v55, 16, 1
	v_add3_u32 v46, v55, v46, s41
	v_bfe_u32 v47, v51, 16, 1
	v_lshrrev_b32_e32 v46, 16, v46
	v_add3_u32 v47, v51, v47, s41
	v_and_or_b32 v46, v47, s42, v46
	v_bfe_u32 v47, v53, 16, 1
	v_add3_u32 v47, v53, v47, s41
	v_bfe_u32 v48, v57, 16, 1
	v_lshrrev_b32_e32 v47, 16, v47
	v_add3_u32 v48, v57, v48, s41
	v_and_or_b32 v47, v48, s42, v47
	v_bfe_u32 v48, v59, 16, 1
	v_add3_u32 v48, v59, v48, s41
	v_bfe_u32 v49, v61, 16, 1
	v_lshrrev_b32_e32 v48, 16, v48
	v_add3_u32 v49, v61, v49, s41
	v_and_or_b32 v48, v49, s42, v48
	v_bfe_u32 v49, v63, 16, 1
	v_add3_u32 v49, v63, v49, s41
	v_lshrrev_b32_e32 v49, 16, v49
	v_and_or_b32 v49, v50, s42, v49
	v_add_u32_e32 v50, s6, v13
	v_cmp_lt_i32_e32 vcc, s24, v50
	v_mov_b32_e32 v53, v3
	ds_read2_b32 v[54:55], v10 offset0:32 offset1:40
	v_cndmask_b32_e32 v51, 0, v43, vcc
	v_add_u32_e32 v51, v51, v50
	v_cndmask_b32_e32 v52, 0, v44, vcc
	v_and_or_b32 v52, v50, s44, v52
	v_ashrrev_i32_e32 v50, 7, v51
	v_ashrrev_i32_e32 v51, 31, v50
	v_lshlrev_b64 v[50:51], 20, v[50:51]
	v_lshl_add_u64 v[50:51], s[8:9], 0, v[50:51]
	v_lshlrev_b32_e32 v52, 7, v52
	v_lshl_add_u64 v[50:51], v[50:51], 0, v[52:53]
	v_lshl_add_u64 v[50:51], v[50:51], 0, v[6:7]
	global_store_dwordx4 v[50:51], v[46:49], off
	ds_read2_b32 v[50:51], v10 offset0:97 offset1:105
	ds_read2_b32 v[52:53], v10 offset0:162 offset1:170
	ds_read2_b32 v[56:57], v10 offset0:227 offset1:235
	s_waitcnt lgkmcnt(3)
	v_bfe_u32 v46, v54, 16, 1
	v_add3_u32 v46, v54, v46, s41
	s_waitcnt lgkmcnt(2)
	v_bfe_u32 v47, v50, 16, 1
	ds_read2_b32 v[58:59], v45 offset0:36 offset1:44
	v_lshrrev_b32_e32 v46, 16, v46
	v_add3_u32 v47, v50, v47, s41
	ds_read2_b32 v[60:61], v45 offset0:101 offset1:109
	v_and_or_b32 v46, v47, s42, v46
	s_waitcnt lgkmcnt(3)
	v_bfe_u32 v47, v52, 16, 1
	v_add3_u32 v47, v52, v47, s41
	s_waitcnt lgkmcnt(2)
	v_bfe_u32 v48, v56, 16, 1
	ds_read2_b32 v[62:63], v45 offset0:166 offset1:174
	v_lshrrev_b32_e32 v47, 16, v47
	v_add3_u32 v48, v56, v48, s41
	ds_read2_b32 v[64:65], v45 offset0:231 offset1:239
	v_and_or_b32 v47, v48, s42, v47
	s_waitcnt lgkmcnt(3)
	v_bfe_u32 v48, v58, 16, 1
	v_add3_u32 v48, v58, v48, s41
	s_waitcnt lgkmcnt(2)
	v_bfe_u32 v49, v60, 16, 1
	v_lshrrev_b32_e32 v48, 16, v48
	v_add3_u32 v49, v60, v49, s41
	v_and_or_b32 v48, v49, s42, v48
	s_waitcnt lgkmcnt(1)
	v_bfe_u32 v49, v62, 16, 1
	v_add3_u32 v49, v62, v49, s41
	s_waitcnt lgkmcnt(0)
	v_bfe_u32 v50, v64, 16, 1
	v_lshrrev_b32_e32 v49, 16, v49
	v_add3_u32 v50, v64, v50, s41
	v_and_or_b32 v49, v50, s42, v49
	v_add_u32_e32 v50, s6, v14
	v_cmp_lt_i32_e32 vcc, s24, v50
	s_nop 1
	v_cndmask_b32_e32 v52, 0, v43, vcc
	v_add_u32_e32 v52, v52, v50
	v_ashrrev_i32_e32 v66, 7, v52
	v_cndmask_b32_e32 v54, 0, v44, vcc
	v_ashrrev_i32_e32 v67, 31, v66
	v_and_or_b32 v50, v50, s44, v54
	v_lshlrev_b64 v[66:67], 20, v[66:67]
	v_lshl_add_u64 v[66:67], s[8:9], 0, v[66:67]
	v_lshlrev_b32_e32 v68, 7, v50
	v_lshl_add_u64 v[66:67], v[66:67], 0, v[68:69]
	v_lshl_add_u64 v[66:67], v[66:67], 0, v[6:7]
	global_store_dwordx4 v[66:67], v[46:49], off
	v_bfe_u32 v50, v65, 16, 1
	v_add3_u32 v50, v65, v50, s41
	v_bfe_u32 v46, v55, 16, 1
	v_add3_u32 v46, v55, v46, s41
	v_bfe_u32 v47, v51, 16, 1
	v_lshrrev_b32_e32 v46, 16, v46
	v_add3_u32 v47, v51, v47, s41
	v_and_or_b32 v46, v47, s42, v46
	v_bfe_u32 v47, v53, 16, 1
	v_add3_u32 v47, v53, v47, s41
	v_bfe_u32 v48, v57, 16, 1
	v_lshrrev_b32_e32 v47, 16, v47
	v_add3_u32 v48, v57, v48, s41
	v_and_or_b32 v47, v48, s42, v47
	v_bfe_u32 v48, v59, 16, 1
	v_add3_u32 v48, v59, v48, s41
	v_bfe_u32 v49, v61, 16, 1
	v_lshrrev_b32_e32 v48, 16, v48
	v_add3_u32 v49, v61, v49, s41
	v_and_or_b32 v48, v49, s42, v48
	v_bfe_u32 v49, v63, 16, 1
	v_add3_u32 v49, v63, v49, s41
	v_lshrrev_b32_e32 v49, 16, v49
	v_and_or_b32 v49, v50, s42, v49
	v_add_u32_e32 v50, s6, v15
	v_cmp_lt_i32_e32 vcc, s24, v50
	v_mov_b32_e32 v53, v3
	ds_read2_b32 v[54:55], v10 offset0:48 offset1:56
	v_cndmask_b32_e32 v51, 0, v43, vcc
	v_add_u32_e32 v51, v51, v50
	v_cndmask_b32_e32 v52, 0, v44, vcc
	v_and_or_b32 v52, v50, s44, v52
	v_ashrrev_i32_e32 v50, 7, v51
	v_ashrrev_i32_e32 v51, 31, v50
	v_lshlrev_b64 v[50:51], 20, v[50:51]
	v_lshl_add_u64 v[50:51], s[8:9], 0, v[50:51]
	v_lshlrev_b32_e32 v52, 7, v52
	v_lshl_add_u64 v[50:51], v[50:51], 0, v[52:53]
	v_lshl_add_u64 v[50:51], v[50:51], 0, v[6:7]
	global_store_dwordx4 v[50:51], v[46:49], off
	ds_read2_b32 v[50:51], v10 offset0:113 offset1:121
	ds_read2_b32 v[52:53], v10 offset0:178 offset1:186
	ds_read2_b32 v[56:57], v10 offset0:243 offset1:251
	s_waitcnt lgkmcnt(3)
	v_bfe_u32 v46, v54, 16, 1
	v_add3_u32 v46, v54, v46, s41
	s_waitcnt lgkmcnt(2)
	v_bfe_u32 v47, v50, 16, 1
	ds_read2_b32 v[58:59], v45 offset0:52 offset1:60
	v_lshrrev_b32_e32 v46, 16, v46
	v_add3_u32 v47, v50, v47, s41
	ds_read2_b32 v[60:61], v45 offset0:117 offset1:125
	v_and_or_b32 v46, v47, s42, v46
	s_waitcnt lgkmcnt(3)
	v_bfe_u32 v47, v52, 16, 1
	ds_read2_b32 v[62:63], v45 offset0:182 offset1:190
	v_add3_u32 v47, v52, v47, s41
	s_waitcnt lgkmcnt(3)
	v_bfe_u32 v48, v56, 16, 1
	ds_read2_b32 v[64:65], v45 offset0:247 offset1:255
	v_lshrrev_b32_e32 v47, 16, v47
	v_add3_u32 v48, v56, v48, s41
	v_and_or_b32 v47, v48, s42, v47
	s_waitcnt lgkmcnt(3)
	v_bfe_u32 v48, v58, 16, 1
	v_add3_u32 v48, v58, v48, s41
	s_waitcnt lgkmcnt(2)
	v_bfe_u32 v49, v60, 16, 1
	v_lshrrev_b32_e32 v48, 16, v48
	v_add3_u32 v49, v60, v49, s41
	s_waitcnt lgkmcnt(1)
	v_bfe_u32 v45, v62, 16, 1
	v_and_or_b32 v48, v49, s42, v48
	v_add3_u32 v45, v62, v45, s41
	s_waitcnt lgkmcnt(0)
	v_bfe_u32 v49, v64, 16, 1
	v_lshrrev_b32_e32 v45, 16, v45
	v_add3_u32 v49, v64, v49, s41
	v_and_or_b32 v49, v49, s42, v45
	v_add_u32_e32 v45, s6, v16
	v_cmp_lt_i32_e32 vcc, s24, v45
	s_nop 1
	v_cndmask_b32_e32 v50, 0, v43, vcc
	v_add_u32_e32 v50, v50, v45
	v_ashrrev_i32_e32 v66, 7, v50
	v_cndmask_b32_e32 v52, 0, v44, vcc
	v_ashrrev_i32_e32 v67, 31, v66
	v_and_or_b32 v45, v45, s44, v52
	v_lshlrev_b64 v[66:67], 20, v[66:67]
	v_lshl_add_u64 v[66:67], s[8:9], 0, v[66:67]
	v_lshlrev_b32_e32 v68, 7, v45
	v_lshl_add_u64 v[66:67], v[66:67], 0, v[68:69]
	v_lshl_add_u64 v[66:67], v[66:67], 0, v[6:7]
	v_bfe_u32 v45, v55, 16, 1
	global_store_dwordx4 v[66:67], v[46:49], off
	v_add3_u32 v45, v55, v45, s41
	v_lshrrev_b32_e32 v45, 16, v45
	v_bfe_u32 v46, v51, 16, 1
	v_add3_u32 v46, v51, v46, s41
	v_and_or_b32 v46, v46, s42, v45
	v_bfe_u32 v45, v53, 16, 1
	v_add3_u32 v45, v53, v45, s41
	v_bfe_u32 v47, v57, 16, 1
	v_lshrrev_b32_e32 v45, 16, v45
	v_add3_u32 v47, v57, v47, s41
	v_and_or_b32 v47, v47, s42, v45
	v_bfe_u32 v45, v59, 16, 1
	v_add3_u32 v45, v59, v45, s41
	v_bfe_u32 v48, v61, 16, 1
	v_lshrrev_b32_e32 v45, 16, v45
	v_add3_u32 v48, v61, v48, s41
	v_and_or_b32 v48, v48, s42, v45
	v_bfe_u32 v45, v63, 16, 1
	v_add3_u32 v45, v63, v45, s41
	v_bfe_u32 v49, v65, 16, 1
	v_lshrrev_b32_e32 v45, 16, v45
	v_add3_u32 v49, v65, v49, s41
	v_and_or_b32 v49, v49, s42, v45
	v_add_u32_e32 v45, s6, v17
	v_cmp_lt_i32_e32 vcc, s24, v45
	v_mov_b32_e32 v53, v3
	s_nop 0
	v_cndmask_b32_e32 v50, 0, v43, vcc
	v_add_u32_e32 v50, v50, v45
	v_cndmask_b32_e32 v51, 0, v44, vcc
	v_ashrrev_i32_e32 v50, 7, v50
	v_and_or_b32 v45, v45, s44, v51
	v_ashrrev_i32_e32 v51, 31, v50
	v_lshlrev_b64 v[50:51], 20, v[50:51]
	v_lshl_add_u64 v[50:51], s[8:9], 0, v[50:51]
	v_lshlrev_b32_e32 v52, 7, v45
	v_lshl_add_u64 v[50:51], v[50:51], 0, v[52:53]
	v_lshl_add_u64 v[6:7], v[50:51], 0, v[6:7]
	global_store_dwordx4 v[6:7], v[46:49], off
	s_waitcnt lgkmcnt(0)

.LBB0_41:
	s_andn2_b64 vcc, exec, s[8:9]
	s_cbranch_vccnz .LBB0_43
	s_load_dwordx2 s[8:9], s[16:17], 0x58
	s_add_i32 s10, s22, 0x3400
	s_and_b32 s11, s10, 0x1fc0
	s_add_i32 s10, s20, 0xfff4c000
	s_and_b32 s10, s10, 0x7c0
	s_add_i32 s6, s47, 0xffffd300
	v_add_u32_e32 v6, s11, v5
	s_lshl_b32 s11, s10, 2
	s_waitcnt lgkmcnt(0)
	s_add_u32 s8, s8, s11
	s_addc_u32 s9, s9, 0
	v_ashrrev_i32_e32 v7, 31, v6
	v_lshl_add_u64 v[46:47], s[8:9], 0, v[2:3]
	v_lshlrev_b64 v[6:7], 13, v[6:7]
	v_lshl_add_u64 v[6:7], v[46:47], 0, v[6:7]
	v_add_co_u32_e32 v50, vcc, s25, v6
	v_add_u32_e32 v45, 0x400, v10
	s_nop 0
	v_addc_co_u32_e32 v51, vcc, 0, v7, vcc
	v_add_co_u32_e32 v54, vcc, s26, v6
	global_load_dwordx4 v[46:49], v[6:7], off nt
	s_nop 0
	global_load_dwordx4 v[50:53], v[50:51], off nt
	v_addc_co_u32_e32 v55, vcc, 0, v7, vcc
	v_add_co_u32_e32 v58, vcc, s27, v6
	s_lshr_b32 s6, s6, 5
	s_nop 0
	v_addc_co_u32_e32 v59, vcc, 0, v7, vcc
	v_add_co_u32_e32 v62, vcc, s28, v6
	global_load_dwordx4 v[54:57], v[54:55], off nt
	s_nop 0
	global_load_dwordx4 v[58:61], v[58:59], off nt
	v_addc_co_u32_e32 v63, vcc, 0, v7, vcc
	v_add_co_u32_e32 v66, vcc, s29, v6
	s_lshl_b64 s[8:9], s[6:7], 15
	s_nop 0
	v_addc_co_u32_e32 v67, vcc, 0, v7, vcc
	v_add_co_u32_e32 v70, vcc, s30, v6
	global_load_dwordx4 v[62:65], v[62:63], off nt
	s_nop 0
	global_load_dwordx4 v[66:69], v[66:67], off nt
	v_addc_co_u32_e32 v71, vcc, 0, v7, vcc
	v_add_co_u32_e32 v74, vcc, s31, v6
	s_nop 1
	v_addc_co_u32_e32 v75, vcc, 0, v7, vcc
	v_add_co_u32_e32 v78, vcc, s33, v6
	global_load_dwordx4 v[70:73], v[70:71], off nt
	s_nop 0
	global_load_dwordx4 v[74:77], v[74:75], off nt
	v_addc_co_u32_e32 v79, vcc, 0, v7, vcc
	v_add_co_u32_e32 v82, vcc, s34, v6
	s_nop 1
	v_addc_co_u32_e32 v83, vcc, 0, v7, vcc
	v_add_co_u32_e32 v86, vcc, s35, v6
	global_load_dwordx4 v[78:81], v[78:79], off nt
	s_nop 0
	global_load_dwordx4 v[82:85], v[82:83], off nt
	v_addc_co_u32_e32 v87, vcc, 0, v7, vcc
	v_add_co_u32_e32 v90, vcc, s36, v6
	s_nop 1
	v_addc_co_u32_e32 v91, vcc, 0, v7, vcc
	global_load_dwordx4 v[86:89], v[86:87], off nt
	s_nop 0
	global_load_dwordx4 v[90:93], v[90:91], off nt
	v_add_co_u32_e32 v94, vcc, s37, v6
	s_nop 1
	v_addc_co_u32_e32 v95, vcc, 0, v7, vcc
	global_load_dwordx4 v[94:97], v[94:95], off nt
	v_add_co_u32_e32 v98, vcc, s38, v6
	s_nop 1
	v_addc_co_u32_e32 v99, vcc, 0, v7, vcc
	global_load_dwordx4 v[98:101], v[98:99], off nt
	v_add_co_u32_e32 v102, vcc, s39, v6
	s_nop 1
	v_addc_co_u32_e32 v103, vcc, 0, v7, vcc
	global_load_dwordx4 v[102:105], v[102:103], off nt
	v_add_co_u32_e32 v6, vcc, s40, v6
	s_nop 1
	v_addc_co_u32_e32 v7, vcc, 0, v7, vcc
	global_load_dwordx4 v[106:109], v[6:7], off nt
	v_add_u32_e32 v6, 0x2498, v8
	s_waitcnt vmcnt(15)
	ds_write2_b32 v8, v46, v47 offset1:1
	ds_write2_b32 v8, v48, v49 offset0:2 offset1:3
	s_waitcnt vmcnt(14)
	ds_write2_b32 v26, v50, v51 offset1:1
	ds_write2_b32 v27, v52, v53 offset1:1
	s_waitcnt vmcnt(13)
	ds_write2_b32 v28, v54, v55 offset1:1
	ds_write2_b32 v29, v56, v57 offset1:1
	s_waitcnt vmcnt(12)
	ds_write2_b32 v30, v58, v59 offset1:1
	ds_write2_b32 v31, v60, v61 offset1:1
	s_waitcnt vmcnt(11)
	ds_write2_b32 v32, v62, v63 offset1:1
	ds_write2_b32 v33, v64, v65 offset1:1
	s_waitcnt vmcnt(10)
	ds_write2_b32 v34, v66, v67 offset1:1
	ds_write2_b32 v35, v68, v69 offset1:1
	s_waitcnt vmcnt(9)
	ds_write2_b32 v36, v70, v71 offset1:1
	ds_write2_b32 v37, v72, v73 offset1:1
	s_waitcnt vmcnt(8)
	ds_write2_b32 v38, v74, v75 offset1:1
	ds_write2_b32 v39, v76, v77 offset1:1
	s_waitcnt vmcnt(7)
	ds_write2_b32 v40, v78, v79 offset1:1
	ds_write2_b32 v41, v80, v81 offset1:1
	s_waitcnt vmcnt(6)
	ds_write2_b32 v42, v82, v83 offset1:1
	ds_write2_b32 v6, v84, v85 offset1:1
	v_add_u32_e32 v6, 0x28a0, v8
	v_mov_b32_e32 v67, v3
	v_mov_b32_e32 v69, v3
	s_waitcnt vmcnt(5)
	ds_write2_b32 v6, v86, v87 offset1:1
	v_add_u32_e32 v6, 0x28a8, v8
	ds_write2_b32 v6, v88, v89 offset1:1
	v_add_u32_e32 v6, 0x2cb0, v8
	s_waitcnt vmcnt(4)
	ds_write2_b32 v6, v90, v91 offset1:1
	v_add_u32_e32 v6, 0x2cb8, v8
	ds_write2_b32 v6, v92, v93 offset1:1
	v_add_u32_e32 v6, 0x30c0, v8
	s_waitcnt vmcnt(3)
	ds_write2_b32 v6, v94, v95 offset1:1
	v_add_u32_e32 v6, 0x30c8, v8
	ds_write2_b32 v6, v96, v97 offset1:1
	v_add_u32_e32 v6, 0x34d0, v8
	s_waitcnt vmcnt(2)
	ds_write2_b32 v6, v98, v99 offset1:1
	v_add_u32_e32 v6, 0x34d8, v8
	ds_write2_b32 v6, v100, v101 offset1:1
	v_add_u32_e32 v6, 0x38e0, v8
	s_waitcnt vmcnt(1)
	ds_write2_b32 v6, v102, v103 offset1:1
	v_add_u32_e32 v6, 0x38e8, v8
	ds_write2_b32 v6, v104, v105 offset1:1
	v_add_u32_e32 v6, 0x3cf0, v8
	s_waitcnt vmcnt(0)
	ds_write2_b32 v6, v106, v107 offset1:1
	v_add_u32_e32 v6, 0x3cf8, v8
	ds_write2_b32 v6, v108, v109 offset1:1
	s_waitcnt lgkmcnt(0)
	ds_read2_b32 v[50:51], v10 offset1:8
	ds_read2_b32 v[52:53], v10 offset0:65 offset1:73
	ds_read2_b32 v[54:55], v10 offset0:130 offset1:138
	ds_read2_b32 v[56:57], v10 offset0:195 offset1:203
	ds_read2_b32 v[58:59], v45 offset0:4 offset1:12
	s_waitcnt lgkmcnt(4)
	v_bfe_u32 v6, v50, 16, 1
	v_add3_u32 v6, v50, v6, s41
	s_waitcnt lgkmcnt(3)
	v_bfe_u32 v7, v52, 16, 1
	v_lshrrev_b32_e32 v6, 16, v6
	v_add3_u32 v7, v52, v7, s41
	ds_read2_b32 v[60:61], v45 offset0:69 offset1:77
	v_and_or_b32 v46, v7, s42, v6
	s_waitcnt lgkmcnt(3)
	v_bfe_u32 v6, v54, 16, 1
	v_add3_u32 v6, v54, v6, s41
	s_waitcnt lgkmcnt(2)
	v_bfe_u32 v7, v56, 16, 1
	ds_read2_b32 v[62:63], v45 offset0:134 offset1:142
	v_lshrrev_b32_e32 v6, 16, v6
	v_add3_u32 v7, v56, v7, s41
	ds_read2_b32 v[64:65], v45 offset0:199 offset1:207
	v_and_or_b32 v47, v7, s42, v6
	s_waitcnt lgkmcnt(3)
	v_bfe_u32 v6, v58, 16, 1
	v_add3_u32 v6, v58, v6, s41
	s_waitcnt lgkmcnt(2)
	v_bfe_u32 v7, v60, 16, 1
	v_lshrrev_b32_e32 v6, 16, v6
	v_add3_u32 v7, v60, v7, s41
	v_and_or_b32 v48, v7, s42, v6
	s_waitcnt lgkmcnt(1)
	v_bfe_u32 v6, v62, 16, 1
	v_add3_u32 v6, v62, v6, s41
	s_waitcnt lgkmcnt(0)
	v_bfe_u32 v7, v64, 16, 1
	v_lshrrev_b32_e32 v6, 16, v6
	v_add3_u32 v7, v64, v7, s41
	v_add_u32_e32 v50, s10, v9
	v_and_or_b32 v49, v7, s42, v6
	v_ashrrev_i32_e32 v6, 8, v50
	v_ashrrev_i32_e32 v7, 31, v6
	v_lshlrev_b64 v[6:7], 20, v[6:7]
	v_lshl_add_u64 v[6:7], s[2:3], 0, v[6:7]
	v_lshlrev_b32_e32 v50, 7, v50
	v_lshl_add_u64 v[6:7], v[6:7], 0, s[8:9]
	v_and_b32_e32 v66, 0x7f80, v50
	v_lshl_add_u64 v[66:67], v[6:7], 0, v[66:67]
	v_lshlrev_b32_e32 v6, 1, v4
	v_mov_b32_e32 v7, v3
	v_lshl_add_u64 v[66:67], v[66:67], 0, v[6:7]
	global_store_dwordx4 v[66:67], v[46:49], off
	v_bfe_u32 v50, v65, 16, 1
	v_add3_u32 v50, v65, v50, s41
	v_bfe_u32 v46, v51, 16, 1
	v_add3_u32 v46, v51, v46, s41
	v_bfe_u32 v47, v53, 16, 1
	v_lshrrev_b32_e32 v46, 16, v46
	v_add3_u32 v47, v53, v47, s41
	v_and_or_b32 v46, v47, s42, v46
	v_bfe_u32 v47, v55, 16, 1
	v_add3_u32 v47, v55, v47, s41
	v_bfe_u32 v48, v57, 16, 1
	v_lshrrev_b32_e32 v47, 16, v47
	v_add3_u32 v48, v57, v48, s41
	v_and_or_b32 v47, v48, s42, v47
	v_bfe_u32 v48, v59, 16, 1
	v_add3_u32 v48, v59, v48, s41
	v_bfe_u32 v49, v61, 16, 1
	v_lshrrev_b32_e32 v48, 16, v48
	v_add3_u32 v49, v61, v49, s41
	v_and_or_b32 v48, v49, s42, v48
	v_bfe_u32 v49, v63, 16, 1
	v_add3_u32 v49, v63, v49, s41
	v_lshrrev_b32_e32 v49, 16, v49
	v_add_u32_e32 v52, s10, v11
	v_and_or_b32 v49, v50, s42, v49
	v_ashrrev_i32_e32 v50, 8, v52
	v_ashrrev_i32_e32 v51, 31, v50
	v_lshlrev_b64 v[50:51], 20, v[50:51]
	v_lshl_add_u64 v[50:51], s[2:3], 0, v[50:51]
	v_lshlrev_b32_e32 v52, 7, v52
	v_lshl_add_u64 v[50:51], v[50:51], 0, s[8:9]
	v_and_b32_e32 v52, 0x7f80, v52
	v_mov_b32_e32 v53, v3
	v_lshl_add_u64 v[50:51], v[50:51], 0, v[52:53]
	ds_read2_b32 v[54:55], v10 offset0:16 offset1:24
	v_lshl_add_u64 v[50:51], v[50:51], 0, v[6:7]
	global_store_dwordx4 v[50:51], v[46:49], off
	ds_read2_b32 v[50:51], v10 offset0:81 offset1:89
	ds_read2_b32 v[52:53], v10 offset0:146 offset1:154
	ds_read2_b32 v[56:57], v10 offset0:211 offset1:219
	s_waitcnt lgkmcnt(3)
	v_bfe_u32 v46, v54, 16, 1
	v_add3_u32 v46, v54, v46, s41
	s_waitcnt lgkmcnt(2)
	v_bfe_u32 v47, v50, 16, 1
	ds_read2_b32 v[58:59], v45 offset0:20 offset1:28
	v_lshrrev_b32_e32 v46, 16, v46
	v_add3_u32 v47, v50, v47, s41
	ds_read2_b32 v[60:61], v45 offset0:85 offset1:93
	v_and_or_b32 v46, v47, s42, v46
	s_waitcnt lgkmcnt(3)
	v_bfe_u32 v47, v52, 16, 1
	v_add3_u32 v47, v52, v47, s41
	s_waitcnt lgkmcnt(2)
	v_bfe_u32 v48, v56, 16, 1
	ds_read2_b32 v[62:63], v45 offset0:150 offset1:158
	v_lshrrev_b32_e32 v47, 16, v47
	v_add3_u32 v48, v56, v48, s41
	ds_read2_b32 v[64:65], v45 offset0:215 offset1:223
	v_and_or_b32 v47, v48, s42, v47
	s_waitcnt lgkmcnt(3)
	v_bfe_u32 v48, v58, 16, 1
	v_add3_u32 v48, v58, v48, s41
	s_waitcnt lgkmcnt(2)
	v_bfe_u32 v49, v60, 16, 1
	v_lshrrev_b32_e32 v48, 16, v48
	v_add3_u32 v49, v60, v49, s41
	v_and_or_b32 v48, v49, s42, v48
	s_waitcnt lgkmcnt(1)
	v_bfe_u32 v49, v62, 16, 1
	v_add3_u32 v49, v62, v49, s41
	s_waitcnt lgkmcnt(0)
	v_bfe_u32 v50, v64, 16, 1
	v_lshrrev_b32_e32 v49, 16, v49
	v_add3_u32 v50, v64, v50, s41
	v_and_or_b32 v49, v50, s42, v49
	v_add_u32_e32 v50, s10, v12
	v_ashrrev_i32_e32 v66, 8, v50
	v_ashrrev_i32_e32 v67, 31, v66
	v_lshlrev_b64 v[66:67], 20, v[66:67]
	v_lshl_add_u64 v[66:67], s[2:3], 0, v[66:67]
	v_lshlrev_b32_e32 v50, 7, v50
	v_lshl_add_u64 v[66:67], v[66:67], 0, s[8:9]
	v_and_b32_e32 v68, 0x7f80, v50
	v_lshl_add_u64 v[66:67], v[66:67], 0, v[68:69]
	v_lshl_add_u64 v[66:67], v[66:67], 0, v[6:7]
	global_store_dwordx4 v[66:67], v[46:49], off
	v_bfe_u32 v50, v65, 16, 1
	v_add3_u32 v50, v65, v50, s41
	v_bfe_u32 v46, v55, 16, 1
	v_add3_u32 v46, v55, v46, s41
	v_bfe_u32 v47, v51, 16, 1
	v_lshrrev_b32_e32 v46, 16, v46
	v_add3_u32 v47, v51, v47, s41
	v_and_or_b32 v46, v47, s42, v46
	v_bfe_u32 v47, v53, 16, 1
	v_add3_u32 v47, v53, v47, s41
	v_bfe_u32 v48, v57, 16, 1
	v_lshrrev_b32_e32 v47, 16, v47
	v_add3_u32 v48, v57, v48, s41
	v_and_or_b32 v47, v48, s42, v47
	v_bfe_u32 v48, v59, 16, 1
	v_add3_u32 v48, v59, v48, s41
	v_bfe_u32 v49, v61, 16, 1
	v_lshrrev_b32_e32 v48, 16, v48
	v_add3_u32 v49, v61, v49, s41
	v_and_or_b32 v48, v49, s42, v48
	v_bfe_u32 v49, v63, 16, 1
	v_add3_u32 v49, v63, v49, s41
	v_lshrrev_b32_e32 v49, 16, v49
	v_add_u32_e32 v52, s10, v13
	v_and_or_b32 v49, v50, s42, v49
	v_ashrrev_i32_e32 v50, 8, v52
	v_ashrrev_i32_e32 v51, 31, v50
	v_lshlrev_b64 v[50:51], 20, v[50:51]
	v_lshl_add_u64 v[50:51], s[2:3], 0, v[50:51]
	v_lshlrev_b32_e32 v52, 7, v52
	v_lshl_add_u64 v[50:51], v[50:51], 0, s[8:9]
	v_and_b32_e32 v52, 0x7f80, v52
	v_mov_b32_e32 v53, v3
	v_lshl_add_u64 v[50:51], v[50:51], 0, v[52:53]
	ds_read2_b32 v[54:55], v10 offset0:32 offset1:40
	v_lshl_add_u64 v[50:51], v[50:51], 0, v[6:7]
	global_store_dwordx4 v[50:51], v[46:49], off
	ds_read2_b32 v[50:51], v10 offset0:97 offset1:105
	ds_read2_b32 v[52:53], v10 offset0:162 offset1:170
	ds_read2_b32 v[56:57], v10 offset0:227 offset1:235
	s_waitcnt lgkmcnt(3)
	v_bfe_u32 v46, v54, 16, 1
	v_add3_u32 v46, v54, v46, s41
	s_waitcnt lgkmcnt(2)
	v_bfe_u32 v47, v50, 16, 1
	ds_read2_b32 v[58:59], v45 offset0:36 offset1:44
	v_lshrrev_b32_e32 v46, 16, v46
	v_add3_u32 v47, v50, v47, s41
	ds_read2_b32 v[60:61], v45 offset0:101 offset1:109
	v_and_or_b32 v46, v47, s42, v46
	s_waitcnt lgkmcnt(3)
	v_bfe_u32 v47, v52, 16, 1
	v_add3_u32 v47, v52, v47, s41
	s_waitcnt lgkmcnt(2)
	v_bfe_u32 v48, v56, 16, 1
	ds_read2_b32 v[62:63], v45 offset0:166 offset1:174
	v_lshrrev_b32_e32 v47, 16, v47
	v_add3_u32 v48, v56, v48, s41
	ds_read2_b32 v[64:65], v45 offset0:231 offset1:239
	v_and_or_b32 v47, v48, s42, v47
	s_waitcnt lgkmcnt(3)
	v_bfe_u32 v48, v58, 16, 1
	v_add3_u32 v48, v58, v48, s41
	s_waitcnt lgkmcnt(2)
	v_bfe_u32 v49, v60, 16, 1
	v_lshrrev_b32_e32 v48, 16, v48
	v_add3_u32 v49, v60, v49, s41
	v_and_or_b32 v48, v49, s42, v48
	s_waitcnt lgkmcnt(1)
	v_bfe_u32 v49, v62, 16, 1
	v_add3_u32 v49, v62, v49, s41
	s_waitcnt lgkmcnt(0)
	v_bfe_u32 v50, v64, 16, 1
	v_lshrrev_b32_e32 v49, 16, v49
	v_add3_u32 v50, v64, v50, s41
	v_and_or_b32 v49, v50, s42, v49
	v_add_u32_e32 v50, s10, v14
	v_ashrrev_i32_e32 v66, 8, v50
	v_ashrrev_i32_e32 v67, 31, v66
	v_lshlrev_b64 v[66:67], 20, v[66:67]
	v_lshl_add_u64 v[66:67], s[2:3], 0, v[66:67]
	v_lshlrev_b32_e32 v50, 7, v50
	v_lshl_add_u64 v[66:67], v[66:67], 0, s[8:9]
	v_and_b32_e32 v68, 0x7f80, v50
	v_lshl_add_u64 v[66:67], v[66:67], 0, v[68:69]
	v_lshl_add_u64 v[66:67], v[66:67], 0, v[6:7]
	global_store_dwordx4 v[66:67], v[46:49], off
	v_bfe_u32 v50, v65, 16, 1
	v_add3_u32 v50, v65, v50, s41
	v_bfe_u32 v46, v55, 16, 1
	v_add3_u32 v46, v55, v46, s41
	v_bfe_u32 v47, v51, 16, 1
	v_lshrrev_b32_e32 v46, 16, v46
	v_add3_u32 v47, v51, v47, s41
	v_and_or_b32 v46, v47, s42, v46
	v_bfe_u32 v47, v53, 16, 1
	v_add3_u32 v47, v53, v47, s41
	v_bfe_u32 v48, v57, 16, 1
	v_lshrrev_b32_e32 v47, 16, v47
	v_add3_u32 v48, v57, v48, s41
	v_and_or_b32 v47, v48, s42, v47
	v_bfe_u32 v48, v59, 16, 1
	v_add3_u32 v48, v59, v48, s41
	v_bfe_u32 v49, v61, 16, 1
	v_lshrrev_b32_e32 v48, 16, v48
	v_add3_u32 v49, v61, v49, s41
	v_and_or_b32 v48, v49, s42, v48
	v_bfe_u32 v49, v63, 16, 1
	v_add3_u32 v49, v63, v49, s41
	v_lshrrev_b32_e32 v49, 16, v49
	v_add_u32_e32 v52, s10, v15
	v_and_or_b32 v49, v50, s42, v49
	v_ashrrev_i32_e32 v50, 8, v52
	v_ashrrev_i32_e32 v51, 31, v50
	v_lshlrev_b64 v[50:51], 20, v[50:51]
	v_lshl_add_u64 v[50:51], s[2:3], 0, v[50:51]
	v_lshlrev_b32_e32 v52, 7, v52
	v_lshl_add_u64 v[50:51], v[50:51], 0, s[8:9]
	v_and_b32_e32 v52, 0x7f80, v52
	v_mov_b32_e32 v53, v3
	v_lshl_add_u64 v[50:51], v[50:51], 0, v[52:53]
	ds_read2_b32 v[54:55], v10 offset0:48 offset1:56
	v_lshl_add_u64 v[50:51], v[50:51], 0, v[6:7]
	global_store_dwordx4 v[50:51], v[46:49], off
	ds_read2_b32 v[50:51], v10 offset0:113 offset1:121
	ds_read2_b32 v[52:53], v10 offset0:178 offset1:186
	ds_read2_b32 v[56:57], v10 offset0:243 offset1:251
	s_waitcnt lgkmcnt(3)
	v_bfe_u32 v46, v54, 16, 1
	v_add3_u32 v46, v54, v46, s41
	s_waitcnt lgkmcnt(2)
	v_bfe_u32 v47, v50, 16, 1
	ds_read2_b32 v[58:59], v45 offset0:52 offset1:60
	v_lshrrev_b32_e32 v46, 16, v46
	v_add3_u32 v47, v50, v47, s41
	ds_read2_b32 v[60:61], v45 offset0:117 offset1:125
	v_and_or_b32 v46, v47, s42, v46
	s_waitcnt lgkmcnt(3)
	v_bfe_u32 v47, v52, 16, 1
	ds_read2_b32 v[62:63], v45 offset0:182 offset1:190
	v_add3_u32 v47, v52, v47, s41
	s_waitcnt lgkmcnt(3)
	v_bfe_u32 v48, v56, 16, 1
	ds_read2_b32 v[64:65], v45 offset0:247 offset1:255
	v_lshrrev_b32_e32 v47, 16, v47
	v_add3_u32 v48, v56, v48, s41
	v_and_or_b32 v47, v48, s42, v47
	s_waitcnt lgkmcnt(3)
	v_bfe_u32 v48, v58, 16, 1
	v_add3_u32 v48, v58, v48, s41
	s_waitcnt lgkmcnt(2)
	v_bfe_u32 v49, v60, 16, 1
	v_lshrrev_b32_e32 v48, 16, v48
	v_add3_u32 v49, v60, v49, s41
	s_waitcnt lgkmcnt(1)
	v_bfe_u32 v45, v62, 16, 1
	v_and_or_b32 v48, v49, s42, v48
	v_add3_u32 v45, v62, v45, s41
	s_waitcnt lgkmcnt(0)
	v_bfe_u32 v49, v64, 16, 1
	v_lshrrev_b32_e32 v45, 16, v45
	v_add3_u32 v49, v64, v49, s41
	v_and_or_b32 v49, v49, s42, v45
	v_add_u32_e32 v45, s10, v16
	v_ashrrev_i32_e32 v66, 8, v45
	v_ashrrev_i32_e32 v67, 31, v66
	v_lshlrev_b64 v[66:67], 20, v[66:67]
	v_lshl_add_u64 v[66:67], s[2:3], 0, v[66:67]
	v_lshlrev_b32_e32 v45, 7, v45
	v_lshl_add_u64 v[66:67], v[66:67], 0, s[8:9]
	v_and_b32_e32 v68, 0x7f80, v45
	v_lshl_add_u64 v[66:67], v[66:67], 0, v[68:69]
	v_lshl_add_u64 v[66:67], v[66:67], 0, v[6:7]
	v_bfe_u32 v45, v55, 16, 1
	global_store_dwordx4 v[66:67], v[46:49], off
	v_add3_u32 v45, v55, v45, s41
	v_lshrrev_b32_e32 v45, 16, v45
	v_bfe_u32 v46, v51, 16, 1
	v_add3_u32 v46, v51, v46, s41
	v_and_or_b32 v46, v46, s42, v45
	v_bfe_u32 v45, v53, 16, 1
	v_add3_u32 v45, v53, v45, s41
	v_bfe_u32 v47, v57, 16, 1
	v_lshrrev_b32_e32 v45, 16, v45
	v_add3_u32 v47, v57, v47, s41
	v_and_or_b32 v47, v47, s42, v45
	v_bfe_u32 v45, v59, 16, 1
	v_add3_u32 v45, v59, v45, s41
	v_bfe_u32 v48, v61, 16, 1
	v_lshrrev_b32_e32 v45, 16, v45
	v_add3_u32 v48, v61, v48, s41
	v_and_or_b32 v48, v48, s42, v45
	v_bfe_u32 v45, v63, 16, 1
	v_add3_u32 v45, v63, v45, s41
	v_bfe_u32 v49, v65, 16, 1
	v_lshrrev_b32_e32 v45, 16, v45
	v_add3_u32 v49, v65, v49, s41
	v_and_or_b32 v49, v49, s42, v45
	v_add_u32_e32 v45, s10, v17
	v_ashrrev_i32_e32 v50, 8, v45
	v_ashrrev_i32_e32 v51, 31, v50
	v_lshlrev_b64 v[50:51], 20, v[50:51]
	v_lshl_add_u64 v[50:51], s[2:3], 0, v[50:51]
	v_lshlrev_b32_e32 v45, 7, v45
	v_lshl_add_u64 v[50:51], v[50:51], 0, s[8:9]
	v_and_b32_e32 v52, 0x7f80, v45
	v_mov_b32_e32 v53, v3
	v_lshl_add_u64 v[50:51], v[50:51], 0, v[52:53]
	v_lshl_add_u64 v[6:7], v[50:51], 0, v[6:7]
	global_store_dwordx4 v[6:7], v[46:49], off
	s_waitcnt lgkmcnt(0)

.LBB0_44:
	s_andn2_b64 vcc, exec, s[8:9]
	s_cbranch_vccnz .LBB0_46
	s_add_i32 s6, s47, 0xdf00
	s_and_b32 s10, s6, 0xffff
	s_mul_i32 s10, s10, 0xaaab
	s_lshr_b32 s10, s10, 22
	s_load_dwordx2 s[8:9], s[16:17], 0x50
	s_mul_i32 s11, s10, 0x60
	s_sub_i32 s6, s6, s11
	s_lshl_b32 s6, s6, 6
	s_and_b32 s6, s6, 0xffc0
	s_lshl_b32 s11, s6, 2
	s_waitcnt lgkmcnt(0)
	s_add_u32 s8, s8, s11
	v_lshl_add_u32 v45, s10, 6, v5
	s_addc_u32 s9, s9, 0
	v_lshl_add_u64 v[6:7], s[8:9], 0, v[2:3]
	v_add_u32_e32 v48, 4, v45
	v_add_u32_e32 v54, 8, v45
	v_add_u32_e32 v56, 12, v45
	v_add_u32_e32 v62, 16, v45
	v_add_u32_e32 v64, 20, v45
	v_add_u32_e32 v70, 24, v45
	v_add_u32_e32 v72, 28, v45
	v_add_u32_e32 v82, 36, v45
	v_mad_i64_i32 v[46:47], s[8:9], v45, s45, v[6:7]
	v_mad_i64_i32 v[50:51], s[8:9], v48, s45, v[6:7]
	v_mad_i64_i32 v[54:55], s[8:9], v54, s45, v[6:7]
	v_mad_i64_i32 v[58:59], s[8:9], v56, s45, v[6:7]
	v_mad_i64_i32 v[62:63], s[8:9], v62, s45, v[6:7]
	v_mad_i64_i32 v[66:67], s[8:9], v64, s45, v[6:7]
	v_mad_i64_i32 v[70:71], s[8:9], v70, s45, v[6:7]
	v_mad_i64_i32 v[74:75], s[8:9], v72, s45, v[6:7]
	v_mad_i64_i32 v[82:83], s[8:9], v82, s45, v[6:7]
	v_add_u32_e32 v86, 40, v45
	global_load_dwordx4 v[46:49], v[46:47], off nt
	s_nop 0
	global_load_dwordx4 v[50:53], v[50:51], off nt
	s_nop 0
	global_load_dwordx4 v[54:57], v[54:55], off nt
	s_nop 0
	global_load_dwordx4 v[58:61], v[58:59], off nt
	s_nop 0
	global_load_dwordx4 v[62:65], v[62:63], off nt
	s_nop 0
	global_load_dwordx4 v[66:69], v[66:67], off nt
	s_nop 0
	global_load_dwordx4 v[70:73], v[70:71], off nt
	s_nop 0
	global_load_dwordx4 v[74:77], v[74:75], off nt
	v_mad_i64_i32 v[86:87], s[8:9], v86, s45, v[6:7]
	global_load_dwordx4 v[82:85], v[82:83], off nt
	v_add_u32_e32 v90, 44, v45
	global_load_dwordx4 v[86:89], v[86:87], off nt
	v_mad_i64_i32 v[90:91], s[8:9], v90, s45, v[6:7]
	global_load_dwordx4 v[90:93], v[90:91], off nt
	v_add_u32_e32 v94, 48, v45
	v_mad_i64_i32 v[94:95], s[8:9], v94, s45, v[6:7]
	global_load_dwordx4 v[94:97], v[94:95], off nt
	v_add_u32_e32 v98, 52, v45
	v_mad_i64_i32 v[98:99], s[8:9], v98, s45, v[6:7]
	global_load_dwordx4 v[98:101], v[98:99], off nt
	v_add_u32_e32 v102, 56, v45
	v_mad_i64_i32 v[102:103], s[8:9], v102, s45, v[6:7]
	v_add_u32_e32 v78, 32, v45
	global_load_dwordx4 v[102:105], v[102:103], off nt
	v_add_u32_e32 v45, 60, v45
	v_mad_i64_i32 v[78:79], s[8:9], v78, s45, v[6:7]
	v_mad_i64_i32 v[6:7], s[8:9], v45, s45, v[6:7]
	global_load_dwordx4 v[78:81], v[78:79], off nt
	v_add_u32_e32 v45, 0x400, v10
	global_load_dwordx4 v[106:109], v[6:7], off nt
	v_add_u32_e32 v6, 0x2498, v8
	s_lshl_b32 s8, s10, 15
	s_add_u32 s8, s18, s8
	s_addc_u32 s9, s19, 0
	s_waitcnt vmcnt(15)
	ds_write2_b32 v8, v46, v47 offset1:1
	ds_write2_b32 v8, v48, v49 offset0:2 offset1:3
	s_waitcnt vmcnt(14)
	ds_write2_b32 v26, v50, v51 offset1:1
	ds_write2_b32 v27, v52, v53 offset1:1
	s_waitcnt vmcnt(13)
	ds_write2_b32 v28, v54, v55 offset1:1
	ds_write2_b32 v29, v56, v57 offset1:1
	s_waitcnt vmcnt(12)
	ds_write2_b32 v30, v58, v59 offset1:1
	ds_write2_b32 v31, v60, v61 offset1:1
	s_waitcnt vmcnt(11)
	ds_write2_b32 v32, v62, v63 offset1:1
	ds_write2_b32 v33, v64, v65 offset1:1
	s_waitcnt vmcnt(10)
	ds_write2_b32 v34, v66, v67 offset1:1
	ds_write2_b32 v35, v68, v69 offset1:1
	s_waitcnt vmcnt(9)
	ds_write2_b32 v36, v70, v71 offset1:1
	ds_write2_b32 v37, v72, v73 offset1:1
	s_waitcnt vmcnt(8)
	ds_write2_b32 v38, v74, v75 offset1:1
	ds_write2_b32 v39, v76, v77 offset1:1
	s_waitcnt vmcnt(1)
	ds_write2_b32 v40, v78, v79 offset1:1
	ds_write2_b32 v41, v80, v81 offset1:1
	ds_write2_b32 v42, v82, v83 offset1:1
	ds_write2_b32 v6, v84, v85 offset1:1
	v_add_u32_e32 v6, 0x28a0, v8
	ds_write2_b32 v6, v86, v87 offset1:1
	v_add_u32_e32 v6, 0x28a8, v8
	ds_write2_b32 v6, v88, v89 offset1:1
	v_add_u32_e32 v6, 0x2cb0, v8
	ds_write2_b32 v6, v90, v91 offset1:1
	v_add_u32_e32 v6, 0x2cb8, v8
	ds_write2_b32 v6, v92, v93 offset1:1
	v_add_u32_e32 v6, 0x30c0, v8
	ds_write2_b32 v6, v94, v95 offset1:1
	v_add_u32_e32 v6, 0x30c8, v8
	ds_write2_b32 v6, v96, v97 offset1:1
	v_add_u32_e32 v6, 0x34d0, v8
	ds_write2_b32 v6, v98, v99 offset1:1
	v_add_u32_e32 v6, 0x34d8, v8
	ds_write2_b32 v6, v100, v101 offset1:1
	v_add_u32_e32 v6, 0x38e0, v8
	ds_write2_b32 v6, v102, v103 offset1:1
	v_add_u32_e32 v6, 0x38e8, v8
	ds_write2_b32 v6, v104, v105 offset1:1
	v_add_u32_e32 v6, 0x3cf0, v8
	s_waitcnt vmcnt(0)
	ds_write2_b32 v6, v106, v107 offset1:1
	v_add_u32_e32 v6, 0x3cf8, v8
	ds_write2_b32 v6, v108, v109 offset1:1
	s_waitcnt lgkmcnt(0)
	ds_read2_b32 v[50:51], v10 offset1:8
	ds_read2_b32 v[52:53], v10 offset0:65 offset1:73
	ds_read2_b32 v[54:55], v10 offset0:130 offset1:138
	ds_read2_b32 v[56:57], v10 offset0:195 offset1:203
	ds_read2_b32 v[58:59], v45 offset0:4 offset1:12
	s_waitcnt lgkmcnt(4)
	v_bfe_u32 v6, v50, 16, 1
	v_add3_u32 v6, v50, v6, s41
	s_waitcnt lgkmcnt(3)
	v_bfe_u32 v7, v52, 16, 1
	v_lshrrev_b32_e32 v6, 16, v6
	v_add3_u32 v7, v52, v7, s41
	ds_read2_b32 v[60:61], v45 offset0:69 offset1:77
	v_and_or_b32 v46, v7, s42, v6
	s_waitcnt lgkmcnt(3)
	v_bfe_u32 v6, v54, 16, 1
	v_add3_u32 v6, v54, v6, s41
	s_waitcnt lgkmcnt(2)
	v_bfe_u32 v7, v56, 16, 1
	ds_read2_b32 v[62:63], v45 offset0:134 offset1:142
	v_lshrrev_b32_e32 v6, 16, v6
	v_add3_u32 v7, v56, v7, s41
	ds_read2_b32 v[64:65], v45 offset0:199 offset1:207
	v_and_or_b32 v47, v7, s42, v6
	s_waitcnt lgkmcnt(3)
	v_bfe_u32 v6, v58, 16, 1
	v_add3_u32 v6, v58, v6, s41
	s_waitcnt lgkmcnt(2)
	v_bfe_u32 v7, v60, 16, 1
	v_lshrrev_b32_e32 v6, 16, v6
	v_add3_u32 v7, v60, v7, s41
	v_and_or_b32 v48, v7, s42, v6
	s_waitcnt lgkmcnt(1)
	v_bfe_u32 v6, v62, 16, 1
	v_add3_u32 v6, v62, v6, s41
	s_waitcnt lgkmcnt(0)
	v_bfe_u32 v7, v64, 16, 1
	v_lshrrev_b32_e32 v6, 16, v6
	v_add3_u32 v7, v64, v7, s41
	v_and_or_b32 v49, v7, s42, v6
	v_add_u32_e32 v6, s6, v9
	v_and_b32_e32 v7, 0xffffffc0, v6
	v_add_u32_e32 v7, v7, v18
	v_cmp_gt_i32_e32 vcc, s46, v6
	v_mov_b32_e32 v67, v3
	v_mov_b32_e32 v69, v3
	v_cndmask_b32_e32 v50, v6, v7, vcc
	v_ashrrev_i32_e32 v6, 8, v50
	v_ashrrev_i32_e32 v7, 31, v6
	v_lshlrev_b64 v[6:7], 20, v[6:7]
	v_lshlrev_b32_e32 v50, 7, v50
	v_lshl_add_u64 v[6:7], s[8:9], 0, v[6:7]
	v_and_b32_e32 v66, 0x7f80, v50
	v_lshl_add_u64 v[66:67], v[6:7], 0, v[66:67]
	v_lshlrev_b32_e32 v6, 1, v4
	v_mov_b32_e32 v7, v3
	v_lshl_add_u64 v[66:67], v[66:67], 0, v[6:7]
	global_store_dwordx4 v[66:67], v[46:49], off
	v_bfe_u32 v50, v65, 16, 1
	v_add3_u32 v50, v65, v50, s41
	v_bfe_u32 v46, v51, 16, 1
	v_add3_u32 v46, v51, v46, s41
	v_bfe_u32 v47, v53, 16, 1
	v_lshrrev_b32_e32 v46, 16, v46
	v_add3_u32 v47, v53, v47, s41
	v_and_or_b32 v46, v47, s42, v46
	v_bfe_u32 v47, v55, 16, 1
	v_add3_u32 v47, v55, v47, s41
	v_bfe_u32 v48, v57, 16, 1
	v_lshrrev_b32_e32 v47, 16, v47
	v_add3_u32 v48, v57, v48, s41
	v_and_or_b32 v47, v48, s42, v47
	v_bfe_u32 v48, v59, 16, 1
	v_add3_u32 v48, v59, v48, s41
	v_bfe_u32 v49, v61, 16, 1
	v_lshrrev_b32_e32 v48, 16, v48
	v_add3_u32 v49, v61, v49, s41
	v_and_or_b32 v48, v49, s42, v48
	v_bfe_u32 v49, v63, 16, 1
	v_add3_u32 v49, v63, v49, s41
	v_lshrrev_b32_e32 v49, 16, v49
	v_and_or_b32 v49, v50, s42, v49
	v_add_u32_e32 v50, s6, v11
	v_and_b32_e32 v51, 0xffffffc0, v50
	v_add_u32_e32 v51, v51, v19
	v_cmp_gt_i32_e32 vcc, s46, v50
	v_mov_b32_e32 v53, v3
	ds_read2_b32 v[54:55], v10 offset0:16 offset1:24
	v_cndmask_b32_e32 v52, v50, v51, vcc
	v_ashrrev_i32_e32 v50, 8, v52
	v_ashrrev_i32_e32 v51, 31, v50
	v_lshlrev_b64 v[50:51], 20, v[50:51]
	v_lshlrev_b32_e32 v52, 7, v52
	v_lshl_add_u64 v[50:51], s[8:9], 0, v[50:51]
	v_and_b32_e32 v52, 0x7f80, v52
	v_lshl_add_u64 v[50:51], v[50:51], 0, v[52:53]
	v_lshl_add_u64 v[50:51], v[50:51], 0, v[6:7]
	global_store_dwordx4 v[50:51], v[46:49], off
	ds_read2_b32 v[50:51], v10 offset0:81 offset1:89
	ds_read2_b32 v[52:53], v10 offset0:146 offset1:154
	ds_read2_b32 v[56:57], v10 offset0:211 offset1:219
	s_waitcnt lgkmcnt(3)
	v_bfe_u32 v46, v54, 16, 1
	v_add3_u32 v46, v54, v46, s41
	s_waitcnt lgkmcnt(2)
	v_bfe_u32 v47, v50, 16, 1
	ds_read2_b32 v[58:59], v45 offset0:20 offset1:28
	v_lshrrev_b32_e32 v46, 16, v46
	v_add3_u32 v47, v50, v47, s41
	ds_read2_b32 v[60:61], v45 offset0:85 offset1:93
	v_and_or_b32 v46, v47, s42, v46
	s_waitcnt lgkmcnt(3)
	v_bfe_u32 v47, v52, 16, 1
	v_add3_u32 v47, v52, v47, s41
	s_waitcnt lgkmcnt(2)
	v_bfe_u32 v48, v56, 16, 1
	ds_read2_b32 v[62:63], v45 offset0:150 offset1:158
	v_lshrrev_b32_e32 v47, 16, v47
	v_add3_u32 v48, v56, v48, s41
	ds_read2_b32 v[64:65], v45 offset0:215 offset1:223
	v_and_or_b32 v47, v48, s42, v47
	s_waitcnt lgkmcnt(3)
	v_bfe_u32 v48, v58, 16, 1
	v_add3_u32 v48, v58, v48, s41
	s_waitcnt lgkmcnt(2)
	v_bfe_u32 v49, v60, 16, 1
	v_lshrrev_b32_e32 v48, 16, v48
	v_add3_u32 v49, v60, v49, s41
	v_and_or_b32 v48, v49, s42, v48
	s_waitcnt lgkmcnt(1)
	v_bfe_u32 v49, v62, 16, 1
	v_add3_u32 v49, v62, v49, s41
	s_waitcnt lgkmcnt(0)
	v_bfe_u32 v50, v64, 16, 1
	v_lshrrev_b32_e32 v49, 16, v49
	v_add3_u32 v50, v64, v50, s41
	v_and_or_b32 v49, v50, s42, v49
	v_add_u32_e32 v50, s6, v12
	v_and_b32_e32 v52, 0xffffffc0, v50
	v_add_u32_e32 v52, v52, v20
	v_cmp_gt_i32_e32 vcc, s46, v50
	s_nop 1
	v_cndmask_b32_e32 v50, v50, v52, vcc
	v_ashrrev_i32_e32 v66, 8, v50
	v_ashrrev_i32_e32 v67, 31, v66
	v_lshlrev_b64 v[66:67], 20, v[66:67]
	v_lshlrev_b32_e32 v50, 7, v50
	v_lshl_add_u64 v[66:67], s[8:9], 0, v[66:67]
	v_and_b32_e32 v68, 0x7f80, v50
	v_lshl_add_u64 v[66:67], v[66:67], 0, v[68:69]
	v_lshl_add_u64 v[66:67], v[66:67], 0, v[6:7]
	global_store_dwordx4 v[66:67], v[46:49], off
	v_bfe_u32 v50, v65, 16, 1
	v_add3_u32 v50, v65, v50, s41
	v_bfe_u32 v46, v55, 16, 1
	v_add3_u32 v46, v55, v46, s41
	v_bfe_u32 v47, v51, 16, 1
	v_lshrrev_b32_e32 v46, 16, v46
	v_add3_u32 v47, v51, v47, s41
	v_and_or_b32 v46, v47, s42, v46
	v_bfe_u32 v47, v53, 16, 1
	v_add3_u32 v47, v53, v47, s41
	v_bfe_u32 v48, v57, 16, 1
	v_lshrrev_b32_e32 v47, 16, v47
	v_add3_u32 v48, v57, v48, s41
	v_and_or_b32 v47, v48, s42, v47
	v_bfe_u32 v48, v59, 16, 1
	v_add3_u32 v48, v59, v48, s41
	v_bfe_u32 v49, v61, 16, 1
	v_lshrrev_b32_e32 v48, 16, v48
	v_add3_u32 v49, v61, v49, s41
	v_and_or_b32 v48, v49, s42, v48
	v_bfe_u32 v49, v63, 16, 1
	v_add3_u32 v49, v63, v49, s41
	v_lshrrev_b32_e32 v49, 16, v49
	v_and_or_b32 v49, v50, s42, v49
	v_add_u32_e32 v50, s6, v13
	v_and_b32_e32 v51, 0xffffffc0, v50
	v_add_u32_e32 v51, v51, v21
	v_cmp_gt_i32_e32 vcc, s46, v50
	v_mov_b32_e32 v53, v3
	ds_read2_b32 v[54:55], v10 offset0:32 offset1:40
	v_cndmask_b32_e32 v52, v50, v51, vcc
	v_ashrrev_i32_e32 v50, 8, v52
	v_ashrrev_i32_e32 v51, 31, v50
	v_lshlrev_b64 v[50:51], 20, v[50:51]
	v_lshlrev_b32_e32 v52, 7, v52
	v_lshl_add_u64 v[50:51], s[8:9], 0, v[50:51]
	v_and_b32_e32 v52, 0x7f80, v52
	v_lshl_add_u64 v[50:51], v[50:51], 0, v[52:53]
	v_lshl_add_u64 v[50:51], v[50:51], 0, v[6:7]
	global_store_dwordx4 v[50:51], v[46:49], off
	ds_read2_b32 v[50:51], v10 offset0:97 offset1:105
	ds_read2_b32 v[52:53], v10 offset0:162 offset1:170
	ds_read2_b32 v[56:57], v10 offset0:227 offset1:235
	s_waitcnt lgkmcnt(3)
	v_bfe_u32 v46, v54, 16, 1
	v_add3_u32 v46, v54, v46, s41
	s_waitcnt lgkmcnt(2)
	v_bfe_u32 v47, v50, 16, 1
	ds_read2_b32 v[58:59], v45 offset0:36 offset1:44
	v_lshrrev_b32_e32 v46, 16, v46
	v_add3_u32 v47, v50, v47, s41
	ds_read2_b32 v[60:61], v45 offset0:101 offset1:109
	v_and_or_b32 v46, v47, s42, v46
	s_waitcnt lgkmcnt(3)
	v_bfe_u32 v47, v52, 16, 1
	v_add3_u32 v47, v52, v47, s41
	s_waitcnt lgkmcnt(2)
	v_bfe_u32 v48, v56, 16, 1
	ds_read2_b32 v[62:63], v45 offset0:166 offset1:174
	v_lshrrev_b32_e32 v47, 16, v47
	v_add3_u32 v48, v56, v48, s41
	ds_read2_b32 v[64:65], v45 offset0:231 offset1:239
	v_and_or_b32 v47, v48, s42, v47
	s_waitcnt lgkmcnt(3)
	v_bfe_u32 v48, v58, 16, 1
	v_add3_u32 v48, v58, v48, s41
	s_waitcnt lgkmcnt(2)
	v_bfe_u32 v49, v60, 16, 1
	v_lshrrev_b32_e32 v48, 16, v48
	v_add3_u32 v49, v60, v49, s41
	v_and_or_b32 v48, v49, s42, v48
	s_waitcnt lgkmcnt(1)
	v_bfe_u32 v49, v62, 16, 1
	v_add3_u32 v49, v62, v49, s41
	s_waitcnt lgkmcnt(0)
	v_bfe_u32 v50, v64, 16, 1
	v_lshrrev_b32_e32 v49, 16, v49
	v_add3_u32 v50, v64, v50, s41
	v_and_or_b32 v49, v50, s42, v49
	v_add_u32_e32 v50, s6, v14
	v_and_b32_e32 v52, 0xffffffc0, v50
	v_add_u32_e32 v52, v52, v22
	v_cmp_gt_i32_e32 vcc, s46, v50
	s_nop 1
	v_cndmask_b32_e32 v50, v50, v52, vcc
	v_ashrrev_i32_e32 v66, 8, v50
	v_ashrrev_i32_e32 v67, 31, v66
	v_lshlrev_b64 v[66:67], 20, v[66:67]
	v_lshlrev_b32_e32 v50, 7, v50
	v_lshl_add_u64 v[66:67], s[8:9], 0, v[66:67]
	v_and_b32_e32 v68, 0x7f80, v50
	v_lshl_add_u64 v[66:67], v[66:67], 0, v[68:69]
	v_lshl_add_u64 v[66:67], v[66:67], 0, v[6:7]
	global_store_dwordx4 v[66:67], v[46:49], off
	v_bfe_u32 v50, v65, 16, 1
	v_add3_u32 v50, v65, v50, s41
	v_bfe_u32 v46, v55, 16, 1
	v_add3_u32 v46, v55, v46, s41
	v_bfe_u32 v47, v51, 16, 1
	v_lshrrev_b32_e32 v46, 16, v46
	v_add3_u32 v47, v51, v47, s41
	v_and_or_b32 v46, v47, s42, v46
	v_bfe_u32 v47, v53, 16, 1
	v_add3_u32 v47, v53, v47, s41
	v_bfe_u32 v48, v57, 16, 1
	v_lshrrev_b32_e32 v47, 16, v47
	v_add3_u32 v48, v57, v48, s41
	v_and_or_b32 v47, v48, s42, v47
	v_bfe_u32 v48, v59, 16, 1
	v_add3_u32 v48, v59, v48, s41
	v_bfe_u32 v49, v61, 16, 1
	v_lshrrev_b32_e32 v48, 16, v48
	v_add3_u32 v49, v61, v49, s41
	v_and_or_b32 v48, v49, s42, v48
	v_bfe_u32 v49, v63, 16, 1
	v_add3_u32 v49, v63, v49, s41
	v_lshrrev_b32_e32 v49, 16, v49
	v_and_or_b32 v49, v50, s42, v49
	v_add_u32_e32 v50, s6, v15
	v_and_b32_e32 v51, 0xffffffc0, v50
	v_add_u32_e32 v51, v51, v23
	v_cmp_gt_i32_e32 vcc, s46, v50
	v_mov_b32_e32 v53, v3
	ds_read2_b32 v[54:55], v10 offset0:48 offset1:56
	v_cndmask_b32_e32 v52, v50, v51, vcc
	v_ashrrev_i32_e32 v50, 8, v52
	v_ashrrev_i32_e32 v51, 31, v50
	v_lshlrev_b64 v[50:51], 20, v[50:51]
	v_lshlrev_b32_e32 v52, 7, v52
	v_lshl_add_u64 v[50:51], s[8:9], 0, v[50:51]
	v_and_b32_e32 v52, 0x7f80, v52
	v_lshl_add_u64 v[50:51], v[50:51], 0, v[52:53]
	v_lshl_add_u64 v[50:51], v[50:51], 0, v[6:7]
	global_store_dwordx4 v[50:51], v[46:49], off
	ds_read2_b32 v[50:51], v10 offset0:113 offset1:121
	ds_read2_b32 v[52:53], v10 offset0:178 offset1:186
	ds_read2_b32 v[56:57], v10 offset0:243 offset1:251
	s_waitcnt lgkmcnt(3)
	v_bfe_u32 v46, v54, 16, 1
	v_add3_u32 v46, v54, v46, s41
	s_waitcnt lgkmcnt(2)
	v_bfe_u32 v47, v50, 16, 1
	ds_read2_b32 v[58:59], v45 offset0:52 offset1:60
	v_lshrrev_b32_e32 v46, 16, v46
	v_add3_u32 v47, v50, v47, s41
	ds_read2_b32 v[60:61], v45 offset0:117 offset1:125
	v_and_or_b32 v46, v47, s42, v46
	s_waitcnt lgkmcnt(3)
	v_bfe_u32 v47, v52, 16, 1
	ds_read2_b32 v[62:63], v45 offset0:182 offset1:190
	v_add3_u32 v47, v52, v47, s41
	s_waitcnt lgkmcnt(3)
	v_bfe_u32 v48, v56, 16, 1
	ds_read2_b32 v[64:65], v45 offset0:247 offset1:255
	v_lshrrev_b32_e32 v47, 16, v47
	v_add3_u32 v48, v56, v48, s41
	v_and_or_b32 v47, v48, s42, v47
	s_waitcnt lgkmcnt(3)
	v_bfe_u32 v48, v58, 16, 1
	v_add3_u32 v48, v58, v48, s41
	s_waitcnt lgkmcnt(2)
	v_bfe_u32 v49, v60, 16, 1
	v_lshrrev_b32_e32 v48, 16, v48
	v_add3_u32 v49, v60, v49, s41
	s_waitcnt lgkmcnt(1)
	v_bfe_u32 v45, v62, 16, 1
	v_and_or_b32 v48, v49, s42, v48
	v_add3_u32 v45, v62, v45, s41
	s_waitcnt lgkmcnt(0)
	v_bfe_u32 v49, v64, 16, 1
	v_lshrrev_b32_e32 v45, 16, v45
	v_add3_u32 v49, v64, v49, s41
	v_and_or_b32 v49, v49, s42, v45
	v_add_u32_e32 v45, s6, v16
	v_and_b32_e32 v50, 0xffffffc0, v45
	v_add_u32_e32 v50, v50, v24
	v_cmp_gt_i32_e32 vcc, s46, v45
	s_nop 1
	v_cndmask_b32_e32 v45, v45, v50, vcc
	v_ashrrev_i32_e32 v66, 8, v45
	v_ashrrev_i32_e32 v67, 31, v66
	v_lshlrev_b64 v[66:67], 20, v[66:67]
	v_lshlrev_b32_e32 v45, 7, v45
	v_lshl_add_u64 v[66:67], s[8:9], 0, v[66:67]
	v_and_b32_e32 v68, 0x7f80, v45
	v_lshl_add_u64 v[66:67], v[66:67], 0, v[68:69]
	v_lshl_add_u64 v[66:67], v[66:67], 0, v[6:7]
	v_bfe_u32 v45, v55, 16, 1
	global_store_dwordx4 v[66:67], v[46:49], off
	v_add3_u32 v45, v55, v45, s41
	v_lshrrev_b32_e32 v45, 16, v45
	v_bfe_u32 v46, v51, 16, 1
	v_add3_u32 v46, v51, v46, s41
	v_and_or_b32 v46, v46, s42, v45
	v_bfe_u32 v45, v53, 16, 1
	v_add3_u32 v45, v53, v45, s41
	v_bfe_u32 v47, v57, 16, 1
	v_lshrrev_b32_e32 v45, 16, v45
	v_add3_u32 v47, v57, v47, s41
	v_and_or_b32 v47, v47, s42, v45
	v_bfe_u32 v45, v59, 16, 1
	v_add3_u32 v45, v59, v45, s41
	v_bfe_u32 v48, v61, 16, 1
	v_lshrrev_b32_e32 v45, 16, v45
	v_add3_u32 v48, v61, v48, s41
	v_and_or_b32 v48, v48, s42, v45
	v_bfe_u32 v45, v63, 16, 1
	v_add3_u32 v45, v63, v45, s41
	v_bfe_u32 v49, v65, 16, 1
	v_lshrrev_b32_e32 v45, 16, v45
	v_add3_u32 v49, v65, v49, s41
	v_and_or_b32 v49, v49, s42, v45
	v_add_u32_e32 v45, s6, v17
	v_and_b32_e32 v50, 0xffffffc0, v45
	v_add_u32_e32 v50, v50, v25
	v_cmp_gt_i32_e32 vcc, s46, v45
	v_mov_b32_e32 v53, v3
	s_nop 0
	v_cndmask_b32_e32 v45, v45, v50, vcc
	v_ashrrev_i32_e32 v50, 8, v45
	v_ashrrev_i32_e32 v51, 31, v50
	v_lshlrev_b64 v[50:51], 20, v[50:51]
	v_lshlrev_b32_e32 v45, 7, v45
	v_lshl_add_u64 v[50:51], s[8:9], 0, v[50:51]
	v_and_b32_e32 v52, 0x7f80, v45
	v_lshl_add_u64 v[50:51], v[50:51], 0, v[52:53]
	v_lshl_add_u64 v[6:7], v[50:51], 0, v[6:7]
	global_store_dwordx4 v[6:7], v[46:49], off
	s_waitcnt lgkmcnt(0)

.LBB0_47:
	s_andn2_b64 vcc, exec, s[8:9]
	s_cbranch_vccnz .LBB0_49
	s_load_dwordx2 s[10:11], s[16:17], 0x48
	s_add_i32 s8, s22, 0x6200
	s_and_b32 s9, s8, 0x1fc0
	s_add_i32 s8, s20, 0xfffa8000
	s_and_b32 s8, s8, 0x7c0
	s_add_i32 s6, s47, 0xffffea00
	v_add_u32_e32 v6, s9, v5
	s_lshl_b32 s9, s8, 2
	s_waitcnt lgkmcnt(0)
	s_add_u32 s10, s10, s9
	s_addc_u32 s11, s11, 0
	v_ashrrev_i32_e32 v7, 31, v6
	v_lshl_add_u64 v[46:47], s[10:11], 0, v[2:3]
	v_lshlrev_b64 v[6:7], 13, v[6:7]
	v_lshl_add_u64 v[6:7], v[46:47], 0, v[6:7]
	v_add_co_u32_e32 v50, vcc, s25, v6
	v_add_u32_e32 v45, 0x400, v10
	s_nop 0
	v_addc_co_u32_e32 v51, vcc, 0, v7, vcc
	v_add_co_u32_e32 v54, vcc, s26, v6
	global_load_dwordx4 v[46:49], v[6:7], off nt
	s_nop 0
	global_load_dwordx4 v[50:53], v[50:51], off nt
	v_addc_co_u32_e32 v55, vcc, 0, v7, vcc
	v_add_co_u32_e32 v58, vcc, s27, v6
	s_lshr_b32 s6, s6, 5
	s_nop 0
	v_addc_co_u32_e32 v59, vcc, 0, v7, vcc
	v_add_co_u32_e32 v62, vcc, s28, v6
	global_load_dwordx4 v[54:57], v[54:55], off nt
	s_nop 0
	global_load_dwordx4 v[58:61], v[58:59], off nt
	v_addc_co_u32_e32 v63, vcc, 0, v7, vcc
	v_add_co_u32_e32 v66, vcc, s29, v6
	s_nop 1
	v_addc_co_u32_e32 v67, vcc, 0, v7, vcc
	v_add_co_u32_e32 v70, vcc, s30, v6
	global_load_dwordx4 v[62:65], v[62:63], off nt
	s_nop 0
	global_load_dwordx4 v[66:69], v[66:67], off nt
	v_addc_co_u32_e32 v71, vcc, 0, v7, vcc
	v_add_co_u32_e32 v74, vcc, s31, v6
	s_nop 1
	v_addc_co_u32_e32 v75, vcc, 0, v7, vcc
	v_add_co_u32_e32 v78, vcc, s33, v6
	global_load_dwordx4 v[70:73], v[70:71], off nt
	s_nop 0
	global_load_dwordx4 v[74:77], v[74:75], off nt
	v_addc_co_u32_e32 v79, vcc, 0, v7, vcc
	v_add_co_u32_e32 v82, vcc, s34, v6
	s_nop 1
	v_addc_co_u32_e32 v83, vcc, 0, v7, vcc
	v_add_co_u32_e32 v86, vcc, s35, v6
	global_load_dwordx4 v[78:81], v[78:79], off nt
	s_nop 0
	global_load_dwordx4 v[82:85], v[82:83], off nt
	v_addc_co_u32_e32 v87, vcc, 0, v7, vcc
	v_add_co_u32_e32 v90, vcc, s36, v6
	s_nop 1
	v_addc_co_u32_e32 v91, vcc, 0, v7, vcc
	global_load_dwordx4 v[86:89], v[86:87], off nt
	s_nop 0
	global_load_dwordx4 v[90:93], v[90:91], off nt
	v_add_co_u32_e32 v94, vcc, s37, v6
	s_nop 1
	v_addc_co_u32_e32 v95, vcc, 0, v7, vcc
	global_load_dwordx4 v[94:97], v[94:95], off nt
	v_add_co_u32_e32 v98, vcc, s38, v6
	s_nop 1
	v_addc_co_u32_e32 v99, vcc, 0, v7, vcc
	global_load_dwordx4 v[98:101], v[98:99], off nt
	v_add_co_u32_e32 v102, vcc, s39, v6
	s_nop 1
	v_addc_co_u32_e32 v103, vcc, 0, v7, vcc
	global_load_dwordx4 v[102:105], v[102:103], off nt
	v_add_co_u32_e32 v6, vcc, s40, v6
	s_nop 1
	v_addc_co_u32_e32 v7, vcc, 0, v7, vcc
	global_load_dwordx4 v[106:109], v[6:7], off nt
	v_add_u32_e32 v6, 0x2498, v8
	s_waitcnt vmcnt(15)
	ds_write2_b32 v8, v46, v47 offset1:1
	ds_write2_b32 v8, v48, v49 offset0:2 offset1:3
	s_waitcnt vmcnt(14)
	ds_write2_b32 v26, v50, v51 offset1:1
	ds_write2_b32 v27, v52, v53 offset1:1
	s_waitcnt vmcnt(13)
	ds_write2_b32 v28, v54, v55 offset1:1
	ds_write2_b32 v29, v56, v57 offset1:1
	s_waitcnt vmcnt(12)
	ds_write2_b32 v30, v58, v59 offset1:1
	ds_write2_b32 v31, v60, v61 offset1:1
	s_waitcnt vmcnt(11)
	ds_write2_b32 v32, v62, v63 offset1:1
	ds_write2_b32 v33, v64, v65 offset1:1
	s_waitcnt vmcnt(10)
	ds_write2_b32 v34, v66, v67 offset1:1
	ds_write2_b32 v35, v68, v69 offset1:1
	s_waitcnt vmcnt(9)
	ds_write2_b32 v36, v70, v71 offset1:1
	ds_write2_b32 v37, v72, v73 offset1:1
	s_waitcnt vmcnt(8)
	ds_write2_b32 v38, v74, v75 offset1:1
	ds_write2_b32 v39, v76, v77 offset1:1
	s_waitcnt vmcnt(7)
	ds_write2_b32 v40, v78, v79 offset1:1
	ds_write2_b32 v41, v80, v81 offset1:1
	s_waitcnt vmcnt(6)
	ds_write2_b32 v42, v82, v83 offset1:1
	ds_write2_b32 v6, v84, v85 offset1:1
	v_add_u32_e32 v6, 0x28a0, v8
	v_mov_b32_e32 v67, v3
	v_mov_b32_e32 v69, v3
	s_waitcnt vmcnt(5)
	ds_write2_b32 v6, v86, v87 offset1:1
	v_add_u32_e32 v6, 0x28a8, v8
	ds_write2_b32 v6, v88, v89 offset1:1
	v_add_u32_e32 v6, 0x2cb0, v8
	s_waitcnt vmcnt(4)
	ds_write2_b32 v6, v90, v91 offset1:1
	v_add_u32_e32 v6, 0x2cb8, v8
	ds_write2_b32 v6, v92, v93 offset1:1
	v_add_u32_e32 v6, 0x30c0, v8
	s_waitcnt vmcnt(3)
	ds_write2_b32 v6, v94, v95 offset1:1
	v_add_u32_e32 v6, 0x30c8, v8
	ds_write2_b32 v6, v96, v97 offset1:1
	v_add_u32_e32 v6, 0x34d0, v8
	s_waitcnt vmcnt(2)
	ds_write2_b32 v6, v98, v99 offset1:1
	v_add_u32_e32 v6, 0x34d8, v8
	ds_write2_b32 v6, v100, v101 offset1:1
	v_add_u32_e32 v6, 0x38e0, v8
	s_waitcnt vmcnt(1)
	ds_write2_b32 v6, v102, v103 offset1:1
	v_add_u32_e32 v6, 0x38e8, v8
	ds_write2_b32 v6, v104, v105 offset1:1
	v_add_u32_e32 v6, 0x3cf0, v8
	s_waitcnt vmcnt(0)
	ds_write2_b32 v6, v106, v107 offset1:1
	v_add_u32_e32 v6, 0x3cf8, v8
	ds_write2_b32 v6, v108, v109 offset1:1
	s_waitcnt lgkmcnt(0)
	ds_read2_b32 v[50:51], v10 offset1:8
	ds_read2_b32 v[52:53], v10 offset0:65 offset1:73
	ds_read2_b32 v[54:55], v10 offset0:130 offset1:138
	ds_read2_b32 v[56:57], v10 offset0:195 offset1:203
	ds_read2_b32 v[58:59], v45 offset0:4 offset1:12
	s_waitcnt lgkmcnt(4)
	v_bfe_u32 v6, v50, 16, 1
	v_add3_u32 v6, v50, v6, s41
	s_waitcnt lgkmcnt(3)
	v_bfe_u32 v7, v52, 16, 1
	v_lshrrev_b32_e32 v6, 16, v6
	v_add3_u32 v7, v52, v7, s41
	ds_read2_b32 v[60:61], v45 offset0:69 offset1:77
	v_and_or_b32 v46, v7, s42, v6
	s_waitcnt lgkmcnt(3)
	v_bfe_u32 v6, v54, 16, 1
	v_add3_u32 v6, v54, v6, s41
	s_waitcnt lgkmcnt(2)
	v_bfe_u32 v7, v56, 16, 1
	ds_read2_b32 v[62:63], v45 offset0:134 offset1:142
	v_lshrrev_b32_e32 v6, 16, v6
	v_add3_u32 v7, v56, v7, s41
	ds_read2_b32 v[64:65], v45 offset0:199 offset1:207
	v_and_or_b32 v47, v7, s42, v6
	s_waitcnt lgkmcnt(3)
	v_bfe_u32 v6, v58, 16, 1
	v_add3_u32 v6, v58, v6, s41
	s_waitcnt lgkmcnt(2)
	v_bfe_u32 v7, v60, 16, 1
	v_lshrrev_b32_e32 v6, 16, v6
	v_add3_u32 v7, v60, v7, s41
	v_and_or_b32 v48, v7, s42, v6
	s_waitcnt lgkmcnt(1)
	v_bfe_u32 v6, v62, 16, 1
	v_add3_u32 v6, v62, v6, s41
	s_waitcnt lgkmcnt(0)
	v_bfe_u32 v7, v64, 16, 1
	v_lshrrev_b32_e32 v6, 16, v6
	v_add3_u32 v7, v64, v7, s41
	v_add_u32_e32 v50, s8, v9
	v_and_or_b32 v49, v7, s42, v6
	v_lshrrev_b32_e32 v6, 8, v50
	v_mul_i32_i24_e32 v6, 0x58, v6
	v_ashrrev_i32_e32 v7, 31, v6
	v_lshl_add_u64 v[6:7], v[6:7], 0, s[6:7]
	v_lshlrev_b64 v[6:7], 15, v[6:7]
	v_lshlrev_b32_e32 v50, 7, v50
	v_lshl_add_u64 v[6:7], s[4:5], 0, v[6:7]
	v_and_b32_e32 v66, 0x7f80, v50
	v_lshl_add_u64 v[66:67], v[6:7], 0, v[66:67]
	v_lshlrev_b32_e32 v6, 1, v4
	v_mov_b32_e32 v7, v3
	v_lshl_add_u64 v[66:67], v[66:67], 0, v[6:7]
	global_store_dwordx4 v[66:67], v[46:49], off
	v_bfe_u32 v50, v65, 16, 1
	v_add3_u32 v50, v65, v50, s41
	v_bfe_u32 v46, v51, 16, 1
	v_add3_u32 v46, v51, v46, s41
	v_bfe_u32 v47, v53, 16, 1
	v_lshrrev_b32_e32 v46, 16, v46
	v_add3_u32 v47, v53, v47, s41
	v_and_or_b32 v46, v47, s42, v46
	v_bfe_u32 v47, v55, 16, 1
	v_add3_u32 v47, v55, v47, s41
	v_bfe_u32 v48, v57, 16, 1
	v_lshrrev_b32_e32 v47, 16, v47
	v_add3_u32 v48, v57, v48, s41
	v_and_or_b32 v47, v48, s42, v47
	v_bfe_u32 v48, v59, 16, 1
	v_add3_u32 v48, v59, v48, s41
	v_bfe_u32 v49, v61, 16, 1
	v_lshrrev_b32_e32 v48, 16, v48
	v_add3_u32 v49, v61, v49, s41
	v_and_or_b32 v48, v49, s42, v48
	v_bfe_u32 v49, v63, 16, 1
	v_add3_u32 v49, v63, v49, s41
	v_lshrrev_b32_e32 v49, 16, v49
	v_add_u32_e32 v52, s8, v11
	v_and_or_b32 v49, v50, s42, v49
	v_lshrrev_b32_e32 v50, 8, v52
	v_mul_i32_i24_e32 v50, 0x58, v50
	v_ashrrev_i32_e32 v51, 31, v50
	v_lshl_add_u64 v[50:51], v[50:51], 0, s[6:7]
	v_lshlrev_b64 v[50:51], 15, v[50:51]
	v_lshlrev_b32_e32 v52, 7, v52
	v_lshl_add_u64 v[50:51], s[4:5], 0, v[50:51]
	v_and_b32_e32 v52, 0x7f80, v52
	v_mov_b32_e32 v53, v3
	v_lshl_add_u64 v[50:51], v[50:51], 0, v[52:53]
	ds_read2_b32 v[54:55], v10 offset0:16 offset1:24
	v_lshl_add_u64 v[50:51], v[50:51], 0, v[6:7]
	global_store_dwordx4 v[50:51], v[46:49], off
	ds_read2_b32 v[50:51], v10 offset0:81 offset1:89
	ds_read2_b32 v[52:53], v10 offset0:146 offset1:154
	ds_read2_b32 v[56:57], v10 offset0:211 offset1:219
	s_waitcnt lgkmcnt(3)
	v_bfe_u32 v46, v54, 16, 1
	v_add3_u32 v46, v54, v46, s41
	s_waitcnt lgkmcnt(2)
	v_bfe_u32 v47, v50, 16, 1
	ds_read2_b32 v[58:59], v45 offset0:20 offset1:28
	v_lshrrev_b32_e32 v46, 16, v46
	v_add3_u32 v47, v50, v47, s41
	ds_read2_b32 v[60:61], v45 offset0:85 offset1:93
	v_and_or_b32 v46, v47, s42, v46
	s_waitcnt lgkmcnt(3)
	v_bfe_u32 v47, v52, 16, 1
	v_add3_u32 v47, v52, v47, s41
	s_waitcnt lgkmcnt(2)
	v_bfe_u32 v48, v56, 16, 1
	ds_read2_b32 v[62:63], v45 offset0:150 offset1:158
	v_lshrrev_b32_e32 v47, 16, v47
	v_add3_u32 v48, v56, v48, s41
	ds_read2_b32 v[64:65], v45 offset0:215 offset1:223
	v_and_or_b32 v47, v48, s42, v47
	s_waitcnt lgkmcnt(3)
	v_bfe_u32 v48, v58, 16, 1
	v_add3_u32 v48, v58, v48, s41
	s_waitcnt lgkmcnt(2)
	v_bfe_u32 v49, v60, 16, 1
	v_lshrrev_b32_e32 v48, 16, v48
	v_add3_u32 v49, v60, v49, s41
	v_and_or_b32 v48, v49, s42, v48
	s_waitcnt lgkmcnt(1)
	v_bfe_u32 v49, v62, 16, 1
	v_add3_u32 v49, v62, v49, s41
	s_waitcnt lgkmcnt(0)
	v_bfe_u32 v50, v64, 16, 1
	v_lshrrev_b32_e32 v49, 16, v49
	v_add3_u32 v50, v64, v50, s41
	v_and_or_b32 v49, v50, s42, v49
	v_add_u32_e32 v50, s8, v12
	v_lshrrev_b32_e32 v52, 8, v50
	v_mul_i32_i24_e32 v66, 0x58, v52
	v_ashrrev_i32_e32 v67, 31, v66
	v_lshl_add_u64 v[66:67], v[66:67], 0, s[6:7]
	v_lshlrev_b64 v[66:67], 15, v[66:67]
	v_lshlrev_b32_e32 v50, 7, v50
	v_lshl_add_u64 v[66:67], s[4:5], 0, v[66:67]
	v_and_b32_e32 v68, 0x7f80, v50
	v_lshl_add_u64 v[66:67], v[66:67], 0, v[68:69]
	v_lshl_add_u64 v[66:67], v[66:67], 0, v[6:7]
	global_store_dwordx4 v[66:67], v[46:49], off
	v_bfe_u32 v50, v65, 16, 1
	v_add3_u32 v50, v65, v50, s41
	v_bfe_u32 v46, v55, 16, 1
	v_add3_u32 v46, v55, v46, s41
	v_bfe_u32 v47, v51, 16, 1
	v_lshrrev_b32_e32 v46, 16, v46
	v_add3_u32 v47, v51, v47, s41
	v_and_or_b32 v46, v47, s42, v46
	v_bfe_u32 v47, v53, 16, 1
	v_add3_u32 v47, v53, v47, s41
	v_bfe_u32 v48, v57, 16, 1
	v_lshrrev_b32_e32 v47, 16, v47
	v_add3_u32 v48, v57, v48, s41
	v_and_or_b32 v47, v48, s42, v47
	v_bfe_u32 v48, v59, 16, 1
	v_add3_u32 v48, v59, v48, s41
	v_bfe_u32 v49, v61, 16, 1
	v_lshrrev_b32_e32 v48, 16, v48
	v_add3_u32 v49, v61, v49, s41
	v_and_or_b32 v48, v49, s42, v48
	v_bfe_u32 v49, v63, 16, 1
	v_add3_u32 v49, v63, v49, s41
	v_lshrrev_b32_e32 v49, 16, v49
	v_add_u32_e32 v52, s8, v13
	v_and_or_b32 v49, v50, s42, v49
	v_lshrrev_b32_e32 v50, 8, v52
	v_mul_i32_i24_e32 v50, 0x58, v50
	v_ashrrev_i32_e32 v51, 31, v50
	v_lshl_add_u64 v[50:51], v[50:51], 0, s[6:7]
	v_lshlrev_b64 v[50:51], 15, v[50:51]
	v_lshlrev_b32_e32 v52, 7, v52
	v_lshl_add_u64 v[50:51], s[4:5], 0, v[50:51]
	v_and_b32_e32 v52, 0x7f80, v52
	v_mov_b32_e32 v53, v3
	v_lshl_add_u64 v[50:51], v[50:51], 0, v[52:53]
	ds_read2_b32 v[54:55], v10 offset0:32 offset1:40
	v_lshl_add_u64 v[50:51], v[50:51], 0, v[6:7]
	global_store_dwordx4 v[50:51], v[46:49], off
	ds_read2_b32 v[50:51], v10 offset0:97 offset1:105
	ds_read2_b32 v[52:53], v10 offset0:162 offset1:170
	ds_read2_b32 v[56:57], v10 offset0:227 offset1:235
	s_waitcnt lgkmcnt(3)
	v_bfe_u32 v46, v54, 16, 1
	v_add3_u32 v46, v54, v46, s41
	s_waitcnt lgkmcnt(2)
	v_bfe_u32 v47, v50, 16, 1
	ds_read2_b32 v[58:59], v45 offset0:36 offset1:44
	v_lshrrev_b32_e32 v46, 16, v46
	v_add3_u32 v47, v50, v47, s41
	ds_read2_b32 v[60:61], v45 offset0:101 offset1:109
	v_and_or_b32 v46, v47, s42, v46
	s_waitcnt lgkmcnt(3)
	v_bfe_u32 v47, v52, 16, 1
	v_add3_u32 v47, v52, v47, s41
	s_waitcnt lgkmcnt(2)
	v_bfe_u32 v48, v56, 16, 1
	ds_read2_b32 v[62:63], v45 offset0:166 offset1:174
	v_lshrrev_b32_e32 v47, 16, v47
	v_add3_u32 v48, v56, v48, s41
	ds_read2_b32 v[64:65], v45 offset0:231 offset1:239
	v_and_or_b32 v47, v48, s42, v47
	s_waitcnt lgkmcnt(3)
	v_bfe_u32 v48, v58, 16, 1
	v_add3_u32 v48, v58, v48, s41
	s_waitcnt lgkmcnt(2)
	v_bfe_u32 v49, v60, 16, 1
	v_lshrrev_b32_e32 v48, 16, v48
	v_add3_u32 v49, v60, v49, s41
	v_and_or_b32 v48, v49, s42, v48
	s_waitcnt lgkmcnt(1)
	v_bfe_u32 v49, v62, 16, 1
	v_add3_u32 v49, v62, v49, s41
	s_waitcnt lgkmcnt(0)
	v_bfe_u32 v50, v64, 16, 1
	v_lshrrev_b32_e32 v49, 16, v49
	v_add3_u32 v50, v64, v50, s41
	v_and_or_b32 v49, v50, s42, v49
	v_add_u32_e32 v50, s8, v14
	v_lshrrev_b32_e32 v52, 8, v50
	v_mul_i32_i24_e32 v66, 0x58, v52
	v_ashrrev_i32_e32 v67, 31, v66
	v_lshl_add_u64 v[66:67], v[66:67], 0, s[6:7]
	v_lshlrev_b64 v[66:67], 15, v[66:67]
	v_lshlrev_b32_e32 v50, 7, v50
	v_lshl_add_u64 v[66:67], s[4:5], 0, v[66:67]
	v_and_b32_e32 v68, 0x7f80, v50
	v_lshl_add_u64 v[66:67], v[66:67], 0, v[68:69]
	v_lshl_add_u64 v[66:67], v[66:67], 0, v[6:7]
	global_store_dwordx4 v[66:67], v[46:49], off
	v_bfe_u32 v50, v65, 16, 1
	v_add3_u32 v50, v65, v50, s41
	v_bfe_u32 v46, v55, 16, 1
	v_add3_u32 v46, v55, v46, s41
	v_bfe_u32 v47, v51, 16, 1
	v_lshrrev_b32_e32 v46, 16, v46
	v_add3_u32 v47, v51, v47, s41
	v_and_or_b32 v46, v47, s42, v46
	v_bfe_u32 v47, v53, 16, 1
	v_add3_u32 v47, v53, v47, s41
	v_bfe_u32 v48, v57, 16, 1
	v_lshrrev_b32_e32 v47, 16, v47
	v_add3_u32 v48, v57, v48, s41
	v_and_or_b32 v47, v48, s42, v47
	v_bfe_u32 v48, v59, 16, 1
	v_add3_u32 v48, v59, v48, s41
	v_bfe_u32 v49, v61, 16, 1
	v_lshrrev_b32_e32 v48, 16, v48
	v_add3_u32 v49, v61, v49, s41
	v_and_or_b32 v48, v49, s42, v48
	v_bfe_u32 v49, v63, 16, 1
	v_add3_u32 v49, v63, v49, s41
	v_lshrrev_b32_e32 v49, 16, v49
	v_add_u32_e32 v52, s8, v15
	v_and_or_b32 v49, v50, s42, v49
	v_lshrrev_b32_e32 v50, 8, v52
	v_mul_i32_i24_e32 v50, 0x58, v50
	v_ashrrev_i32_e32 v51, 31, v50
	v_lshl_add_u64 v[50:51], v[50:51], 0, s[6:7]
	v_lshlrev_b64 v[50:51], 15, v[50:51]
	v_lshlrev_b32_e32 v52, 7, v52
	v_lshl_add_u64 v[50:51], s[4:5], 0, v[50:51]
	v_and_b32_e32 v52, 0x7f80, v52
	v_mov_b32_e32 v53, v3
	v_lshl_add_u64 v[50:51], v[50:51], 0, v[52:53]
	ds_read2_b32 v[54:55], v10 offset0:48 offset1:56
	v_lshl_add_u64 v[50:51], v[50:51], 0, v[6:7]
	global_store_dwordx4 v[50:51], v[46:49], off
	ds_read2_b32 v[50:51], v10 offset0:113 offset1:121
	ds_read2_b32 v[52:53], v10 offset0:178 offset1:186
	ds_read2_b32 v[56:57], v10 offset0:243 offset1:251
	s_waitcnt lgkmcnt(3)
	v_bfe_u32 v46, v54, 16, 1
	v_add3_u32 v46, v54, v46, s41
	s_waitcnt lgkmcnt(2)
	v_bfe_u32 v47, v50, 16, 1
	ds_read2_b32 v[58:59], v45 offset0:52 offset1:60
	v_lshrrev_b32_e32 v46, 16, v46
	v_add3_u32 v47, v50, v47, s41
	ds_read2_b32 v[60:61], v45 offset0:117 offset1:125
	v_and_or_b32 v46, v47, s42, v46
	s_waitcnt lgkmcnt(3)
	v_bfe_u32 v47, v52, 16, 1
	ds_read2_b32 v[62:63], v45 offset0:182 offset1:190
	v_add3_u32 v47, v52, v47, s41
	s_waitcnt lgkmcnt(3)
	v_bfe_u32 v48, v56, 16, 1
	ds_read2_b32 v[64:65], v45 offset0:247 offset1:255
	v_lshrrev_b32_e32 v47, 16, v47
	v_add3_u32 v48, v56, v48, s41
	v_and_or_b32 v47, v48, s42, v47
	s_waitcnt lgkmcnt(3)
	v_bfe_u32 v48, v58, 16, 1
	v_add3_u32 v48, v58, v48, s41
	s_waitcnt lgkmcnt(2)
	v_bfe_u32 v49, v60, 16, 1
	v_lshrrev_b32_e32 v48, 16, v48
	v_add3_u32 v49, v60, v49, s41
	s_waitcnt lgkmcnt(1)
	v_bfe_u32 v45, v62, 16, 1
	v_and_or_b32 v48, v49, s42, v48
	v_add3_u32 v45, v62, v45, s41
	s_waitcnt lgkmcnt(0)
	v_bfe_u32 v49, v64, 16, 1
	v_lshrrev_b32_e32 v45, 16, v45
	v_add3_u32 v49, v64, v49, s41
	v_and_or_b32 v49, v49, s42, v45
	v_add_u32_e32 v45, s8, v16
	v_lshrrev_b32_e32 v50, 8, v45
	v_mul_i32_i24_e32 v66, 0x58, v50
	v_ashrrev_i32_e32 v67, 31, v66
	v_lshl_add_u64 v[66:67], v[66:67], 0, s[6:7]
	v_lshlrev_b64 v[66:67], 15, v[66:67]
	v_lshlrev_b32_e32 v45, 7, v45
	v_lshl_add_u64 v[66:67], s[4:5], 0, v[66:67]
	v_and_b32_e32 v68, 0x7f80, v45
	v_lshl_add_u64 v[66:67], v[66:67], 0, v[68:69]
	v_lshl_add_u64 v[66:67], v[66:67], 0, v[6:7]
	v_bfe_u32 v45, v55, 16, 1
	global_store_dwordx4 v[66:67], v[46:49], off
	v_add3_u32 v45, v55, v45, s41
	v_lshrrev_b32_e32 v45, 16, v45
	v_bfe_u32 v46, v51, 16, 1
	v_add3_u32 v46, v51, v46, s41
	v_and_or_b32 v46, v46, s42, v45
	v_bfe_u32 v45, v53, 16, 1
	v_add3_u32 v45, v53, v45, s41
	v_bfe_u32 v47, v57, 16, 1
	v_lshrrev_b32_e32 v45, 16, v45
	v_add3_u32 v47, v57, v47, s41
	v_and_or_b32 v47, v47, s42, v45
	v_bfe_u32 v45, v59, 16, 1
	v_add3_u32 v45, v59, v45, s41
	v_bfe_u32 v48, v61, 16, 1
	v_lshrrev_b32_e32 v45, 16, v45
	v_add3_u32 v48, v61, v48, s41
	v_and_or_b32 v48, v48, s42, v45
	v_bfe_u32 v45, v63, 16, 1
	v_add3_u32 v45, v63, v45, s41
	v_bfe_u32 v49, v65, 16, 1
	v_lshrrev_b32_e32 v45, 16, v45
	v_add3_u32 v49, v65, v49, s41
	v_and_or_b32 v49, v49, s42, v45
	v_add_u32_e32 v45, s8, v17
	v_lshrrev_b32_e32 v50, 8, v45
	v_mul_i32_i24_e32 v50, 0x58, v50
	v_ashrrev_i32_e32 v51, 31, v50
	v_lshl_add_u64 v[50:51], v[50:51], 0, s[6:7]
	v_lshlrev_b64 v[50:51], 15, v[50:51]
	v_lshlrev_b32_e32 v45, 7, v45
	v_lshl_add_u64 v[50:51], s[4:5], 0, v[50:51]
	v_and_b32_e32 v52, 0x7f80, v45
	v_mov_b32_e32 v53, v3
	v_lshl_add_u64 v[50:51], v[50:51], 0, v[52:53]
	v_lshl_add_u64 v[6:7], v[50:51], 0, v[6:7]
	global_store_dwordx4 v[6:7], v[46:49], off
	s_waitcnt lgkmcnt(0)

.LBB0_50:
	s_andn2_b64 vcc, exec, s[8:9]
	s_cbranch_vccnz .LBB0_31
	s_mul_hi_i32 s6, s47, 0x2e8ba2e9
	s_lshr_b32 s10, s6, 31
	s_ashr_i32 s6, s6, 5
	s_load_dwordx2 s[8:9], s[16:17], 0x40
	s_add_i32 s10, s6, s10
	s_mul_i32 s6, s10, 0xffffd400
	s_add_i32 s48, s20, s6
	s_ashr_i32 s49, s48, 31
	s_lshl_b64 s[48:49], s[48:49], 2
	s_waitcnt lgkmcnt(0)
	s_add_u32 s8, s8, s48
	v_lshl_add_u32 v45, s10, 6, v5
	s_addc_u32 s9, s9, s49
	v_lshl_add_u64 v[6:7], s[8:9], 0, v[2:3]
	v_add_u32_e32 v48, 4, v45
	v_add_u32_e32 v54, 8, v45
	v_add_u32_e32 v56, 12, v45
	v_add_u32_e32 v62, 16, v45
	v_add_u32_e32 v64, 20, v45
	v_add_u32_e32 v70, 24, v45
	v_add_u32_e32 v72, 28, v45
	v_add_u32_e32 v82, 36, v45
	v_mad_i64_i32 v[46:47], s[8:9], v45, s43, v[6:7]
	v_mad_i64_i32 v[50:51], s[8:9], v48, s43, v[6:7]
	v_mad_i64_i32 v[54:55], s[8:9], v54, s43, v[6:7]
	v_mad_i64_i32 v[58:59], s[8:9], v56, s43, v[6:7]
	v_mad_i64_i32 v[62:63], s[8:9], v62, s43, v[6:7]
	v_mad_i64_i32 v[66:67], s[8:9], v64, s43, v[6:7]
	v_mad_i64_i32 v[70:71], s[8:9], v70, s43, v[6:7]
	v_mad_i64_i32 v[74:75], s[8:9], v72, s43, v[6:7]
	v_mad_i64_i32 v[82:83], s[8:9], v82, s43, v[6:7]
	v_add_u32_e32 v86, 40, v45
	global_load_dwordx4 v[46:49], v[46:47], off nt
	s_nop 0
	global_load_dwordx4 v[50:53], v[50:51], off nt
	s_nop 0
	global_load_dwordx4 v[54:57], v[54:55], off nt
	s_nop 0
	global_load_dwordx4 v[58:61], v[58:59], off nt
	s_nop 0
	global_load_dwordx4 v[62:65], v[62:63], off nt
	s_nop 0
	global_load_dwordx4 v[66:69], v[66:67], off nt
	s_nop 0
	global_load_dwordx4 v[70:73], v[70:71], off nt
	s_nop 0
	global_load_dwordx4 v[74:77], v[74:75], off nt
	v_mad_i64_i32 v[86:87], s[8:9], v86, s43, v[6:7]
	global_load_dwordx4 v[82:85], v[82:83], off nt
	v_add_u32_e32 v90, 44, v45
	global_load_dwordx4 v[86:89], v[86:87], off nt
	v_mad_i64_i32 v[90:91], s[8:9], v90, s43, v[6:7]
	global_load_dwordx4 v[90:93], v[90:91], off nt
	v_add_u32_e32 v94, 48, v45
	v_mad_i64_i32 v[94:95], s[8:9], v94, s43, v[6:7]
	global_load_dwordx4 v[94:97], v[94:95], off nt
	v_add_u32_e32 v98, 52, v45
	v_mad_i64_i32 v[98:99], s[8:9], v98, s43, v[6:7]
	global_load_dwordx4 v[98:101], v[98:99], off nt
	v_add_u32_e32 v102, 56, v45
	v_mad_i64_i32 v[102:103], s[8:9], v102, s43, v[6:7]
	v_add_u32_e32 v78, 32, v45
	global_load_dwordx4 v[102:105], v[102:103], off nt
	v_add_u32_e32 v45, 60, v45
	v_mad_i64_i32 v[78:79], s[8:9], v78, s43, v[6:7]
	v_mad_i64_i32 v[6:7], s[8:9], v45, s43, v[6:7]
	global_load_dwordx4 v[78:81], v[78:79], off nt
	v_add_u32_e32 v45, 0x400, v10
	global_load_dwordx4 v[106:109], v[6:7], off nt
	v_add_u32_e32 v6, 0x2498, v8
	s_ashr_i32 s11, s10, 31
	s_lshl_b64 s[8:9], s[10:11], 15
	s_add_u32 s8, s12, s8
	s_addc_u32 s9, s13, s9
	s_waitcnt vmcnt(15)
	ds_write2_b32 v8, v46, v47 offset1:1
	ds_write2_b32 v8, v48, v49 offset0:2 offset1:3
	s_waitcnt vmcnt(14)
	ds_write2_b32 v26, v50, v51 offset1:1
	ds_write2_b32 v27, v52, v53 offset1:1
	s_waitcnt vmcnt(13)
	ds_write2_b32 v28, v54, v55 offset1:1
	ds_write2_b32 v29, v56, v57 offset1:1
	s_waitcnt vmcnt(12)
	ds_write2_b32 v30, v58, v59 offset1:1
	ds_write2_b32 v31, v60, v61 offset1:1
	s_waitcnt vmcnt(11)
	ds_write2_b32 v32, v62, v63 offset1:1
	ds_write2_b32 v33, v64, v65 offset1:1
	s_waitcnt vmcnt(10)
	ds_write2_b32 v34, v66, v67 offset1:1
	ds_write2_b32 v35, v68, v69 offset1:1
	s_waitcnt vmcnt(9)
	ds_write2_b32 v36, v70, v71 offset1:1
	ds_write2_b32 v37, v72, v73 offset1:1
	s_waitcnt vmcnt(8)
	ds_write2_b32 v38, v74, v75 offset1:1
	ds_write2_b32 v39, v76, v77 offset1:1
	s_waitcnt vmcnt(1)
	ds_write2_b32 v40, v78, v79 offset1:1
	ds_write2_b32 v41, v80, v81 offset1:1
	ds_write2_b32 v42, v82, v83 offset1:1
	ds_write2_b32 v6, v84, v85 offset1:1
	v_add_u32_e32 v6, 0x28a0, v8
	ds_write2_b32 v6, v86, v87 offset1:1
	v_add_u32_e32 v6, 0x28a8, v8
	ds_write2_b32 v6, v88, v89 offset1:1
	v_add_u32_e32 v6, 0x2cb0, v8
	ds_write2_b32 v6, v90, v91 offset1:1
	v_add_u32_e32 v6, 0x2cb8, v8
	ds_write2_b32 v6, v92, v93 offset1:1
	v_add_u32_e32 v6, 0x30c0, v8
	ds_write2_b32 v6, v94, v95 offset1:1
	v_add_u32_e32 v6, 0x30c8, v8
	ds_write2_b32 v6, v96, v97 offset1:1
	v_add_u32_e32 v6, 0x34d0, v8
	ds_write2_b32 v6, v98, v99 offset1:1
	v_add_u32_e32 v6, 0x34d8, v8
	ds_write2_b32 v6, v100, v101 offset1:1
	v_add_u32_e32 v6, 0x38e0, v8
	ds_write2_b32 v6, v102, v103 offset1:1
	v_add_u32_e32 v6, 0x38e8, v8
	ds_write2_b32 v6, v104, v105 offset1:1
	v_add_u32_e32 v6, 0x3cf0, v8
	s_waitcnt vmcnt(0)
	ds_write2_b32 v6, v106, v107 offset1:1
	v_add_u32_e32 v6, 0x3cf8, v8
	ds_write2_b32 v6, v108, v109 offset1:1
	s_waitcnt lgkmcnt(0)
	ds_read2_b32 v[50:51], v10 offset1:8
	ds_read2_b32 v[52:53], v10 offset0:65 offset1:73
	ds_read2_b32 v[54:55], v10 offset0:130 offset1:138
	ds_read2_b32 v[56:57], v10 offset0:195 offset1:203
	ds_read2_b32 v[58:59], v45 offset0:4 offset1:12
	s_waitcnt lgkmcnt(4)
	v_bfe_u32 v6, v50, 16, 1
	v_add3_u32 v6, v50, v6, s41
	s_waitcnt lgkmcnt(3)
	v_bfe_u32 v7, v52, 16, 1
	v_lshrrev_b32_e32 v6, 16, v6
	v_add3_u32 v7, v52, v7, s41
	ds_read2_b32 v[60:61], v45 offset0:69 offset1:77
	v_and_or_b32 v46, v7, s42, v6
	s_waitcnt lgkmcnt(3)
	v_bfe_u32 v6, v54, 16, 1
	v_add3_u32 v6, v54, v6, s41
	s_waitcnt lgkmcnt(2)
	v_bfe_u32 v7, v56, 16, 1
	ds_read2_b32 v[62:63], v45 offset0:134 offset1:142
	v_lshrrev_b32_e32 v6, 16, v6
	v_add3_u32 v7, v56, v7, s41
	ds_read2_b32 v[64:65], v45 offset0:199 offset1:207
	v_and_or_b32 v47, v7, s42, v6
	s_waitcnt lgkmcnt(3)
	v_bfe_u32 v6, v58, 16, 1
	v_add3_u32 v6, v58, v6, s41
	s_waitcnt lgkmcnt(2)
	v_bfe_u32 v7, v60, 16, 1
	v_lshrrev_b32_e32 v6, 16, v6
	v_add3_u32 v7, v60, v7, s41
	v_and_or_b32 v48, v7, s42, v6
	s_waitcnt lgkmcnt(1)
	v_bfe_u32 v6, v62, 16, 1
	v_add_u32_e32 v70, s20, v9
	v_add3_u32 v6, v62, v6, s41
	s_waitcnt lgkmcnt(0)
	v_bfe_u32 v7, v64, 16, 1
	v_add_u32_e32 v71, s6, v70
	v_lshrrev_b32_e32 v6, 16, v6
	v_add3_u32 v7, v64, v7, s41
	v_cmp_lt_i32_e32 vcc, s24, v71
	v_and_or_b32 v49, v7, s42, v6
	s_mul_i32 s6, s10, 0x2c00
	v_cndmask_b32_e32 v6, 0, v43, vcc
	v_subrev_u32_e32 v6, s6, v6
	v_add_u32_e32 v6, v70, v6
	v_cndmask_b32_e32 v7, 0, v44, vcc
	v_ashrrev_i32_e32 v6, 7, v6
	v_and_or_b32 v50, v71, s44, v7
	v_ashrrev_i32_e32 v7, 31, v6
	v_lshlrev_b64 v[6:7], 20, v[6:7]
	v_lshl_add_u64 v[6:7], s[8:9], 0, v[6:7]
	v_lshlrev_b32_e32 v66, 7, v50
	v_mov_b32_e32 v67, v3
	v_lshl_add_u64 v[66:67], v[6:7], 0, v[66:67]
	v_lshlrev_b32_e32 v6, 1, v4
	v_mov_b32_e32 v7, v3
	v_lshl_add_u64 v[66:67], v[66:67], 0, v[6:7]
	global_store_dwordx4 v[66:67], v[46:49], off
	v_bfe_u32 v50, v65, 16, 1
	v_add3_u32 v50, v65, v50, s41
	v_bfe_u32 v46, v51, 16, 1
	v_add3_u32 v46, v51, v46, s41
	v_bfe_u32 v47, v53, 16, 1
	v_lshrrev_b32_e32 v46, 16, v46
	v_add3_u32 v47, v53, v47, s41
	v_and_or_b32 v46, v47, s42, v46
	v_bfe_u32 v47, v55, 16, 1
	v_add3_u32 v47, v55, v47, s41
	v_bfe_u32 v48, v57, 16, 1
	v_lshrrev_b32_e32 v47, 16, v47
	v_add3_u32 v48, v57, v48, s41
	v_and_or_b32 v47, v48, s42, v47
	v_bfe_u32 v48, v59, 16, 1
	v_add3_u32 v48, v59, v48, s41
	v_bfe_u32 v49, v61, 16, 1
	v_lshrrev_b32_e32 v48, 16, v48
	v_add3_u32 v49, v61, v49, s41
	v_and_or_b32 v48, v49, s42, v48
	v_bfe_u32 v49, v63, 16, 1
	v_add3_u32 v49, v63, v49, s41
	v_lshrrev_b32_e32 v49, 16, v49
	v_and_or_b32 v49, v50, s42, v49
	v_add_u32_e32 v50, 8, v71
	v_cmp_lt_i32_e32 vcc, s24, v50
	v_mov_b32_e32 v53, v3
	ds_read2_b32 v[54:55], v10 offset0:16 offset1:24
	v_cndmask_b32_e32 v51, 0, v43, vcc
	v_subrev_u32_e32 v51, s6, v51
	v_add3_u32 v51, v70, v51, 8
	v_cndmask_b32_e32 v52, 0, v44, vcc
	v_and_or_b32 v52, v50, s44, v52
	v_ashrrev_i32_e32 v50, 7, v51
	v_ashrrev_i32_e32 v51, 31, v50
	v_lshlrev_b64 v[50:51], 20, v[50:51]
	v_lshl_add_u64 v[50:51], s[8:9], 0, v[50:51]
	v_lshlrev_b32_e32 v52, 7, v52
	v_lshl_add_u64 v[50:51], v[50:51], 0, v[52:53]
	v_lshl_add_u64 v[50:51], v[50:51], 0, v[6:7]
	global_store_dwordx4 v[50:51], v[46:49], off
	ds_read2_b32 v[50:51], v10 offset0:81 offset1:89
	ds_read2_b32 v[52:53], v10 offset0:146 offset1:154
	ds_read2_b32 v[56:57], v10 offset0:211 offset1:219
	s_waitcnt lgkmcnt(3)
	v_bfe_u32 v46, v54, 16, 1
	v_add3_u32 v46, v54, v46, s41
	s_waitcnt lgkmcnt(2)
	v_bfe_u32 v47, v50, 16, 1
	ds_read2_b32 v[58:59], v45 offset0:20 offset1:28
	v_lshrrev_b32_e32 v46, 16, v46
	v_add3_u32 v47, v50, v47, s41
	ds_read2_b32 v[60:61], v45 offset0:85 offset1:93
	v_and_or_b32 v46, v47, s42, v46
	s_waitcnt lgkmcnt(3)
	v_bfe_u32 v47, v52, 16, 1
	v_add3_u32 v47, v52, v47, s41
	s_waitcnt lgkmcnt(2)
	v_bfe_u32 v48, v56, 16, 1
	ds_read2_b32 v[62:63], v45 offset0:150 offset1:158
	v_lshrrev_b32_e32 v47, 16, v47
	v_add3_u32 v48, v56, v48, s41
	ds_read2_b32 v[64:65], v45 offset0:215 offset1:223
	v_and_or_b32 v47, v48, s42, v47
	s_waitcnt lgkmcnt(3)
	v_bfe_u32 v48, v58, 16, 1
	v_add3_u32 v48, v58, v48, s41
	s_waitcnt lgkmcnt(2)
	v_bfe_u32 v49, v60, 16, 1
	v_lshrrev_b32_e32 v48, 16, v48
	v_add3_u32 v49, v60, v49, s41
	v_and_or_b32 v48, v49, s42, v48
	s_waitcnt lgkmcnt(1)
	v_bfe_u32 v49, v62, 16, 1
	v_add3_u32 v49, v62, v49, s41
	s_waitcnt lgkmcnt(0)
	v_bfe_u32 v50, v64, 16, 1
	v_lshrrev_b32_e32 v49, 16, v49
	v_add3_u32 v50, v64, v50, s41
	v_and_or_b32 v49, v50, s42, v49
	v_add_u32_e32 v50, 16, v71
	v_cmp_lt_i32_e32 vcc, s24, v50
	v_mov_b32_e32 v69, v3
	s_nop 0
	v_cndmask_b32_e32 v52, 0, v43, vcc
	v_subrev_u32_e32 v52, s6, v52
	v_add3_u32 v52, v70, v52, 16
	v_ashrrev_i32_e32 v66, 7, v52
	v_cndmask_b32_e32 v54, 0, v44, vcc
	v_ashrrev_i32_e32 v67, 31, v66
	v_and_or_b32 v50, v50, s44, v54
	v_lshlrev_b64 v[66:67], 20, v[66:67]
	v_lshl_add_u64 v[66:67], s[8:9], 0, v[66:67]
	v_lshlrev_b32_e32 v68, 7, v50
	v_lshl_add_u64 v[66:67], v[66:67], 0, v[68:69]
	v_lshl_add_u64 v[66:67], v[66:67], 0, v[6:7]
	global_store_dwordx4 v[66:67], v[46:49], off
	v_bfe_u32 v50, v65, 16, 1
	v_add3_u32 v50, v65, v50, s41
	v_bfe_u32 v46, v55, 16, 1
	v_add3_u32 v46, v55, v46, s41
	v_bfe_u32 v47, v51, 16, 1
	v_lshrrev_b32_e32 v46, 16, v46
	v_add3_u32 v47, v51, v47, s41
	v_and_or_b32 v46, v47, s42, v46
	v_bfe_u32 v47, v53, 16, 1
	v_add3_u32 v47, v53, v47, s41
	v_bfe_u32 v48, v57, 16, 1
	v_lshrrev_b32_e32 v47, 16, v47
	v_add3_u32 v48, v57, v48, s41
	v_and_or_b32 v47, v48, s42, v47
	v_bfe_u32 v48, v59, 16, 1
	v_add3_u32 v48, v59, v48, s41
	v_bfe_u32 v49, v61, 16, 1
	v_lshrrev_b32_e32 v48, 16, v48
	v_add3_u32 v49, v61, v49, s41
	v_and_or_b32 v48, v49, s42, v48
	v_bfe_u32 v49, v63, 16, 1
	v_add3_u32 v49, v63, v49, s41
	v_lshrrev_b32_e32 v49, 16, v49
	v_and_or_b32 v49, v50, s42, v49
	v_add_u32_e32 v50, 24, v71
	v_cmp_lt_i32_e32 vcc, s24, v50
	v_mov_b32_e32 v53, v3
	ds_read2_b32 v[54:55], v10 offset0:32 offset1:40
	v_cndmask_b32_e32 v51, 0, v43, vcc
	v_subrev_u32_e32 v51, s6, v51
	v_add3_u32 v51, v70, v51, 24
	v_cndmask_b32_e32 v52, 0, v44, vcc
	v_and_or_b32 v52, v50, s44, v52
	v_ashrrev_i32_e32 v50, 7, v51
	v_ashrrev_i32_e32 v51, 31, v50
	v_lshlrev_b64 v[50:51], 20, v[50:51]
	v_lshl_add_u64 v[50:51], s[8:9], 0, v[50:51]
	v_lshlrev_b32_e32 v52, 7, v52
	v_lshl_add_u64 v[50:51], v[50:51], 0, v[52:53]
	v_lshl_add_u64 v[50:51], v[50:51], 0, v[6:7]
	global_store_dwordx4 v[50:51], v[46:49], off
	ds_read2_b32 v[50:51], v10 offset0:97 offset1:105
	ds_read2_b32 v[52:53], v10 offset0:162 offset1:170
	ds_read2_b32 v[56:57], v10 offset0:227 offset1:235
	s_waitcnt lgkmcnt(3)
	v_bfe_u32 v46, v54, 16, 1
	v_add3_u32 v46, v54, v46, s41
	s_waitcnt lgkmcnt(2)
	v_bfe_u32 v47, v50, 16, 1
	ds_read2_b32 v[58:59], v45 offset0:36 offset1:44
	v_lshrrev_b32_e32 v46, 16, v46
	v_add3_u32 v47, v50, v47, s41
	ds_read2_b32 v[60:61], v45 offset0:101 offset1:109
	v_and_or_b32 v46, v47, s42, v46
	s_waitcnt lgkmcnt(3)
	v_bfe_u32 v47, v52, 16, 1
	v_add3_u32 v47, v52, v47, s41
	s_waitcnt lgkmcnt(2)
	v_bfe_u32 v48, v56, 16, 1
	ds_read2_b32 v[62:63], v45 offset0:166 offset1:174
	v_lshrrev_b32_e32 v47, 16, v47
	v_add3_u32 v48, v56, v48, s41
	ds_read2_b32 v[64:65], v45 offset0:231 offset1:239
	v_and_or_b32 v47, v48, s42, v47
	s_waitcnt lgkmcnt(3)
	v_bfe_u32 v48, v58, 16, 1
	v_add3_u32 v48, v58, v48, s41
	s_waitcnt lgkmcnt(2)
	v_bfe_u32 v49, v60, 16, 1
	v_lshrrev_b32_e32 v48, 16, v48
	v_add3_u32 v49, v60, v49, s41
	v_and_or_b32 v48, v49, s42, v48
	s_waitcnt lgkmcnt(1)
	v_bfe_u32 v49, v62, 16, 1
	v_add3_u32 v49, v62, v49, s41
	s_waitcnt lgkmcnt(0)
	v_bfe_u32 v50, v64, 16, 1
	v_lshrrev_b32_e32 v49, 16, v49
	v_add3_u32 v50, v64, v50, s41
	v_and_or_b32 v49, v50, s42, v49
	v_add_u32_e32 v50, 32, v71
	v_cmp_lt_i32_e32 vcc, s24, v50
	s_nop 1
	v_cndmask_b32_e32 v52, 0, v43, vcc
	v_subrev_u32_e32 v52, s6, v52
	v_add3_u32 v52, v70, v52, 32
	v_ashrrev_i32_e32 v66, 7, v52
	v_cndmask_b32_e32 v54, 0, v44, vcc
	v_ashrrev_i32_e32 v67, 31, v66
	v_and_or_b32 v50, v50, s44, v54
	v_lshlrev_b64 v[66:67], 20, v[66:67]
	v_lshl_add_u64 v[66:67], s[8:9], 0, v[66:67]
	v_lshlrev_b32_e32 v68, 7, v50
	v_lshl_add_u64 v[66:67], v[66:67], 0, v[68:69]
	v_lshl_add_u64 v[66:67], v[66:67], 0, v[6:7]
	global_store_dwordx4 v[66:67], v[46:49], off
	v_bfe_u32 v50, v65, 16, 1
	v_add3_u32 v50, v65, v50, s41
	v_bfe_u32 v46, v55, 16, 1
	v_add3_u32 v46, v55, v46, s41
	v_bfe_u32 v47, v51, 16, 1
	v_lshrrev_b32_e32 v46, 16, v46
	v_add3_u32 v47, v51, v47, s41
	v_and_or_b32 v46, v47, s42, v46
	v_bfe_u32 v47, v53, 16, 1
	v_add3_u32 v47, v53, v47, s41
	v_bfe_u32 v48, v57, 16, 1
	v_lshrrev_b32_e32 v47, 16, v47
	v_add3_u32 v48, v57, v48, s41
	v_and_or_b32 v47, v48, s42, v47
	v_bfe_u32 v48, v59, 16, 1
	v_add3_u32 v48, v59, v48, s41
	v_bfe_u32 v49, v61, 16, 1
	v_lshrrev_b32_e32 v48, 16, v48
	v_add3_u32 v49, v61, v49, s41
	v_and_or_b32 v48, v49, s42, v48
	v_bfe_u32 v49, v63, 16, 1
	v_add3_u32 v49, v63, v49, s41
	v_lshrrev_b32_e32 v49, 16, v49
	v_and_or_b32 v49, v50, s42, v49
	v_add_u32_e32 v50, 40, v71
	v_cmp_lt_i32_e32 vcc, s24, v50
	v_mov_b32_e32 v53, v3
	ds_read2_b32 v[54:55], v10 offset0:48 offset1:56
	v_cndmask_b32_e32 v51, 0, v43, vcc
	v_subrev_u32_e32 v51, s6, v51
	v_add3_u32 v51, v70, v51, 40
	v_cndmask_b32_e32 v52, 0, v44, vcc
	v_and_or_b32 v52, v50, s44, v52
	v_ashrrev_i32_e32 v50, 7, v51
	v_ashrrev_i32_e32 v51, 31, v50
	v_lshlrev_b64 v[50:51], 20, v[50:51]
	v_lshl_add_u64 v[50:51], s[8:9], 0, v[50:51]
	v_lshlrev_b32_e32 v52, 7, v52
	v_lshl_add_u64 v[50:51], v[50:51], 0, v[52:53]
	v_lshl_add_u64 v[50:51], v[50:51], 0, v[6:7]
	global_store_dwordx4 v[50:51], v[46:49], off
	ds_read2_b32 v[50:51], v10 offset0:113 offset1:121
	ds_read2_b32 v[52:53], v10 offset0:178 offset1:186
	ds_read2_b32 v[56:57], v10 offset0:243 offset1:251
	s_waitcnt lgkmcnt(3)
	v_bfe_u32 v46, v54, 16, 1
	v_add3_u32 v46, v54, v46, s41
	s_waitcnt lgkmcnt(2)
	v_bfe_u32 v47, v50, 16, 1
	ds_read2_b32 v[58:59], v45 offset0:52 offset1:60
	v_lshrrev_b32_e32 v46, 16, v46
	v_add3_u32 v47, v50, v47, s41
	ds_read2_b32 v[60:61], v45 offset0:117 offset1:125
	v_and_or_b32 v46, v47, s42, v46
	s_waitcnt lgkmcnt(3)
	v_bfe_u32 v47, v52, 16, 1
	ds_read2_b32 v[62:63], v45 offset0:182 offset1:190
	v_add3_u32 v47, v52, v47, s41
	s_waitcnt lgkmcnt(3)
	v_bfe_u32 v48, v56, 16, 1
	ds_read2_b32 v[64:65], v45 offset0:247 offset1:255
	v_lshrrev_b32_e32 v47, 16, v47
	v_add3_u32 v48, v56, v48, s41
	v_and_or_b32 v47, v48, s42, v47
	s_waitcnt lgkmcnt(3)
	v_bfe_u32 v48, v58, 16, 1
	v_add3_u32 v48, v58, v48, s41
	s_waitcnt lgkmcnt(2)
	v_bfe_u32 v49, v60, 16, 1
	v_lshrrev_b32_e32 v48, 16, v48
	v_add3_u32 v49, v60, v49, s41
	s_waitcnt lgkmcnt(1)
	v_bfe_u32 v45, v62, 16, 1
	v_and_or_b32 v48, v49, s42, v48
	v_add3_u32 v45, v62, v45, s41
	s_waitcnt lgkmcnt(0)
	v_bfe_u32 v49, v64, 16, 1
	v_lshrrev_b32_e32 v45, 16, v45
	v_add3_u32 v49, v64, v49, s41
	v_and_or_b32 v49, v49, s42, v45
	v_add_u32_e32 v45, 48, v71
	v_cmp_lt_i32_e32 vcc, s24, v45
	s_nop 1
	v_cndmask_b32_e32 v50, 0, v43, vcc
	v_subrev_u32_e32 v50, s6, v50
	v_add3_u32 v50, v70, v50, 48
	v_ashrrev_i32_e32 v66, 7, v50
	v_cndmask_b32_e32 v52, 0, v44, vcc
	v_ashrrev_i32_e32 v67, 31, v66
	v_and_or_b32 v45, v45, s44, v52
	v_lshlrev_b64 v[66:67], 20, v[66:67]
	v_lshl_add_u64 v[66:67], s[8:9], 0, v[66:67]
	v_lshlrev_b32_e32 v68, 7, v45
	v_lshl_add_u64 v[66:67], v[66:67], 0, v[68:69]
	v_lshl_add_u64 v[66:67], v[66:67], 0, v[6:7]
	v_bfe_u32 v45, v55, 16, 1
	global_store_dwordx4 v[66:67], v[46:49], off
	v_add3_u32 v45, v55, v45, s41
	v_lshrrev_b32_e32 v45, 16, v45
	v_bfe_u32 v46, v51, 16, 1
	v_add3_u32 v46, v51, v46, s41
	v_and_or_b32 v46, v46, s42, v45
	v_bfe_u32 v45, v53, 16, 1
	v_add3_u32 v45, v53, v45, s41
	v_bfe_u32 v47, v57, 16, 1
	v_lshrrev_b32_e32 v45, 16, v45
	v_add3_u32 v47, v57, v47, s41
	v_and_or_b32 v47, v47, s42, v45
	v_bfe_u32 v45, v59, 16, 1
	v_add3_u32 v45, v59, v45, s41
	v_bfe_u32 v48, v61, 16, 1
	v_lshrrev_b32_e32 v45, 16, v45
	v_add3_u32 v48, v61, v48, s41
	v_and_or_b32 v48, v48, s42, v45
	v_bfe_u32 v45, v63, 16, 1
	v_add3_u32 v45, v63, v45, s41
	v_bfe_u32 v49, v65, 16, 1
	v_lshrrev_b32_e32 v45, 16, v45
	v_add3_u32 v49, v65, v49, s41
	v_and_or_b32 v49, v49, s42, v45
	v_add_u32_e32 v45, 56, v71
	v_cmp_lt_i32_e32 vcc, s24, v45
	v_mov_b32_e32 v53, v3
	s_nop 0
	v_cndmask_b32_e32 v50, 0, v43, vcc
	v_subrev_u32_e32 v50, s6, v50
	v_add3_u32 v50, v70, v50, 56
	v_cndmask_b32_e32 v51, 0, v44, vcc
	v_ashrrev_i32_e32 v50, 7, v50
	v_and_or_b32 v45, v45, s44, v51
	v_ashrrev_i32_e32 v51, 31, v50
	v_lshlrev_b64 v[50:51], 20, v[50:51]
	v_lshl_add_u64 v[50:51], s[8:9], 0, v[50:51]
	v_lshlrev_b32_e32 v52, 7, v45
	v_lshl_add_u64 v[50:51], v[50:51], 0, v[52:53]
	v_lshl_add_u64 v[6:7], v[50:51], 0, v[6:7]
	global_store_dwordx4 v[6:7], v[46:49], off
	s_waitcnt lgkmcnt(0)
	s_branch .LBB0_31

.LBB0_945:
	s_cmpk_gt_i32 s22, 0x15ff
	s_mov_b64 s[0:1], -1
	s_cbranch_scc0 .LBB0_963
	s_cmpk_gt_u32 s22, 0x20ff
	s_cbranch_scc0 .LBB0_960
	s_cmpk_gt_u32 s22, 0x2cff
	s_cbranch_scc0 .LBB0_957
	s_cmpk_gt_u32 s22, 0x30ff
	s_cbranch_scc0 .LBB0_954
	s_cmpk_gt_u32 s22, 0x46ff
	s_cbranch_scc0 .LBB0_951
	s_load_dwordx2 s[2:3], s[6:7], 0x98
	s_add_i32 s0, s18, 0xffee4000
	s_and_b32 s23, s20, 0x1fc0
	s_and_b32 s0, s0, 0x7c0
	s_add_i32 s1, s22, 0xffffb900
	v_add_u32_e32 v26, s23, v5
	s_lshl_b32 s23, s0, 2
	s_waitcnt lgkmcnt(0)
	s_add_u32 s2, s2, s23
	s_addc_u32 s3, s3, 0
	v_lshlrev_b32_e32 v2, 2, v4
	v_ashrrev_i32_e32 v27, 31, v26
	v_lshl_add_u64 v[28:29], s[2:3], 0, v[2:3]
	v_lshlrev_b64 v[26:27], 13, v[26:27]
	v_lshl_add_u64 v[86:87], v[28:29], 0, v[26:27]
	v_add_co_u32_e32 v26, vcc, s42, v86
	v_add_u32_e32 v2, 0x410, v7
	s_nop 0
	v_addc_co_u32_e32 v27, vcc, 0, v87, vcc
	v_add_co_u32_e32 v30, vcc, s43, v86
	s_lshr_b32 s72, s1, 5
	s_nop 0
	v_addc_co_u32_e32 v31, vcc, 0, v87, vcc
	v_add_co_u32_e32 v34, vcc, s44, v86
	global_load_dwordx4 v[26:29], v[26:27], off nt
	s_nop 0
	global_load_dwordx4 v[30:33], v[30:31], off nt
	v_addc_co_u32_e32 v35, vcc, 0, v87, vcc
	v_add_co_u32_e32 v38, vcc, s46, v86
	s_nop 1
	v_addc_co_u32_e32 v39, vcc, 0, v87, vcc
	global_load_dwordx4 v[34:37], v[34:35], off nt
	s_nop 0
	global_load_dwordx4 v[38:41], v[38:39], off nt
	v_add_co_u32_e32 v42, vcc, s49, v86
	s_nop 1
	v_addc_co_u32_e32 v43, vcc, 0, v87, vcc
	v_add_co_u32_e32 v46, vcc, s50, v86
	s_nop 1
	v_addc_co_u32_e32 v47, vcc, 0, v87, vcc
	global_load_dwordx4 v[42:45], v[42:43], off nt
	s_nop 0
	global_load_dwordx4 v[46:49], v[46:47], off nt
	v_add_co_u32_e32 v50, vcc, s53, v86
	s_nop 1
	v_addc_co_u32_e32 v51, vcc, 0, v87, vcc
	v_add_co_u32_e32 v54, vcc, s55, v86
	s_nop 1
	v_addc_co_u32_e32 v55, vcc, 0, v87, vcc
	global_load_dwordx4 v[50:53], v[50:51], off nt
	s_nop 0
	global_load_dwordx4 v[54:57], v[54:55], off nt
	v_add_co_u32_e32 v58, vcc, s56, v86
	s_nop 1
	v_addc_co_u32_e32 v59, vcc, 0, v87, vcc
	v_add_co_u32_e32 v62, vcc, s57, v86
	s_nop 1
	v_addc_co_u32_e32 v63, vcc, 0, v87, vcc
	global_load_dwordx4 v[58:61], v[58:59], off nt
	s_nop 0
	global_load_dwordx4 v[62:65], v[62:63], off nt
	v_add_co_u32_e32 v66, vcc, s58, v86
	s_nop 1
	v_addc_co_u32_e32 v67, vcc, 0, v87, vcc
	v_add_co_u32_e32 v70, vcc, s61, v86
	s_nop 1
	v_addc_co_u32_e32 v71, vcc, 0, v87, vcc
	global_load_dwordx4 v[66:69], v[66:67], off nt
	s_nop 0
	global_load_dwordx4 v[70:73], v[70:71], off nt
	v_add_co_u32_e32 v74, vcc, s62, v86
	s_nop 1
	v_addc_co_u32_e32 v75, vcc, 0, v87, vcc
	global_load_dwordx4 v[74:77], v[74:75], off nt
	v_add_co_u32_e32 v78, vcc, s63, v86
	s_nop 1
	v_addc_co_u32_e32 v79, vcc, 0, v87, vcc
	global_load_dwordx4 v[78:81], v[78:79], off nt
	v_add_co_u32_e32 v82, vcc, s64, v86
	s_nop 1
	v_addc_co_u32_e32 v83, vcc, 0, v87, vcc
	global_load_dwordx4 v[82:85], v[82:83], off nt
	v_add_co_u32_e32 v86, vcc, s65, v86
	s_nop 1
	v_addc_co_u32_e32 v87, vcc, 0, v87, vcc
	global_load_dwordx4 v[86:89], v[86:87], off nt
	s_waitcnt vmcnt(0)
	ds_write2_b32 v7, v26, v27 offset1:1
	ds_write2_b32 v7, v28, v29 offset0:2 offset1:3
	ds_write2_b32 v2, v30, v31 offset1:1
	v_add_u32_e32 v2, 0x418, v7
	ds_write2_b32 v2, v32, v33 offset1:1
	v_add_u32_e32 v2, 0x820, v7
	ds_write2_b32 v2, v34, v35 offset1:1
	v_add_u32_e32 v2, 0x828, v7
	ds_write2_b32 v2, v36, v37 offset1:1
	v_add_u32_e32 v2, 0xc30, v7
	ds_write2_b32 v2, v38, v39 offset1:1
	v_add_u32_e32 v2, 0xc38, v7
	ds_write2_b32 v2, v40, v41 offset1:1
	v_add_u32_e32 v2, 0x1040, v7
	ds_write2_b32 v2, v42, v43 offset1:1
	v_add_u32_e32 v2, 0x1048, v7
	ds_write2_b32 v2, v44, v45 offset1:1
	v_add_u32_e32 v2, 0x1450, v7
	ds_write2_b32 v2, v46, v47 offset1:1
	v_add_u32_e32 v2, 0x1458, v7
	ds_write2_b32 v2, v48, v49 offset1:1
	v_add_u32_e32 v2, 0x1860, v7
	v_mov_b32_e32 v49, v3
	ds_write2_b32 v2, v50, v51 offset1:1
	v_add_u32_e32 v2, 0x1868, v7
	ds_write2_b32 v2, v52, v53 offset1:1
	v_add_u32_e32 v2, 0x1c70, v7
	ds_write2_b32 v2, v54, v55 offset1:1
	v_add_u32_e32 v2, 0x1c78, v7
	ds_write2_b32 v2, v56, v57 offset1:1
	v_add_u32_e32 v2, 0x2080, v7
	ds_write2_b32 v2, v58, v59 offset1:1
	v_add_u32_e32 v2, 0x2088, v7
	ds_write2_b32 v2, v60, v61 offset1:1
	v_add_u32_e32 v2, 0x2490, v7
	ds_write2_b32 v2, v62, v63 offset1:1
	v_add_u32_e32 v2, 0x2498, v7
	ds_write2_b32 v2, v64, v65 offset1:1
	v_add_u32_e32 v2, 0x28a0, v7
	ds_write2_b32 v2, v66, v67 offset1:1
	v_add_u32_e32 v2, 0x28a8, v7
	ds_write2_b32 v2, v68, v69 offset1:1
	v_add_u32_e32 v2, 0x2cb0, v7
	ds_write2_b32 v2, v70, v71 offset1:1
	v_add_u32_e32 v2, 0x2cb8, v7
	ds_write2_b32 v2, v72, v73 offset1:1
	v_add_u32_e32 v2, 0x30c0, v7
	ds_write2_b32 v2, v74, v75 offset1:1
	v_add_u32_e32 v2, 0x30c8, v7
	ds_write2_b32 v2, v76, v77 offset1:1
	v_add_u32_e32 v2, 0x34d0, v7
	ds_write2_b32 v2, v78, v79 offset1:1
	v_add_u32_e32 v2, 0x34d8, v7
	ds_write2_b32 v2, v80, v81 offset1:1
	v_add_u32_e32 v2, 0x38e0, v7
	ds_write2_b32 v2, v82, v83 offset1:1
	v_add_u32_e32 v2, 0x38e8, v7
	ds_write2_b32 v2, v84, v85 offset1:1
	v_add_u32_e32 v2, 0x3cf0, v7
	ds_write2_b32 v2, v86, v87 offset1:1
	v_add_u32_e32 v2, 0x3cf8, v7
	ds_write2_b32 v2, v88, v89 offset1:1
	s_waitcnt lgkmcnt(0)
	ds_read2_b32 v[30:31], v9 offset1:8
	ds_read2_b32 v[32:33], v9 offset0:65 offset1:73
	ds_read2_b32 v[34:35], v9 offset0:130 offset1:138
	ds_read2_b32 v[36:37], v9 offset0:195 offset1:203
	s_waitcnt lgkmcnt(3)
	v_bfe_u32 v2, v30, 16, 1
	v_add3_u32 v2, v30, v2, s81
	s_waitcnt lgkmcnt(2)
	v_bfe_u32 v25, v32, 16, 1
	v_lshrrev_b32_e32 v2, 16, v2
	v_add3_u32 v25, v32, v25, s81
	v_and_or_b32 v26, v25, s39, v2
	v_add_u32_e32 v25, 0x400, v9
	ds_read2_b32 v[38:39], v25 offset0:4 offset1:12
	ds_read2_b32 v[40:41], v25 offset0:69 offset1:77
	s_waitcnt lgkmcnt(3)
	v_bfe_u32 v2, v34, 16, 1
	v_add3_u32 v2, v34, v2, s81
	s_waitcnt lgkmcnt(2)
	v_bfe_u32 v27, v36, 16, 1
	ds_read2_b32 v[42:43], v25 offset0:134 offset1:142
	v_lshrrev_b32_e32 v2, 16, v2
	v_add3_u32 v27, v36, v27, s81
	ds_read2_b32 v[44:45], v25 offset0:199 offset1:207
	v_and_or_b32 v27, v27, s39, v2
	s_waitcnt lgkmcnt(3)
	v_bfe_u32 v2, v38, 16, 1
	v_add3_u32 v2, v38, v2, s81
	s_waitcnt lgkmcnt(2)
	v_bfe_u32 v28, v40, 16, 1
	v_lshrrev_b32_e32 v2, 16, v2
	v_add3_u32 v28, v40, v28, s81
	v_and_or_b32 v28, v28, s39, v2
	s_waitcnt lgkmcnt(1)
	v_bfe_u32 v2, v42, 16, 1
	v_add3_u32 v2, v42, v2, s81
	s_waitcnt lgkmcnt(0)
	v_bfe_u32 v29, v44, 16, 1
	v_lshrrev_b32_e32 v2, 16, v2
	v_add3_u32 v29, v44, v29, s81
	v_and_or_b32 v29, v29, s39, v2
	v_add_u32_e32 v2, s0, v8
	v_lshrrev_b32_e32 v30, 8, v2
	v_mul_i32_i24_e32 v46, 0x58, v30
	v_ashrrev_i32_e32 v47, 31, v46
	v_lshl_add_u64 v[46:47], v[46:47], 0, s[72:73]
	v_lshlrev_b64 v[46:47], 15, v[46:47]
	v_lshlrev_b32_e32 v2, 7, v2
	v_lshl_add_u64 v[46:47], s[8:9], 0, v[46:47]
	v_and_b32_e32 v2, 0x7f80, v2
	v_lshl_add_u64 v[46:47], v[46:47], 0, v[2:3]
	v_lshlrev_b32_e32 v2, 1, v6
	v_lshl_add_u64 v[46:47], v[46:47], 0, v[2:3]
	global_store_dwordx4 v[46:47], v[26:29], off
	v_bfe_u32 v30, v45, 16, 1
	v_add3_u32 v30, v45, v30, s81
	v_bfe_u32 v26, v31, 16, 1
	v_add3_u32 v26, v31, v26, s81
	v_bfe_u32 v27, v33, 16, 1
	v_lshrrev_b32_e32 v26, 16, v26
	v_add3_u32 v27, v33, v27, s81
	v_and_or_b32 v26, v27, s39, v26
	v_bfe_u32 v27, v35, 16, 1
	v_add3_u32 v27, v35, v27, s81
	v_bfe_u32 v28, v37, 16, 1
	v_lshrrev_b32_e32 v27, 16, v27
	v_add3_u32 v28, v37, v28, s81
	v_and_or_b32 v27, v28, s39, v27
	v_bfe_u32 v28, v39, 16, 1
	v_add3_u32 v28, v39, v28, s81
	v_bfe_u32 v29, v41, 16, 1
	v_lshrrev_b32_e32 v28, 16, v28
	v_add3_u32 v29, v41, v29, s81
	v_and_or_b32 v28, v29, s39, v28
	v_bfe_u32 v29, v43, 16, 1
	v_add3_u32 v29, v43, v29, s81
	v_lshrrev_b32_e32 v29, 16, v29
	v_add_u32_e32 v32, s0, v10
	v_and_or_b32 v29, v30, s39, v29
	v_lshrrev_b32_e32 v30, 8, v32
	v_mul_i32_i24_e32 v30, 0x58, v30
	v_ashrrev_i32_e32 v31, 31, v30
	v_lshl_add_u64 v[30:31], v[30:31], 0, s[72:73]
	v_lshlrev_b64 v[30:31], 15, v[30:31]
	v_lshlrev_b32_e32 v32, 7, v32
	v_lshl_add_u64 v[30:31], s[8:9], 0, v[30:31]
	v_and_b32_e32 v32, 0x7f80, v32
	v_mov_b32_e32 v33, v3
	v_lshl_add_u64 v[30:31], v[30:31], 0, v[32:33]
	ds_read2_b32 v[34:35], v9 offset0:16 offset1:24
	v_lshl_add_u64 v[30:31], v[30:31], 0, v[2:3]
	global_store_dwordx4 v[30:31], v[26:29], off
	ds_read2_b32 v[30:31], v9 offset0:81 offset1:89
	ds_read2_b32 v[32:33], v9 offset0:146 offset1:154
	ds_read2_b32 v[36:37], v9 offset0:211 offset1:219
	s_waitcnt lgkmcnt(3)
	v_bfe_u32 v26, v34, 16, 1
	v_add3_u32 v26, v34, v26, s81
	s_waitcnt lgkmcnt(2)
	v_bfe_u32 v27, v30, 16, 1
	ds_read2_b32 v[38:39], v25 offset0:20 offset1:28
	v_lshrrev_b32_e32 v26, 16, v26
	v_add3_u32 v27, v30, v27, s81
	ds_read2_b32 v[40:41], v25 offset0:85 offset1:93
	v_and_or_b32 v26, v27, s39, v26
	s_waitcnt lgkmcnt(3)
	v_bfe_u32 v27, v32, 16, 1
	v_add3_u32 v27, v32, v27, s81
	s_waitcnt lgkmcnt(2)
	v_bfe_u32 v28, v36, 16, 1
	ds_read2_b32 v[42:43], v25 offset0:150 offset1:158
	v_lshrrev_b32_e32 v27, 16, v27
	v_add3_u32 v28, v36, v28, s81
	ds_read2_b32 v[44:45], v25 offset0:215 offset1:223
	v_and_or_b32 v27, v28, s39, v27
	s_waitcnt lgkmcnt(3)
	v_bfe_u32 v28, v38, 16, 1
	v_add3_u32 v28, v38, v28, s81
	s_waitcnt lgkmcnt(2)
	v_bfe_u32 v29, v40, 16, 1
	v_lshrrev_b32_e32 v28, 16, v28
	v_add3_u32 v29, v40, v29, s81
	v_and_or_b32 v28, v29, s39, v28
	s_waitcnt lgkmcnt(1)
	v_bfe_u32 v29, v42, 16, 1
	v_add3_u32 v29, v42, v29, s81
	s_waitcnt lgkmcnt(0)
	v_bfe_u32 v30, v44, 16, 1
	v_lshrrev_b32_e32 v29, 16, v29
	v_add3_u32 v30, v44, v30, s81
	v_and_or_b32 v29, v30, s39, v29
	v_add_u32_e32 v30, s0, v11
	v_lshrrev_b32_e32 v32, 8, v30
	v_mul_i32_i24_e32 v46, 0x58, v32
	v_ashrrev_i32_e32 v47, 31, v46
	v_lshl_add_u64 v[46:47], v[46:47], 0, s[72:73]
	v_lshlrev_b64 v[46:47], 15, v[46:47]
	v_lshlrev_b32_e32 v30, 7, v30
	v_lshl_add_u64 v[46:47], s[8:9], 0, v[46:47]
	v_and_b32_e32 v48, 0x7f80, v30
	v_lshl_add_u64 v[46:47], v[46:47], 0, v[48:49]
	v_lshl_add_u64 v[46:47], v[46:47], 0, v[2:3]
	global_store_dwordx4 v[46:47], v[26:29], off
	v_bfe_u32 v30, v45, 16, 1
	v_add3_u32 v30, v45, v30, s81
	v_bfe_u32 v26, v35, 16, 1
	v_add3_u32 v26, v35, v26, s81
	v_bfe_u32 v27, v31, 16, 1
	v_lshrrev_b32_e32 v26, 16, v26
	v_add3_u32 v27, v31, v27, s81
	v_and_or_b32 v26, v27, s39, v26
	v_bfe_u32 v27, v33, 16, 1
	v_add3_u32 v27, v33, v27, s81
	v_bfe_u32 v28, v37, 16, 1
	v_lshrrev_b32_e32 v27, 16, v27
	v_add3_u32 v28, v37, v28, s81
	v_and_or_b32 v27, v28, s39, v27
	v_bfe_u32 v28, v39, 16, 1
	v_add3_u32 v28, v39, v28, s81
	v_bfe_u32 v29, v41, 16, 1
	v_lshrrev_b32_e32 v28, 16, v28
	v_add3_u32 v29, v41, v29, s81
	v_and_or_b32 v28, v29, s39, v28
	v_bfe_u32 v29, v43, 16, 1
	v_add3_u32 v29, v43, v29, s81
	v_lshrrev_b32_e32 v29, 16, v29
	v_add_u32_e32 v32, s0, v12
	v_and_or_b32 v29, v30, s39, v29
	v_lshrrev_b32_e32 v30, 8, v32
	v_mul_i32_i24_e32 v30, 0x58, v30
	v_ashrrev_i32_e32 v31, 31, v30
	v_lshl_add_u64 v[30:31], v[30:31], 0, s[72:73]
	v_lshlrev_b64 v[30:31], 15, v[30:31]
	v_lshlrev_b32_e32 v32, 7, v32
	v_lshl_add_u64 v[30:31], s[8:9], 0, v[30:31]
	v_and_b32_e32 v32, 0x7f80, v32
	v_mov_b32_e32 v33, v3
	v_lshl_add_u64 v[30:31], v[30:31], 0, v[32:33]
	ds_read2_b32 v[34:35], v9 offset0:32 offset1:40
	v_lshl_add_u64 v[30:31], v[30:31], 0, v[2:3]
	global_store_dwordx4 v[30:31], v[26:29], off
	ds_read2_b32 v[30:31], v9 offset0:97 offset1:105
	ds_read2_b32 v[32:33], v9 offset0:162 offset1:170
	ds_read2_b32 v[36:37], v9 offset0:227 offset1:235
	s_waitcnt lgkmcnt(3)
	v_bfe_u32 v26, v34, 16, 1
	v_add3_u32 v26, v34, v26, s81
	s_waitcnt lgkmcnt(2)
	v_bfe_u32 v27, v30, 16, 1
	ds_read2_b32 v[38:39], v25 offset0:36 offset1:44
	v_lshrrev_b32_e32 v26, 16, v26
	v_add3_u32 v27, v30, v27, s81
	ds_read2_b32 v[40:41], v25 offset0:101 offset1:109
	v_and_or_b32 v26, v27, s39, v26
	s_waitcnt lgkmcnt(3)
	v_bfe_u32 v27, v32, 16, 1
	v_add3_u32 v27, v32, v27, s81
	s_waitcnt lgkmcnt(2)
	v_bfe_u32 v28, v36, 16, 1
	ds_read2_b32 v[42:43], v25 offset0:166 offset1:174
	v_lshrrev_b32_e32 v27, 16, v27
	v_add3_u32 v28, v36, v28, s81
	ds_read2_b32 v[44:45], v25 offset0:231 offset1:239
	v_and_or_b32 v27, v28, s39, v27
	s_waitcnt lgkmcnt(3)
	v_bfe_u32 v28, v38, 16, 1
	v_add3_u32 v28, v38, v28, s81
	s_waitcnt lgkmcnt(2)
	v_bfe_u32 v29, v40, 16, 1
	v_lshrrev_b32_e32 v28, 16, v28
	v_add3_u32 v29, v40, v29, s81
	v_and_or_b32 v28, v29, s39, v28
	s_waitcnt lgkmcnt(1)
	v_bfe_u32 v29, v42, 16, 1
	v_add3_u32 v29, v42, v29, s81
	s_waitcnt lgkmcnt(0)
	v_bfe_u32 v30, v44, 16, 1
	v_lshrrev_b32_e32 v29, 16, v29
	v_add3_u32 v30, v44, v30, s81
	v_and_or_b32 v29, v30, s39, v29
	v_add_u32_e32 v30, s0, v13
	v_lshrrev_b32_e32 v32, 8, v30
	v_mul_i32_i24_e32 v46, 0x58, v32
	v_ashrrev_i32_e32 v47, 31, v46
	v_lshl_add_u64 v[46:47], v[46:47], 0, s[72:73]
	v_lshlrev_b64 v[46:47], 15, v[46:47]
	v_lshlrev_b32_e32 v30, 7, v30
	v_lshl_add_u64 v[46:47], s[8:9], 0, v[46:47]
	v_and_b32_e32 v48, 0x7f80, v30
	v_lshl_add_u64 v[46:47], v[46:47], 0, v[48:49]
	v_lshl_add_u64 v[46:47], v[46:47], 0, v[2:3]
	global_store_dwordx4 v[46:47], v[26:29], off
	v_bfe_u32 v30, v45, 16, 1
	v_add3_u32 v30, v45, v30, s81
	v_bfe_u32 v26, v35, 16, 1
	v_add3_u32 v26, v35, v26, s81
	v_bfe_u32 v27, v31, 16, 1
	v_lshrrev_b32_e32 v26, 16, v26
	v_add3_u32 v27, v31, v27, s81
	v_and_or_b32 v26, v27, s39, v26
	v_bfe_u32 v27, v33, 16, 1
	v_add3_u32 v27, v33, v27, s81
	v_bfe_u32 v28, v37, 16, 1
	v_lshrrev_b32_e32 v27, 16, v27
	v_add3_u32 v28, v37, v28, s81
	v_and_or_b32 v27, v28, s39, v27
	v_bfe_u32 v28, v39, 16, 1
	v_add3_u32 v28, v39, v28, s81
	v_bfe_u32 v29, v41, 16, 1
	v_lshrrev_b32_e32 v28, 16, v28
	v_add3_u32 v29, v41, v29, s81
	v_and_or_b32 v28, v29, s39, v28
	v_bfe_u32 v29, v43, 16, 1
	v_add3_u32 v29, v43, v29, s81
	v_lshrrev_b32_e32 v29, 16, v29
	v_add_u32_e32 v32, s0, v14
	v_and_or_b32 v29, v30, s39, v29
	v_lshrrev_b32_e32 v30, 8, v32
	v_mul_i32_i24_e32 v30, 0x58, v30
	v_ashrrev_i32_e32 v31, 31, v30
	v_lshl_add_u64 v[30:31], v[30:31], 0, s[72:73]
	v_lshlrev_b64 v[30:31], 15, v[30:31]
	v_lshlrev_b32_e32 v32, 7, v32
	v_lshl_add_u64 v[30:31], s[8:9], 0, v[30:31]
	v_and_b32_e32 v32, 0x7f80, v32
	v_mov_b32_e32 v33, v3
	v_lshl_add_u64 v[30:31], v[30:31], 0, v[32:33]
	ds_read2_b32 v[34:35], v9 offset0:48 offset1:56
	v_lshl_add_u64 v[30:31], v[30:31], 0, v[2:3]
	global_store_dwordx4 v[30:31], v[26:29], off
	ds_read2_b32 v[30:31], v9 offset0:113 offset1:121
	ds_read2_b32 v[32:33], v9 offset0:178 offset1:186
	ds_read2_b32 v[36:37], v9 offset0:243 offset1:251
	s_waitcnt lgkmcnt(3)
	v_bfe_u32 v26, v34, 16, 1
	v_add3_u32 v26, v34, v26, s81
	s_waitcnt lgkmcnt(2)
	v_bfe_u32 v27, v30, 16, 1
	ds_read2_b32 v[38:39], v25 offset0:52 offset1:60
	v_lshrrev_b32_e32 v26, 16, v26
	v_add3_u32 v27, v30, v27, s81
	ds_read2_b32 v[40:41], v25 offset0:117 offset1:125
	v_and_or_b32 v26, v27, s39, v26
	s_waitcnt lgkmcnt(3)
	v_bfe_u32 v27, v32, 16, 1
	ds_read2_b32 v[42:43], v25 offset0:182 offset1:190
	v_add3_u32 v27, v32, v27, s81
	s_waitcnt lgkmcnt(3)
	v_bfe_u32 v28, v36, 16, 1
	ds_read2_b32 v[44:45], v25 offset0:247 offset1:255
	v_lshrrev_b32_e32 v27, 16, v27
	v_add3_u32 v28, v36, v28, s81
	v_and_or_b32 v27, v28, s39, v27
	s_waitcnt lgkmcnt(3)
	v_bfe_u32 v28, v38, 16, 1
	v_add3_u32 v28, v38, v28, s81
	s_waitcnt lgkmcnt(2)
	v_bfe_u32 v29, v40, 16, 1
	v_lshrrev_b32_e32 v28, 16, v28
	v_add3_u32 v29, v40, v29, s81
	s_waitcnt lgkmcnt(1)
	v_bfe_u32 v25, v42, 16, 1
	v_and_or_b32 v28, v29, s39, v28
	v_add3_u32 v25, v42, v25, s81
	s_waitcnt lgkmcnt(0)
	v_bfe_u32 v29, v44, 16, 1
	v_lshrrev_b32_e32 v25, 16, v25
	v_add3_u32 v29, v44, v29, s81
	v_and_or_b32 v29, v29, s39, v25
	v_add_u32_e32 v25, s0, v15
	v_lshrrev_b32_e32 v30, 8, v25
	v_mul_i32_i24_e32 v46, 0x58, v30
	v_ashrrev_i32_e32 v47, 31, v46
	v_lshl_add_u64 v[46:47], v[46:47], 0, s[72:73]
	v_lshlrev_b64 v[46:47], 15, v[46:47]
	v_lshlrev_b32_e32 v25, 7, v25
	v_lshl_add_u64 v[46:47], s[8:9], 0, v[46:47]
	v_and_b32_e32 v48, 0x7f80, v25
	v_lshl_add_u64 v[46:47], v[46:47], 0, v[48:49]
	v_lshl_add_u64 v[46:47], v[46:47], 0, v[2:3]
	v_bfe_u32 v25, v35, 16, 1
	global_store_dwordx4 v[46:47], v[26:29], off
	v_add3_u32 v25, v35, v25, s81
	v_lshrrev_b32_e32 v25, 16, v25
	v_bfe_u32 v26, v31, 16, 1
	v_add3_u32 v26, v31, v26, s81
	v_and_or_b32 v26, v26, s39, v25
	v_bfe_u32 v25, v33, 16, 1
	v_add3_u32 v25, v33, v25, s81
	v_bfe_u32 v27, v37, 16, 1
	v_lshrrev_b32_e32 v25, 16, v25
	v_add3_u32 v27, v37, v27, s81
	v_and_or_b32 v27, v27, s39, v25
	v_bfe_u32 v25, v39, 16, 1
	v_add3_u32 v25, v39, v25, s81
	v_bfe_u32 v28, v41, 16, 1
	v_lshrrev_b32_e32 v25, 16, v25
	v_add3_u32 v28, v41, v28, s81
	v_and_or_b32 v28, v28, s39, v25
	v_bfe_u32 v25, v43, 16, 1
	v_add3_u32 v25, v43, v25, s81
	v_bfe_u32 v29, v45, 16, 1
	v_lshrrev_b32_e32 v25, 16, v25
	v_add3_u32 v29, v45, v29, s81
	v_and_or_b32 v29, v29, s39, v25
	v_add_u32_e32 v25, s0, v16
	v_lshrrev_b32_e32 v30, 8, v25
	v_mul_i32_i24_e32 v30, 0x58, v30
	v_ashrrev_i32_e32 v31, 31, v30
	v_lshl_add_u64 v[30:31], v[30:31], 0, s[72:73]
	v_lshlrev_b64 v[30:31], 15, v[30:31]
	v_lshlrev_b32_e32 v25, 7, v25
	v_lshl_add_u64 v[30:31], s[8:9], 0, v[30:31]
	v_and_b32_e32 v32, 0x7f80, v25
	v_mov_b32_e32 v33, v3
	v_lshl_add_u64 v[30:31], v[30:31], 0, v[32:33]
	v_lshl_add_u64 v[30:31], v[30:31], 0, v[2:3]
	global_store_dwordx4 v[30:31], v[26:29], off
	s_waitcnt lgkmcnt(0)
	s_mov_b64 s[0:1], 0
.LBB0_951:
	s_andn2_b64 vcc, exec, s[0:1]
	s_cbranch_vccnz .LBB0_953
	s_add_i32 s1, s22, 0xcf00
	s_and_b32 s0, s1, 0xffff
	s_mul_i32 s0, s0, 0xba2f
	s_lshr_b32 s0, s0, 23
	s_load_dwordx2 s[24:25], s[6:7], 0x90
	s_mul_i32 s2, s0, 0xb0
	s_sub_i32 s1, s1, s2
	s_lshl_b32 s1, s1, 6
	s_and_b32 s2, s1, 0xffc0
	s_lshl_b32 s1, s2, 2
	s_waitcnt lgkmcnt(0)
	s_add_u32 s24, s24, s1
	s_addc_u32 s25, s25, 0
	v_lshlrev_b32_e32 v2, 2, v4
	v_lshl_add_u32 v25, s0, 6, v5
	v_lshl_add_u64 v[26:27], s[24:25], 0, v[2:3]
	s_mov_b64 s[24:25], 0x5800000
	v_lshl_add_u64 v[86:87], v[26:27], 0, s[24:25]
	v_add_u32_e32 v2, 4, v25
	v_mad_i64_i32 v[26:27], s[24:25], v25, s59, v[86:87]
	v_mad_i64_i32 v[30:31], s[24:25], v2, s59, v[86:87]
	global_load_dwordx4 v[26:29], v[26:27], off nt
	v_add_u32_e32 v2, 8, v25
	global_load_dwordx4 v[30:33], v[30:31], off nt
	v_mad_i64_i32 v[34:35], s[24:25], v2, s59, v[86:87]
	global_load_dwordx4 v[34:37], v[34:35], off nt
	v_add_u32_e32 v2, 12, v25
	v_mad_i64_i32 v[38:39], s[24:25], v2, s59, v[86:87]
	global_load_dwordx4 v[38:41], v[38:39], off nt
	v_add_u32_e32 v2, 16, v25
	v_mad_i64_i32 v[42:43], s[24:25], v2, s59, v[86:87]
	global_load_dwordx4 v[42:45], v[42:43], off nt
	v_add_u32_e32 v2, 20, v25
	v_mad_i64_i32 v[46:47], s[24:25], v2, s59, v[86:87]
	global_load_dwordx4 v[46:49], v[46:47], off nt
	v_add_u32_e32 v2, 24, v25
	v_mad_i64_i32 v[50:51], s[24:25], v2, s59, v[86:87]
	global_load_dwordx4 v[50:53], v[50:51], off nt
	v_add_u32_e32 v2, 28, v25
	v_mad_i64_i32 v[54:55], s[24:25], v2, s59, v[86:87]
	global_load_dwordx4 v[54:57], v[54:55], off nt
	v_add_u32_e32 v2, 32, v25
	v_mad_i64_i32 v[58:59], s[24:25], v2, s59, v[86:87]
	global_load_dwordx4 v[58:61], v[58:59], off nt
	v_add_u32_e32 v2, 36, v25
	v_mad_i64_i32 v[62:63], s[24:25], v2, s59, v[86:87]
	global_load_dwordx4 v[62:65], v[62:63], off nt
	v_add_u32_e32 v2, 40, v25
	v_mad_i64_i32 v[66:67], s[24:25], v2, s59, v[86:87]
	global_load_dwordx4 v[66:69], v[66:67], off nt
	v_add_u32_e32 v2, 44, v25
	v_mad_i64_i32 v[70:71], s[24:25], v2, s59, v[86:87]
	global_load_dwordx4 v[70:73], v[70:71], off nt
	v_add_u32_e32 v2, 48, v25
	v_mad_i64_i32 v[74:75], s[24:25], v2, s59, v[86:87]
	global_load_dwordx4 v[74:77], v[74:75], off nt
	v_add_u32_e32 v2, 52, v25
	v_mad_i64_i32 v[78:79], s[24:25], v2, s59, v[86:87]
	global_load_dwordx4 v[78:81], v[78:79], off nt
	v_add_u32_e32 v2, 56, v25
	v_mad_i64_i32 v[82:83], s[24:25], v2, s59, v[86:87]
	global_load_dwordx4 v[82:85], v[82:83], off nt
	v_add_u32_e32 v2, 60, v25
	v_mad_i64_i32 v[86:87], s[24:25], v2, s59, v[86:87]
	global_load_dwordx4 v[86:89], v[86:87], off nt
	v_add_u32_e32 v2, 0x410, v7
	s_lshl_b32 s0, s0, 15
	s_add_u32 s0, s14, s0
	s_addc_u32 s1, s15, 0
	s_waitcnt vmcnt(0)
	ds_write2_b32 v7, v26, v27 offset1:1
	ds_write2_b32 v7, v28, v29 offset0:2 offset1:3
	ds_write2_b32 v2, v30, v31 offset1:1
	v_add_u32_e32 v2, 0x418, v7
	ds_write2_b32 v2, v32, v33 offset1:1
	v_add_u32_e32 v2, 0x820, v7
	ds_write2_b32 v2, v34, v35 offset1:1
	v_add_u32_e32 v2, 0x828, v7
	ds_write2_b32 v2, v36, v37 offset1:1
	v_add_u32_e32 v2, 0xc30, v7
	ds_write2_b32 v2, v38, v39 offset1:1
	v_add_u32_e32 v2, 0xc38, v7
	ds_write2_b32 v2, v40, v41 offset1:1
	v_add_u32_e32 v2, 0x1040, v7
	ds_write2_b32 v2, v42, v43 offset1:1
	v_add_u32_e32 v2, 0x1048, v7
	ds_write2_b32 v2, v44, v45 offset1:1
	v_add_u32_e32 v2, 0x1450, v7
	ds_write2_b32 v2, v46, v47 offset1:1
	v_add_u32_e32 v2, 0x1458, v7
	ds_write2_b32 v2, v48, v49 offset1:1
	v_add_u32_e32 v2, 0x1860, v7
	ds_write2_b32 v2, v50, v51 offset1:1
	v_add_u32_e32 v2, 0x1868, v7
	ds_write2_b32 v2, v52, v53 offset1:1
	v_add_u32_e32 v2, 0x1c70, v7
	ds_write2_b32 v2, v54, v55 offset1:1
	v_add_u32_e32 v2, 0x1c78, v7
	ds_write2_b32 v2, v56, v57 offset1:1
	v_add_u32_e32 v2, 0x2080, v7
	ds_write2_b32 v2, v58, v59 offset1:1
	v_add_u32_e32 v2, 0x2088, v7
	ds_write2_b32 v2, v60, v61 offset1:1
	v_add_u32_e32 v2, 0x2490, v7
	ds_write2_b32 v2, v62, v63 offset1:1
	v_add_u32_e32 v2, 0x2498, v7
	ds_write2_b32 v2, v64, v65 offset1:1
	v_add_u32_e32 v2, 0x28a0, v7
	ds_write2_b32 v2, v66, v67 offset1:1
	v_add_u32_e32 v2, 0x28a8, v7
	ds_write2_b32 v2, v68, v69 offset1:1
	v_add_u32_e32 v2, 0x2cb0, v7
	ds_write2_b32 v2, v70, v71 offset1:1
	v_add_u32_e32 v2, 0x2cb8, v7
	ds_write2_b32 v2, v72, v73 offset1:1
	v_add_u32_e32 v2, 0x30c0, v7
	ds_write2_b32 v2, v74, v75 offset1:1
	v_add_u32_e32 v2, 0x30c8, v7
	ds_write2_b32 v2, v76, v77 offset1:1
	v_add_u32_e32 v2, 0x34d0, v7
	ds_write2_b32 v2, v78, v79 offset1:1
	v_add_u32_e32 v2, 0x34d8, v7
	ds_write2_b32 v2, v80, v81 offset1:1
	v_add_u32_e32 v2, 0x38e0, v7
	ds_write2_b32 v2, v82, v83 offset1:1
	v_add_u32_e32 v2, 0x38e8, v7
	ds_write2_b32 v2, v84, v85 offset1:1
	v_add_u32_e32 v2, 0x3cf0, v7
	ds_write2_b32 v2, v86, v87 offset1:1
	v_add_u32_e32 v2, 0x3cf8, v7
	ds_write2_b32 v2, v88, v89 offset1:1
	s_waitcnt lgkmcnt(0)
	ds_read2_b32 v[30:31], v9 offset0:65 offset1:73
	ds_read2_b32 v[32:33], v9 offset1:8
	ds_read2_b32 v[34:35], v9 offset0:130 offset1:138
	ds_read2_b32 v[36:37], v9 offset0:195 offset1:203
	v_mov_b32_e32 v49, v3
	s_waitcnt lgkmcnt(3)
	v_bfe_u32 v25, v30, 16, 1
	s_waitcnt lgkmcnt(2)
	v_bfe_u32 v2, v32, 16, 1
	v_add3_u32 v2, v32, v2, s81
	v_lshrrev_b32_e32 v2, 16, v2
	v_add3_u32 v25, v30, v25, s81
	v_and_or_b32 v26, v25, s39, v2
	s_waitcnt lgkmcnt(1)
	v_bfe_u32 v2, v34, 16, 1
	v_add3_u32 v2, v34, v2, s81
	s_waitcnt lgkmcnt(0)
	v_bfe_u32 v25, v36, 16, 1
	v_lshrrev_b32_e32 v2, 16, v2
	v_add3_u32 v25, v36, v25, s81
	v_and_or_b32 v27, v25, s39, v2
	v_add_u32_e32 v25, 0x400, v9
	ds_read2_b32 v[38:39], v25 offset0:4 offset1:12
	ds_read2_b32 v[40:41], v25 offset0:69 offset1:77
	ds_read2_b32 v[42:43], v25 offset0:134 offset1:142
	ds_read2_b32 v[44:45], v25 offset0:199 offset1:207
	s_waitcnt lgkmcnt(3)
	v_bfe_u32 v2, v38, 16, 1
	v_add3_u32 v2, v38, v2, s81
	s_waitcnt lgkmcnt(2)
	v_bfe_u32 v28, v40, 16, 1
	v_lshrrev_b32_e32 v2, 16, v2
	v_add3_u32 v28, v40, v28, s81
	v_and_or_b32 v28, v28, s39, v2
	s_waitcnt lgkmcnt(1)
	v_bfe_u32 v2, v42, 16, 1
	v_add3_u32 v2, v42, v2, s81
	s_waitcnt lgkmcnt(0)
	v_bfe_u32 v29, v44, 16, 1
	v_lshrrev_b32_e32 v2, 16, v2
	v_add3_u32 v29, v44, v29, s81
	v_and_or_b32 v29, v29, s39, v2
	v_add_u32_e32 v2, s2, v8
	v_cmp_lt_i32_e32 vcc, s41, v2
	s_nop 1
	v_cndmask_b32_e32 v30, 0, v247, vcc
	v_add_u32_e32 v30, v30, v2
	v_ashrrev_i32_e32 v46, 7, v30
	v_cndmask_b32_e32 v32, 0, v248, vcc
	v_ashrrev_i32_e32 v47, 31, v46
	v_and_or_b32 v2, v2, s40, v32
	v_lshlrev_b64 v[46:47], 20, v[46:47]
	v_lshl_add_u64 v[46:47], s[0:1], 0, v[46:47]
	v_lshlrev_b32_e32 v2, 7, v2
	v_lshl_add_u64 v[46:47], v[46:47], 0, v[2:3]
	v_lshlrev_b32_e32 v2, 1, v6
	v_lshl_add_u64 v[46:47], v[46:47], 0, v[2:3]
	global_store_dwordx4 v[46:47], v[26:29], off
	v_bfe_u32 v30, v45, 16, 1
	v_add3_u32 v30, v45, v30, s81
	v_bfe_u32 v26, v33, 16, 1
	v_add3_u32 v26, v33, v26, s81
	v_bfe_u32 v27, v31, 16, 1
	v_lshrrev_b32_e32 v26, 16, v26
	v_add3_u32 v27, v31, v27, s81
	v_and_or_b32 v26, v27, s39, v26
	v_bfe_u32 v27, v35, 16, 1
	v_add3_u32 v27, v35, v27, s81
	v_bfe_u32 v28, v37, 16, 1
	v_lshrrev_b32_e32 v27, 16, v27
	v_add3_u32 v28, v37, v28, s81
	v_and_or_b32 v27, v28, s39, v27
	v_bfe_u32 v28, v39, 16, 1
	v_add3_u32 v28, v39, v28, s81
	v_bfe_u32 v29, v41, 16, 1
	v_lshrrev_b32_e32 v28, 16, v28
	v_add3_u32 v29, v41, v29, s81
	v_and_or_b32 v28, v29, s39, v28
	v_bfe_u32 v29, v43, 16, 1
	v_add3_u32 v29, v43, v29, s81
	v_lshrrev_b32_e32 v29, 16, v29
	v_and_or_b32 v29, v30, s39, v29
	v_add_u32_e32 v30, s2, v10
	v_cmp_lt_i32_e32 vcc, s41, v30
	v_mov_b32_e32 v33, v3
	s_nop 0
	v_cndmask_b32_e32 v31, 0, v247, vcc
	v_add_u32_e32 v31, v31, v30
	v_cndmask_b32_e32 v32, 0, v248, vcc
	v_and_or_b32 v32, v30, s40, v32
	v_ashrrev_i32_e32 v30, 7, v31
	v_ashrrev_i32_e32 v31, 31, v30
	v_lshlrev_b64 v[30:31], 20, v[30:31]
	v_lshl_add_u64 v[30:31], s[0:1], 0, v[30:31]
	v_lshlrev_b32_e32 v32, 7, v32
	v_lshl_add_u64 v[30:31], v[30:31], 0, v[32:33]
	v_lshl_add_u64 v[30:31], v[30:31], 0, v[2:3]
	global_store_dwordx4 v[30:31], v[26:29], off
	ds_read2_b32 v[30:31], v9 offset0:16 offset1:24
	ds_read2_b32 v[32:33], v9 offset0:81 offset1:89
	ds_read2_b32 v[34:35], v9 offset0:146 offset1:154
	ds_read2_b32 v[36:37], v9 offset0:211 offset1:219
	ds_read2_b32 v[38:39], v25 offset0:20 offset1:28
	ds_read2_b32 v[40:41], v25 offset0:85 offset1:93
	ds_read2_b32 v[42:43], v25 offset0:150 offset1:158
	ds_read2_b32 v[44:45], v25 offset0:215 offset1:223
	s_waitcnt lgkmcnt(7)
	v_bfe_u32 v26, v30, 16, 1
	v_add3_u32 v26, v30, v26, s81
	s_waitcnt lgkmcnt(6)
	v_bfe_u32 v27, v32, 16, 1
	v_lshrrev_b32_e32 v26, 16, v26
	v_add3_u32 v27, v32, v27, s81
	v_and_or_b32 v26, v27, s39, v26
	s_waitcnt lgkmcnt(5)
	v_bfe_u32 v27, v34, 16, 1
	v_add3_u32 v27, v34, v27, s81
	s_waitcnt lgkmcnt(4)
	v_bfe_u32 v28, v36, 16, 1
	v_lshrrev_b32_e32 v27, 16, v27
	v_add3_u32 v28, v36, v28, s81
	v_and_or_b32 v27, v28, s39, v27
	s_waitcnt lgkmcnt(3)
	v_bfe_u32 v28, v38, 16, 1
	v_add3_u32 v28, v38, v28, s81
	s_waitcnt lgkmcnt(2)
	v_bfe_u32 v29, v40, 16, 1
	v_lshrrev_b32_e32 v28, 16, v28
	v_add3_u32 v29, v40, v29, s81
	v_and_or_b32 v28, v29, s39, v28
	s_waitcnt lgkmcnt(1)
	v_bfe_u32 v29, v42, 16, 1
	v_add3_u32 v29, v42, v29, s81
	s_waitcnt lgkmcnt(0)
	v_bfe_u32 v30, v44, 16, 1
	v_lshrrev_b32_e32 v29, 16, v29
	v_add3_u32 v30, v44, v30, s81
	v_and_or_b32 v29, v30, s39, v29
	v_add_u32_e32 v30, s2, v11
	v_cmp_lt_i32_e32 vcc, s41, v30
	s_nop 1
	v_cndmask_b32_e32 v32, 0, v247, vcc
	v_add_u32_e32 v32, v32, v30
	v_ashrrev_i32_e32 v46, 7, v32
	v_cndmask_b32_e32 v34, 0, v248, vcc
	v_ashrrev_i32_e32 v47, 31, v46
	v_and_or_b32 v30, v30, s40, v34
	v_lshlrev_b64 v[46:47], 20, v[46:47]
	v_lshl_add_u64 v[46:47], s[0:1], 0, v[46:47]
	v_lshlrev_b32_e32 v48, 7, v30
	v_lshl_add_u64 v[46:47], v[46:47], 0, v[48:49]
	v_lshl_add_u64 v[46:47], v[46:47], 0, v[2:3]
	global_store_dwordx4 v[46:47], v[26:29], off
	v_bfe_u32 v30, v45, 16, 1
	v_add3_u32 v30, v45, v30, s81
	v_bfe_u32 v26, v31, 16, 1
	v_add3_u32 v26, v31, v26, s81
	v_bfe_u32 v27, v33, 16, 1
	v_lshrrev_b32_e32 v26, 16, v26
	v_add3_u32 v27, v33, v27, s81
	v_and_or_b32 v26, v27, s39, v26
	v_bfe_u32 v27, v35, 16, 1
	v_add3_u32 v27, v35, v27, s81
	v_bfe_u32 v28, v37, 16, 1
	v_lshrrev_b32_e32 v27, 16, v27
	v_add3_u32 v28, v37, v28, s81
	v_and_or_b32 v27, v28, s39, v27
	v_bfe_u32 v28, v39, 16, 1
	v_add3_u32 v28, v39, v28, s81
	v_bfe_u32 v29, v41, 16, 1
	v_lshrrev_b32_e32 v28, 16, v28
	v_add3_u32 v29, v41, v29, s81
	v_and_or_b32 v28, v29, s39, v28
	v_bfe_u32 v29, v43, 16, 1
	v_add3_u32 v29, v43, v29, s81
	v_lshrrev_b32_e32 v29, 16, v29
	v_and_or_b32 v29, v30, s39, v29
	v_add_u32_e32 v30, s2, v12
	v_cmp_lt_i32_e32 vcc, s41, v30
	v_mov_b32_e32 v33, v3
	s_nop 0
	v_cndmask_b32_e32 v31, 0, v247, vcc
	v_add_u32_e32 v31, v31, v30
	v_cndmask_b32_e32 v32, 0, v248, vcc
	v_and_or_b32 v32, v30, s40, v32
	v_ashrrev_i32_e32 v30, 7, v31
	v_ashrrev_i32_e32 v31, 31, v30
	v_lshlrev_b64 v[30:31], 20, v[30:31]
	v_lshl_add_u64 v[30:31], s[0:1], 0, v[30:31]
	v_lshlrev_b32_e32 v32, 7, v32
	v_lshl_add_u64 v[30:31], v[30:31], 0, v[32:33]
	v_lshl_add_u64 v[30:31], v[30:31], 0, v[2:3]
	global_store_dwordx4 v[30:31], v[26:29], off
	ds_read2_b32 v[30:31], v9 offset0:32 offset1:40
	ds_read2_b32 v[32:33], v9 offset0:97 offset1:105
	ds_read2_b32 v[34:35], v9 offset0:162 offset1:170
	ds_read2_b32 v[36:37], v9 offset0:227 offset1:235
	ds_read2_b32 v[38:39], v25 offset0:36 offset1:44
	ds_read2_b32 v[40:41], v25 offset0:101 offset1:109
	ds_read2_b32 v[42:43], v25 offset0:166 offset1:174
	ds_read2_b32 v[44:45], v25 offset0:231 offset1:239
	s_waitcnt lgkmcnt(7)
	v_bfe_u32 v26, v30, 16, 1
	v_add3_u32 v26, v30, v26, s81
	s_waitcnt lgkmcnt(6)
	v_bfe_u32 v27, v32, 16, 1
	v_lshrrev_b32_e32 v26, 16, v26
	v_add3_u32 v27, v32, v27, s81
	v_and_or_b32 v26, v27, s39, v26
	s_waitcnt lgkmcnt(5)
	v_bfe_u32 v27, v34, 16, 1
	v_add3_u32 v27, v34, v27, s81
	s_waitcnt lgkmcnt(4)
	v_bfe_u32 v28, v36, 16, 1
	v_lshrrev_b32_e32 v27, 16, v27
	v_add3_u32 v28, v36, v28, s81
	v_and_or_b32 v27, v28, s39, v27
	s_waitcnt lgkmcnt(3)
	v_bfe_u32 v28, v38, 16, 1
	v_add3_u32 v28, v38, v28, s81
	s_waitcnt lgkmcnt(2)
	v_bfe_u32 v29, v40, 16, 1
	v_lshrrev_b32_e32 v28, 16, v28
	v_add3_u32 v29, v40, v29, s81
	v_and_or_b32 v28, v29, s39, v28
	s_waitcnt lgkmcnt(1)
	v_bfe_u32 v29, v42, 16, 1
	v_add3_u32 v29, v42, v29, s81
	s_waitcnt lgkmcnt(0)
	v_bfe_u32 v30, v44, 16, 1
	v_lshrrev_b32_e32 v29, 16, v29
	v_add3_u32 v30, v44, v30, s81
	v_and_or_b32 v29, v30, s39, v29
	v_add_u32_e32 v30, s2, v13
	v_cmp_lt_i32_e32 vcc, s41, v30
	s_nop 1
	v_cndmask_b32_e32 v32, 0, v247, vcc
	v_add_u32_e32 v32, v32, v30
	v_ashrrev_i32_e32 v46, 7, v32
	v_cndmask_b32_e32 v34, 0, v248, vcc
	v_ashrrev_i32_e32 v47, 31, v46
	v_and_or_b32 v30, v30, s40, v34
	v_lshlrev_b64 v[46:47], 20, v[46:47]
	v_lshl_add_u64 v[46:47], s[0:1], 0, v[46:47]
	v_lshlrev_b32_e32 v48, 7, v30
	v_lshl_add_u64 v[46:47], v[46:47], 0, v[48:49]
	v_lshl_add_u64 v[46:47], v[46:47], 0, v[2:3]
	global_store_dwordx4 v[46:47], v[26:29], off
	v_bfe_u32 v30, v45, 16, 1
	v_add3_u32 v30, v45, v30, s81
	v_bfe_u32 v26, v31, 16, 1
	v_add3_u32 v26, v31, v26, s81
	v_bfe_u32 v27, v33, 16, 1
	v_lshrrev_b32_e32 v26, 16, v26
	v_add3_u32 v27, v33, v27, s81
	v_and_or_b32 v26, v27, s39, v26
	v_bfe_u32 v27, v35, 16, 1
	v_add3_u32 v27, v35, v27, s81
	v_bfe_u32 v28, v37, 16, 1
	v_lshrrev_b32_e32 v27, 16, v27
	v_add3_u32 v28, v37, v28, s81
	v_and_or_b32 v27, v28, s39, v27
	v_bfe_u32 v28, v39, 16, 1
	v_add3_u32 v28, v39, v28, s81
	v_bfe_u32 v29, v41, 16, 1
	v_lshrrev_b32_e32 v28, 16, v28
	v_add3_u32 v29, v41, v29, s81
	v_and_or_b32 v28, v29, s39, v28
	v_bfe_u32 v29, v43, 16, 1
	v_add3_u32 v29, v43, v29, s81
	v_lshrrev_b32_e32 v29, 16, v29
	v_and_or_b32 v29, v30, s39, v29
	v_add_u32_e32 v30, s2, v14
	v_cmp_lt_i32_e32 vcc, s41, v30
	v_mov_b32_e32 v33, v3
	s_nop 0
	v_cndmask_b32_e32 v31, 0, v247, vcc
	v_add_u32_e32 v31, v31, v30
	v_cndmask_b32_e32 v32, 0, v248, vcc
	v_and_or_b32 v32, v30, s40, v32
	v_ashrrev_i32_e32 v30, 7, v31
	v_ashrrev_i32_e32 v31, 31, v30
	v_lshlrev_b64 v[30:31], 20, v[30:31]
	v_lshl_add_u64 v[30:31], s[0:1], 0, v[30:31]
	v_lshlrev_b32_e32 v32, 7, v32
	v_lshl_add_u64 v[30:31], v[30:31], 0, v[32:33]
	v_lshl_add_u64 v[30:31], v[30:31], 0, v[2:3]
	global_store_dwordx4 v[30:31], v[26:29], off
	ds_read2_b32 v[30:31], v9 offset0:48 offset1:56
	ds_read2_b32 v[32:33], v9 offset0:113 offset1:121
	ds_read2_b32 v[34:35], v9 offset0:178 offset1:186
	ds_read2_b32 v[36:37], v9 offset0:243 offset1:251
	ds_read2_b32 v[38:39], v25 offset0:52 offset1:60
	ds_read2_b32 v[40:41], v25 offset0:117 offset1:125
	ds_read2_b32 v[42:43], v25 offset0:182 offset1:190
	ds_read2_b32 v[44:45], v25 offset0:247 offset1:255
	s_waitcnt lgkmcnt(7)
	v_bfe_u32 v26, v30, 16, 1
	v_add3_u32 v26, v30, v26, s81
	s_waitcnt lgkmcnt(6)
	v_bfe_u32 v27, v32, 16, 1
	v_lshrrev_b32_e32 v26, 16, v26
	v_add3_u32 v27, v32, v27, s81
	v_and_or_b32 v26, v27, s39, v26
	s_waitcnt lgkmcnt(5)
	v_bfe_u32 v27, v34, 16, 1
	v_add3_u32 v27, v34, v27, s81
	s_waitcnt lgkmcnt(4)
	v_bfe_u32 v28, v36, 16, 1
	v_lshrrev_b32_e32 v27, 16, v27
	v_add3_u32 v28, v36, v28, s81
	v_and_or_b32 v27, v28, s39, v27
	s_waitcnt lgkmcnt(3)
	v_bfe_u32 v28, v38, 16, 1
	v_add3_u32 v28, v38, v28, s81
	s_waitcnt lgkmcnt(2)
	v_bfe_u32 v29, v40, 16, 1
	v_lshrrev_b32_e32 v28, 16, v28
	v_add3_u32 v29, v40, v29, s81
	s_waitcnt lgkmcnt(1)
	v_bfe_u32 v25, v42, 16, 1
	v_and_or_b32 v28, v29, s39, v28
	v_add3_u32 v25, v42, v25, s81
	s_waitcnt lgkmcnt(0)
	v_bfe_u32 v29, v44, 16, 1
	v_lshrrev_b32_e32 v25, 16, v25
	v_add3_u32 v29, v44, v29, s81
	v_and_or_b32 v29, v29, s39, v25
	v_add_u32_e32 v25, s2, v15
	v_cmp_lt_i32_e32 vcc, s41, v25
	s_nop 1
	v_cndmask_b32_e32 v30, 0, v247, vcc
	v_add_u32_e32 v30, v30, v25
	v_ashrrev_i32_e32 v46, 7, v30
	v_cndmask_b32_e32 v32, 0, v248, vcc
	v_ashrrev_i32_e32 v47, 31, v46
	v_and_or_b32 v25, v25, s40, v32
	v_lshlrev_b64 v[46:47], 20, v[46:47]
	v_lshl_add_u64 v[46:47], s[0:1], 0, v[46:47]
	v_lshlrev_b32_e32 v48, 7, v25
	v_lshl_add_u64 v[46:47], v[46:47], 0, v[48:49]
	v_lshl_add_u64 v[46:47], v[46:47], 0, v[2:3]
	v_bfe_u32 v25, v31, 16, 1
	global_store_dwordx4 v[46:47], v[26:29], off
	v_add3_u32 v25, v31, v25, s81
	v_lshrrev_b32_e32 v25, 16, v25
	v_bfe_u32 v26, v33, 16, 1
	v_add3_u32 v26, v33, v26, s81
	v_and_or_b32 v26, v26, s39, v25
	v_bfe_u32 v25, v35, 16, 1
	v_add3_u32 v25, v35, v25, s81
	v_bfe_u32 v27, v37, 16, 1
	v_lshrrev_b32_e32 v25, 16, v25
	v_add3_u32 v27, v37, v27, s81
	v_and_or_b32 v27, v27, s39, v25
	v_bfe_u32 v25, v39, 16, 1
	v_add3_u32 v25, v39, v25, s81
	v_bfe_u32 v28, v41, 16, 1
	v_lshrrev_b32_e32 v25, 16, v25
	v_add3_u32 v28, v41, v28, s81
	v_and_or_b32 v28, v28, s39, v25
	v_bfe_u32 v25, v43, 16, 1
	v_add3_u32 v25, v43, v25, s81
	v_bfe_u32 v29, v45, 16, 1
	v_lshrrev_b32_e32 v25, 16, v25
	v_add3_u32 v29, v45, v29, s81
	v_and_or_b32 v29, v29, s39, v25
	v_add_u32_e32 v25, s2, v16
	v_cmp_lt_i32_e32 vcc, s41, v25
	v_mov_b32_e32 v33, v3
	s_nop 0
	v_cndmask_b32_e32 v30, 0, v247, vcc
	v_add_u32_e32 v30, v30, v25
	v_cndmask_b32_e32 v31, 0, v248, vcc
	v_ashrrev_i32_e32 v30, 7, v30
	v_and_or_b32 v25, v25, s40, v31
	v_ashrrev_i32_e32 v31, 31, v30
	v_lshlrev_b64 v[30:31], 20, v[30:31]
	v_lshl_add_u64 v[30:31], s[0:1], 0, v[30:31]
	v_lshlrev_b32_e32 v32, 7, v25
	v_lshl_add_u64 v[30:31], v[30:31], 0, v[32:33]
	v_lshl_add_u64 v[30:31], v[30:31], 0, v[2:3]
	global_store_dwordx4 v[30:31], v[26:29], off
	s_waitcnt lgkmcnt(0)

.LBB0_954:
	s_andn2_b64 vcc, exec, s[0:1]
	s_cbranch_vccnz .LBB0_956
	s_load_dwordx2 s[0:1], s[6:7], 0x58
	s_add_i32 s2, s20, 0x3400
	s_and_b32 s23, s2, 0x1fc0
	s_add_i32 s2, s18, 0xfff4c000
	s_and_b32 s2, s2, 0x7c0
	s_add_i32 s3, s22, 0xffffd300
	v_add_u32_e32 v26, s23, v5
	s_lshl_b32 s23, s2, 2
	s_waitcnt lgkmcnt(0)
	s_add_u32 s0, s0, s23
	s_addc_u32 s1, s1, 0
	v_lshlrev_b32_e32 v2, 2, v4
	v_ashrrev_i32_e32 v27, 31, v26
	v_lshl_add_u64 v[28:29], s[0:1], 0, v[2:3]
	v_lshlrev_b64 v[26:27], 13, v[26:27]
	v_lshl_add_u64 v[86:87], v[28:29], 0, v[26:27]
	s_mov_b32 s0, 0x1000000
	v_add_co_u32_e32 v26, vcc, s0, v86
	s_mov_b32 s0, 0x1008000
	s_nop 0
	v_addc_co_u32_e32 v27, vcc, 0, v87, vcc
	v_add_co_u32_e32 v30, vcc, s0, v86
	s_mov_b32 s0, 0x1010000
	s_nop 0
	v_addc_co_u32_e32 v31, vcc, 0, v87, vcc
	v_add_co_u32_e32 v34, vcc, s0, v86
	global_load_dwordx4 v[26:29], v[26:27], off nt
	s_nop 0
	global_load_dwordx4 v[30:33], v[30:31], off nt
	v_addc_co_u32_e32 v35, vcc, 0, v87, vcc
	s_mov_b32 s0, 0x1018000
	v_add_co_u32_e32 v38, vcc, s0, v86
	s_mov_b32 s0, 0x1020000
	s_nop 0
	v_addc_co_u32_e32 v39, vcc, 0, v87, vcc
	global_load_dwordx4 v[34:37], v[34:35], off nt
	s_nop 0
	global_load_dwordx4 v[38:41], v[38:39], off nt
	v_add_co_u32_e32 v42, vcc, s0, v86
	s_mov_b32 s0, 0x1028000
	s_nop 0
	v_addc_co_u32_e32 v43, vcc, 0, v87, vcc
	v_add_co_u32_e32 v46, vcc, s0, v86
	s_mov_b32 s0, 0x1030000
	s_nop 0
	v_addc_co_u32_e32 v47, vcc, 0, v87, vcc
	global_load_dwordx4 v[42:45], v[42:43], off nt
	s_nop 0
	global_load_dwordx4 v[46:49], v[46:47], off nt
	v_add_co_u32_e32 v50, vcc, s0, v86
	s_mov_b32 s0, 0x1038000
	s_nop 0
	v_addc_co_u32_e32 v51, vcc, 0, v87, vcc
	v_add_co_u32_e32 v54, vcc, s0, v86
	s_mov_b32 s0, 0x1040000
	s_nop 0
	v_addc_co_u32_e32 v55, vcc, 0, v87, vcc
	global_load_dwordx4 v[50:53], v[50:51], off nt
	s_nop 0
	global_load_dwordx4 v[54:57], v[54:55], off nt
	v_add_co_u32_e32 v58, vcc, s0, v86
	s_mov_b32 s0, 0x1048000
	s_nop 0
	v_addc_co_u32_e32 v59, vcc, 0, v87, vcc
	v_add_co_u32_e32 v62, vcc, s0, v86
	s_mov_b32 s0, 0x1050000
	s_nop 0
	v_addc_co_u32_e32 v63, vcc, 0, v87, vcc
	global_load_dwordx4 v[58:61], v[58:59], off nt
	s_nop 0
	global_load_dwordx4 v[62:65], v[62:63], off nt
	v_add_co_u32_e32 v66, vcc, s0, v86
	s_mov_b32 s0, 0x1058000
	s_nop 0
	v_addc_co_u32_e32 v67, vcc, 0, v87, vcc
	v_add_co_u32_e32 v70, vcc, s0, v86
	s_mov_b32 s0, 0x1060000
	s_nop 0
	v_addc_co_u32_e32 v71, vcc, 0, v87, vcc
	global_load_dwordx4 v[66:69], v[66:67], off nt
	s_nop 0
	global_load_dwordx4 v[70:73], v[70:71], off nt
	v_add_co_u32_e32 v74, vcc, s0, v86
	s_mov_b32 s0, 0x1068000
	s_nop 0
	v_addc_co_u32_e32 v75, vcc, 0, v87, vcc
	global_load_dwordx4 v[74:77], v[74:75], off nt
	v_add_co_u32_e32 v78, vcc, s0, v86
	s_mov_b32 s0, 0x1070000
	s_nop 0
	v_addc_co_u32_e32 v79, vcc, 0, v87, vcc
	global_load_dwordx4 v[78:81], v[78:79], off nt
	v_add_co_u32_e32 v82, vcc, s0, v86
	s_mov_b32 s0, 0x1078000
	s_nop 0
	v_addc_co_u32_e32 v83, vcc, 0, v87, vcc
	global_load_dwordx4 v[82:85], v[82:83], off nt
	v_add_co_u32_e32 v86, vcc, s0, v86
	v_add_u32_e32 v2, 0x410, v7
	s_nop 0
	v_addc_co_u32_e32 v87, vcc, 0, v87, vcc
	global_load_dwordx4 v[86:89], v[86:87], off nt
	s_waitcnt vmcnt(0)
	ds_write2_b32 v7, v26, v27 offset1:1
	ds_write2_b32 v7, v28, v29 offset0:2 offset1:3
	ds_write2_b32 v2, v30, v31 offset1:1
	v_add_u32_e32 v2, 0x418, v7
	ds_write2_b32 v2, v32, v33 offset1:1
	v_add_u32_e32 v2, 0x820, v7
	s_lshr_b32 s72, s3, 5
	s_lshl_b64 s[0:1], s[72:73], 15
	ds_write2_b32 v2, v34, v35 offset1:1
	v_add_u32_e32 v2, 0x828, v7
	ds_write2_b32 v2, v36, v37 offset1:1
	v_add_u32_e32 v2, 0xc30, v7
	ds_write2_b32 v2, v38, v39 offset1:1
	v_add_u32_e32 v2, 0xc38, v7
	ds_write2_b32 v2, v40, v41 offset1:1
	v_add_u32_e32 v2, 0x1040, v7
	ds_write2_b32 v2, v42, v43 offset1:1
	v_add_u32_e32 v2, 0x1048, v7
	ds_write2_b32 v2, v44, v45 offset1:1
	v_add_u32_e32 v2, 0x1450, v7
	ds_write2_b32 v2, v46, v47 offset1:1
	v_add_u32_e32 v2, 0x1458, v7
	ds_write2_b32 v2, v48, v49 offset1:1
	v_add_u32_e32 v2, 0x1860, v7
	v_mov_b32_e32 v49, v3
	ds_write2_b32 v2, v50, v51 offset1:1
	v_add_u32_e32 v2, 0x1868, v7
	ds_write2_b32 v2, v52, v53 offset1:1
	v_add_u32_e32 v2, 0x1c70, v7
	ds_write2_b32 v2, v54, v55 offset1:1
	v_add_u32_e32 v2, 0x1c78, v7
	ds_write2_b32 v2, v56, v57 offset1:1
	v_add_u32_e32 v2, 0x2080, v7
	ds_write2_b32 v2, v58, v59 offset1:1
	v_add_u32_e32 v2, 0x2088, v7
	ds_write2_b32 v2, v60, v61 offset1:1
	v_add_u32_e32 v2, 0x2490, v7
	ds_write2_b32 v2, v62, v63 offset1:1
	v_add_u32_e32 v2, 0x2498, v7
	ds_write2_b32 v2, v64, v65 offset1:1
	v_add_u32_e32 v2, 0x28a0, v7
	ds_write2_b32 v2, v66, v67 offset1:1
	v_add_u32_e32 v2, 0x28a8, v7
	ds_write2_b32 v2, v68, v69 offset1:1
	v_add_u32_e32 v2, 0x2cb0, v7
	ds_write2_b32 v2, v70, v71 offset1:1
	v_add_u32_e32 v2, 0x2cb8, v7
	ds_write2_b32 v2, v72, v73 offset1:1
	v_add_u32_e32 v2, 0x30c0, v7
	ds_write2_b32 v2, v74, v75 offset1:1
	v_add_u32_e32 v2, 0x30c8, v7
	ds_write2_b32 v2, v76, v77 offset1:1
	v_add_u32_e32 v2, 0x34d0, v7
	ds_write2_b32 v2, v78, v79 offset1:1
	v_add_u32_e32 v2, 0x34d8, v7
	ds_write2_b32 v2, v80, v81 offset1:1
	v_add_u32_e32 v2, 0x38e0, v7
	ds_write2_b32 v2, v82, v83 offset1:1
	v_add_u32_e32 v2, 0x38e8, v7
	ds_write2_b32 v2, v84, v85 offset1:1
	v_add_u32_e32 v2, 0x3cf0, v7
	ds_write2_b32 v2, v86, v87 offset1:1
	v_add_u32_e32 v2, 0x3cf8, v7
	ds_write2_b32 v2, v88, v89 offset1:1
	s_waitcnt lgkmcnt(0)
	ds_read2_b32 v[30:31], v9 offset1:8
	ds_read2_b32 v[32:33], v9 offset0:65 offset1:73
	ds_read2_b32 v[34:35], v9 offset0:130 offset1:138
	ds_read2_b32 v[36:37], v9 offset0:195 offset1:203
	s_waitcnt lgkmcnt(3)
	v_bfe_u32 v2, v30, 16, 1
	v_add3_u32 v2, v30, v2, s81
	s_waitcnt lgkmcnt(2)
	v_bfe_u32 v25, v32, 16, 1
	v_lshrrev_b32_e32 v2, 16, v2
	v_add3_u32 v25, v32, v25, s81
	v_and_or_b32 v26, v25, s39, v2
	v_add_u32_e32 v25, 0x400, v9
	ds_read2_b32 v[38:39], v25 offset0:4 offset1:12
	ds_read2_b32 v[40:41], v25 offset0:69 offset1:77
	s_waitcnt lgkmcnt(3)
	v_bfe_u32 v2, v34, 16, 1
	v_add3_u32 v2, v34, v2, s81
	s_waitcnt lgkmcnt(2)
	v_bfe_u32 v27, v36, 16, 1
	ds_read2_b32 v[42:43], v25 offset0:134 offset1:142
	v_lshrrev_b32_e32 v2, 16, v2
	v_add3_u32 v27, v36, v27, s81
	ds_read2_b32 v[44:45], v25 offset0:199 offset1:207
	v_and_or_b32 v27, v27, s39, v2
	s_waitcnt lgkmcnt(3)
	v_bfe_u32 v2, v38, 16, 1
	v_add3_u32 v2, v38, v2, s81
	s_waitcnt lgkmcnt(2)
	v_bfe_u32 v28, v40, 16, 1
	v_lshrrev_b32_e32 v2, 16, v2
	v_add3_u32 v28, v40, v28, s81
	v_and_or_b32 v28, v28, s39, v2
	s_waitcnt lgkmcnt(1)
	v_bfe_u32 v2, v42, 16, 1
	v_add3_u32 v2, v42, v2, s81
	s_waitcnt lgkmcnt(0)
	v_bfe_u32 v29, v44, 16, 1
	v_lshrrev_b32_e32 v2, 16, v2
	v_add3_u32 v29, v44, v29, s81
	v_and_or_b32 v29, v29, s39, v2
	v_add_u32_e32 v2, s2, v8
	v_ashrrev_i32_e32 v46, 8, v2
	v_ashrrev_i32_e32 v47, 31, v46
	v_lshlrev_b64 v[46:47], 20, v[46:47]
	v_lshl_add_u64 v[46:47], s[10:11], 0, v[46:47]
	v_lshlrev_b32_e32 v2, 7, v2
	v_lshl_add_u64 v[46:47], v[46:47], 0, s[0:1]
	v_and_b32_e32 v2, 0x7f80, v2
	v_lshl_add_u64 v[46:47], v[46:47], 0, v[2:3]
	v_lshlrev_b32_e32 v2, 1, v6
	v_lshl_add_u64 v[46:47], v[46:47], 0, v[2:3]
	global_store_dwordx4 v[46:47], v[26:29], off
	v_bfe_u32 v30, v45, 16, 1
	v_add3_u32 v30, v45, v30, s81
	v_bfe_u32 v26, v31, 16, 1
	v_add3_u32 v26, v31, v26, s81
	v_bfe_u32 v27, v33, 16, 1
	v_lshrrev_b32_e32 v26, 16, v26
	v_add3_u32 v27, v33, v27, s81
	v_and_or_b32 v26, v27, s39, v26
	v_bfe_u32 v27, v35, 16, 1
	v_add3_u32 v27, v35, v27, s81
	v_bfe_u32 v28, v37, 16, 1
	v_lshrrev_b32_e32 v27, 16, v27
	v_add3_u32 v28, v37, v28, s81
	v_and_or_b32 v27, v28, s39, v27
	v_bfe_u32 v28, v39, 16, 1
	v_add3_u32 v28, v39, v28, s81
	v_bfe_u32 v29, v41, 16, 1
	v_lshrrev_b32_e32 v28, 16, v28
	v_add3_u32 v29, v41, v29, s81
	v_and_or_b32 v28, v29, s39, v28
	v_bfe_u32 v29, v43, 16, 1
	v_add3_u32 v29, v43, v29, s81
	v_lshrrev_b32_e32 v29, 16, v29
	v_add_u32_e32 v32, s2, v10
	v_and_or_b32 v29, v30, s39, v29
	v_ashrrev_i32_e32 v30, 8, v32
	v_ashrrev_i32_e32 v31, 31, v30
	v_lshlrev_b64 v[30:31], 20, v[30:31]
	v_lshl_add_u64 v[30:31], s[10:11], 0, v[30:31]
	v_lshlrev_b32_e32 v32, 7, v32
	v_lshl_add_u64 v[30:31], v[30:31], 0, s[0:1]
	v_and_b32_e32 v32, 0x7f80, v32
	v_mov_b32_e32 v33, v3
	v_lshl_add_u64 v[30:31], v[30:31], 0, v[32:33]
	ds_read2_b32 v[34:35], v9 offset0:16 offset1:24
	v_lshl_add_u64 v[30:31], v[30:31], 0, v[2:3]
	global_store_dwordx4 v[30:31], v[26:29], off
	ds_read2_b32 v[30:31], v9 offset0:81 offset1:89
	ds_read2_b32 v[32:33], v9 offset0:146 offset1:154
	ds_read2_b32 v[36:37], v9 offset0:211 offset1:219
	s_waitcnt lgkmcnt(3)
	v_bfe_u32 v26, v34, 16, 1
	v_add3_u32 v26, v34, v26, s81
	s_waitcnt lgkmcnt(2)
	v_bfe_u32 v27, v30, 16, 1
	ds_read2_b32 v[38:39], v25 offset0:20 offset1:28
	v_lshrrev_b32_e32 v26, 16, v26
	v_add3_u32 v27, v30, v27, s81
	ds_read2_b32 v[40:41], v25 offset0:85 offset1:93
	v_and_or_b32 v26, v27, s39, v26
	s_waitcnt lgkmcnt(3)
	v_bfe_u32 v27, v32, 16, 1
	v_add3_u32 v27, v32, v27, s81
	s_waitcnt lgkmcnt(2)
	v_bfe_u32 v28, v36, 16, 1
	ds_read2_b32 v[42:43], v25 offset0:150 offset1:158
	v_lshrrev_b32_e32 v27, 16, v27
	v_add3_u32 v28, v36, v28, s81
	ds_read2_b32 v[44:45], v25 offset0:215 offset1:223
	v_and_or_b32 v27, v28, s39, v27
	s_waitcnt lgkmcnt(3)
	v_bfe_u32 v28, v38, 16, 1
	v_add3_u32 v28, v38, v28, s81
	s_waitcnt lgkmcnt(2)
	v_bfe_u32 v29, v40, 16, 1
	v_lshrrev_b32_e32 v28, 16, v28
	v_add3_u32 v29, v40, v29, s81
	v_and_or_b32 v28, v29, s39, v28
	s_waitcnt lgkmcnt(1)
	v_bfe_u32 v29, v42, 16, 1
	v_add3_u32 v29, v42, v29, s81
	s_waitcnt lgkmcnt(0)
	v_bfe_u32 v30, v44, 16, 1
	v_lshrrev_b32_e32 v29, 16, v29
	v_add3_u32 v30, v44, v30, s81
	v_and_or_b32 v29, v30, s39, v29
	v_add_u32_e32 v30, s2, v11
	v_ashrrev_i32_e32 v46, 8, v30
	v_ashrrev_i32_e32 v47, 31, v46
	v_lshlrev_b64 v[46:47], 20, v[46:47]
	v_lshl_add_u64 v[46:47], s[10:11], 0, v[46:47]
	v_lshlrev_b32_e32 v30, 7, v30
	v_lshl_add_u64 v[46:47], v[46:47], 0, s[0:1]
	v_and_b32_e32 v48, 0x7f80, v30
	v_lshl_add_u64 v[46:47], v[46:47], 0, v[48:49]
	v_lshl_add_u64 v[46:47], v[46:47], 0, v[2:3]
	global_store_dwordx4 v[46:47], v[26:29], off
	v_bfe_u32 v30, v45, 16, 1
	v_add3_u32 v30, v45, v30, s81
	v_bfe_u32 v26, v35, 16, 1
	v_add3_u32 v26, v35, v26, s81
	v_bfe_u32 v27, v31, 16, 1
	v_lshrrev_b32_e32 v26, 16, v26
	v_add3_u32 v27, v31, v27, s81
	v_and_or_b32 v26, v27, s39, v26
	v_bfe_u32 v27, v33, 16, 1
	v_add3_u32 v27, v33, v27, s81
	v_bfe_u32 v28, v37, 16, 1
	v_lshrrev_b32_e32 v27, 16, v27
	v_add3_u32 v28, v37, v28, s81
	v_and_or_b32 v27, v28, s39, v27
	v_bfe_u32 v28, v39, 16, 1
	v_add3_u32 v28, v39, v28, s81
	v_bfe_u32 v29, v41, 16, 1
	v_lshrrev_b32_e32 v28, 16, v28
	v_add3_u32 v29, v41, v29, s81
	v_and_or_b32 v28, v29, s39, v28
	v_bfe_u32 v29, v43, 16, 1
	v_add3_u32 v29, v43, v29, s81
	v_lshrrev_b32_e32 v29, 16, v29
	v_add_u32_e32 v32, s2, v12
	v_and_or_b32 v29, v30, s39, v29
	v_ashrrev_i32_e32 v30, 8, v32
	v_ashrrev_i32_e32 v31, 31, v30
	v_lshlrev_b64 v[30:31], 20, v[30:31]
	v_lshl_add_u64 v[30:31], s[10:11], 0, v[30:31]
	v_lshlrev_b32_e32 v32, 7, v32
	v_lshl_add_u64 v[30:31], v[30:31], 0, s[0:1]
	v_and_b32_e32 v32, 0x7f80, v32
	v_mov_b32_e32 v33, v3
	v_lshl_add_u64 v[30:31], v[30:31], 0, v[32:33]
	ds_read2_b32 v[34:35], v9 offset0:32 offset1:40
	v_lshl_add_u64 v[30:31], v[30:31], 0, v[2:3]
	global_store_dwordx4 v[30:31], v[26:29], off
	ds_read2_b32 v[30:31], v9 offset0:97 offset1:105
	ds_read2_b32 v[32:33], v9 offset0:162 offset1:170
	ds_read2_b32 v[36:37], v9 offset0:227 offset1:235
	s_waitcnt lgkmcnt(3)
	v_bfe_u32 v26, v34, 16, 1
	v_add3_u32 v26, v34, v26, s81
	s_waitcnt lgkmcnt(2)
	v_bfe_u32 v27, v30, 16, 1
	ds_read2_b32 v[38:39], v25 offset0:36 offset1:44
	v_lshrrev_b32_e32 v26, 16, v26
	v_add3_u32 v27, v30, v27, s81
	ds_read2_b32 v[40:41], v25 offset0:101 offset1:109
	v_and_or_b32 v26, v27, s39, v26
	s_waitcnt lgkmcnt(3)
	v_bfe_u32 v27, v32, 16, 1
	v_add3_u32 v27, v32, v27, s81
	s_waitcnt lgkmcnt(2)
	v_bfe_u32 v28, v36, 16, 1
	ds_read2_b32 v[42:43], v25 offset0:166 offset1:174
	v_lshrrev_b32_e32 v27, 16, v27
	v_add3_u32 v28, v36, v28, s81
	ds_read2_b32 v[44:45], v25 offset0:231 offset1:239
	v_and_or_b32 v27, v28, s39, v27
	s_waitcnt lgkmcnt(3)
	v_bfe_u32 v28, v38, 16, 1
	v_add3_u32 v28, v38, v28, s81
	s_waitcnt lgkmcnt(2)
	v_bfe_u32 v29, v40, 16, 1
	v_lshrrev_b32_e32 v28, 16, v28
	v_add3_u32 v29, v40, v29, s81
	v_and_or_b32 v28, v29, s39, v28
	s_waitcnt lgkmcnt(1)
	v_bfe_u32 v29, v42, 16, 1
	v_add3_u32 v29, v42, v29, s81
	s_waitcnt lgkmcnt(0)
	v_bfe_u32 v30, v44, 16, 1
	v_lshrrev_b32_e32 v29, 16, v29
	v_add3_u32 v30, v44, v30, s81
	v_and_or_b32 v29, v30, s39, v29
	v_add_u32_e32 v30, s2, v13
	v_ashrrev_i32_e32 v46, 8, v30
	v_ashrrev_i32_e32 v47, 31, v46
	v_lshlrev_b64 v[46:47], 20, v[46:47]
	v_lshl_add_u64 v[46:47], s[10:11], 0, v[46:47]
	v_lshlrev_b32_e32 v30, 7, v30
	v_lshl_add_u64 v[46:47], v[46:47], 0, s[0:1]
	v_and_b32_e32 v48, 0x7f80, v30
	v_lshl_add_u64 v[46:47], v[46:47], 0, v[48:49]
	v_lshl_add_u64 v[46:47], v[46:47], 0, v[2:3]
	global_store_dwordx4 v[46:47], v[26:29], off
	v_bfe_u32 v30, v45, 16, 1
	v_add3_u32 v30, v45, v30, s81
	v_bfe_u32 v26, v35, 16, 1
	v_add3_u32 v26, v35, v26, s81
	v_bfe_u32 v27, v31, 16, 1
	v_lshrrev_b32_e32 v26, 16, v26
	v_add3_u32 v27, v31, v27, s81
	v_and_or_b32 v26, v27, s39, v26
	v_bfe_u32 v27, v33, 16, 1
	v_add3_u32 v27, v33, v27, s81
	v_bfe_u32 v28, v37, 16, 1
	v_lshrrev_b32_e32 v27, 16, v27
	v_add3_u32 v28, v37, v28, s81
	v_and_or_b32 v27, v28, s39, v27
	v_bfe_u32 v28, v39, 16, 1
	v_add3_u32 v28, v39, v28, s81
	v_bfe_u32 v29, v41, 16, 1
	v_lshrrev_b32_e32 v28, 16, v28
	v_add3_u32 v29, v41, v29, s81
	v_and_or_b32 v28, v29, s39, v28
	v_bfe_u32 v29, v43, 16, 1
	v_add3_u32 v29, v43, v29, s81
	v_lshrrev_b32_e32 v29, 16, v29
	v_add_u32_e32 v32, s2, v14
	v_and_or_b32 v29, v30, s39, v29
	v_ashrrev_i32_e32 v30, 8, v32
	v_ashrrev_i32_e32 v31, 31, v30
	v_lshlrev_b64 v[30:31], 20, v[30:31]
	v_lshl_add_u64 v[30:31], s[10:11], 0, v[30:31]
	v_lshlrev_b32_e32 v32, 7, v32
	v_lshl_add_u64 v[30:31], v[30:31], 0, s[0:1]
	v_and_b32_e32 v32, 0x7f80, v32
	v_mov_b32_e32 v33, v3
	v_lshl_add_u64 v[30:31], v[30:31], 0, v[32:33]
	ds_read2_b32 v[34:35], v9 offset0:48 offset1:56
	v_lshl_add_u64 v[30:31], v[30:31], 0, v[2:3]
	global_store_dwordx4 v[30:31], v[26:29], off
	ds_read2_b32 v[30:31], v9 offset0:113 offset1:121
	ds_read2_b32 v[32:33], v9 offset0:178 offset1:186
	ds_read2_b32 v[36:37], v9 offset0:243 offset1:251
	s_waitcnt lgkmcnt(3)
	v_bfe_u32 v26, v34, 16, 1
	v_add3_u32 v26, v34, v26, s81
	s_waitcnt lgkmcnt(2)
	v_bfe_u32 v27, v30, 16, 1
	ds_read2_b32 v[38:39], v25 offset0:52 offset1:60
	v_lshrrev_b32_e32 v26, 16, v26
	v_add3_u32 v27, v30, v27, s81
	ds_read2_b32 v[40:41], v25 offset0:117 offset1:125
	v_and_or_b32 v26, v27, s39, v26
	s_waitcnt lgkmcnt(3)
	v_bfe_u32 v27, v32, 16, 1
	ds_read2_b32 v[42:43], v25 offset0:182 offset1:190
	v_add3_u32 v27, v32, v27, s81
	s_waitcnt lgkmcnt(3)
	v_bfe_u32 v28, v36, 16, 1
	ds_read2_b32 v[44:45], v25 offset0:247 offset1:255
	v_lshrrev_b32_e32 v27, 16, v27
	v_add3_u32 v28, v36, v28, s81
	v_and_or_b32 v27, v28, s39, v27
	s_waitcnt lgkmcnt(3)
	v_bfe_u32 v28, v38, 16, 1
	v_add3_u32 v28, v38, v28, s81
	s_waitcnt lgkmcnt(2)
	v_bfe_u32 v29, v40, 16, 1
	v_lshrrev_b32_e32 v28, 16, v28
	v_add3_u32 v29, v40, v29, s81
	s_waitcnt lgkmcnt(1)
	v_bfe_u32 v25, v42, 16, 1
	v_and_or_b32 v28, v29, s39, v28
	v_add3_u32 v25, v42, v25, s81
	s_waitcnt lgkmcnt(0)
	v_bfe_u32 v29, v44, 16, 1
	v_lshrrev_b32_e32 v25, 16, v25
	v_add3_u32 v29, v44, v29, s81
	v_and_or_b32 v29, v29, s39, v25
	v_add_u32_e32 v25, s2, v15
	v_ashrrev_i32_e32 v46, 8, v25
	v_ashrrev_i32_e32 v47, 31, v46
	v_lshlrev_b64 v[46:47], 20, v[46:47]
	v_lshl_add_u64 v[46:47], s[10:11], 0, v[46:47]
	v_lshlrev_b32_e32 v25, 7, v25
	v_lshl_add_u64 v[46:47], v[46:47], 0, s[0:1]
	v_and_b32_e32 v48, 0x7f80, v25
	v_lshl_add_u64 v[46:47], v[46:47], 0, v[48:49]
	v_lshl_add_u64 v[46:47], v[46:47], 0, v[2:3]
	v_bfe_u32 v25, v35, 16, 1
	global_store_dwordx4 v[46:47], v[26:29], off
	v_add3_u32 v25, v35, v25, s81
	v_lshrrev_b32_e32 v25, 16, v25
	v_bfe_u32 v26, v31, 16, 1
	v_add3_u32 v26, v31, v26, s81
	v_and_or_b32 v26, v26, s39, v25
	v_bfe_u32 v25, v33, 16, 1
	v_add3_u32 v25, v33, v25, s81
	v_bfe_u32 v27, v37, 16, 1
	v_lshrrev_b32_e32 v25, 16, v25
	v_add3_u32 v27, v37, v27, s81
	v_and_or_b32 v27, v27, s39, v25
	v_bfe_u32 v25, v39, 16, 1
	v_add3_u32 v25, v39, v25, s81
	v_bfe_u32 v28, v41, 16, 1
	v_lshrrev_b32_e32 v25, 16, v25
	v_add3_u32 v28, v41, v28, s81
	v_and_or_b32 v28, v28, s39, v25
	v_bfe_u32 v25, v43, 16, 1
	v_add3_u32 v25, v43, v25, s81
	v_bfe_u32 v29, v45, 16, 1
	v_lshrrev_b32_e32 v25, 16, v25
	v_add3_u32 v29, v45, v29, s81
	v_and_or_b32 v29, v29, s39, v25
	v_add_u32_e32 v25, s2, v16
	v_ashrrev_i32_e32 v30, 8, v25
	v_ashrrev_i32_e32 v31, 31, v30
	v_lshlrev_b64 v[30:31], 20, v[30:31]
	v_lshl_add_u64 v[30:31], s[10:11], 0, v[30:31]
	v_lshlrev_b32_e32 v25, 7, v25
	v_lshl_add_u64 v[30:31], v[30:31], 0, s[0:1]
	v_and_b32_e32 v32, 0x7f80, v25
	v_mov_b32_e32 v33, v3
	v_lshl_add_u64 v[30:31], v[30:31], 0, v[32:33]
	v_lshl_add_u64 v[30:31], v[30:31], 0, v[2:3]
	global_store_dwordx4 v[30:31], v[26:29], off
	s_waitcnt lgkmcnt(0)

.LBB0_957:
	s_andn2_b64 vcc, exec, s[0:1]
	s_cbranch_vccnz .LBB0_959
	s_add_i32 s1, s22, 0xdf00
	s_and_b32 s0, s1, 0xffff
	s_mul_i32 s0, s0, 0xaaab
	s_lshr_b32 s0, s0, 22
	s_load_dwordx2 s[24:25], s[6:7], 0x50
	s_mul_i32 s2, s0, 0x60
	s_sub_i32 s1, s1, s2
	s_lshl_b32 s1, s1, 6
	s_and_b32 s2, s1, 0xffc0
	s_lshl_b32 s1, s2, 2
	s_waitcnt lgkmcnt(0)
	s_add_u32 s24, s24, s1
	s_addc_u32 s25, s25, 0
	v_lshlrev_b32_e32 v2, 2, v4
	v_lshl_add_u32 v25, s0, 6, v5
	v_lshl_add_u64 v[26:27], s[24:25], 0, v[2:3]
	s_mov_b64 s[24:25], 0x3000000
	v_lshl_add_u64 v[86:87], v[26:27], 0, s[24:25]
	s_movk_i32 s1, 0x6000
	v_add_u32_e32 v2, 4, v25
	v_mad_i64_i32 v[26:27], s[24:25], v25, s1, v[86:87]
	v_mad_i64_i32 v[30:31], s[24:25], v2, s1, v[86:87]
	global_load_dwordx4 v[26:29], v[26:27], off nt
	v_add_u32_e32 v2, 8, v25
	global_load_dwordx4 v[30:33], v[30:31], off nt
	v_mad_i64_i32 v[34:35], s[24:25], v2, s1, v[86:87]
	global_load_dwordx4 v[34:37], v[34:35], off nt
	v_add_u32_e32 v2, 12, v25
	v_mad_i64_i32 v[38:39], s[24:25], v2, s1, v[86:87]
	global_load_dwordx4 v[38:41], v[38:39], off nt
	v_add_u32_e32 v2, 16, v25
	v_mad_i64_i32 v[42:43], s[24:25], v2, s1, v[86:87]
	global_load_dwordx4 v[42:45], v[42:43], off nt
	v_add_u32_e32 v2, 20, v25
	v_mad_i64_i32 v[46:47], s[24:25], v2, s1, v[86:87]
	global_load_dwordx4 v[46:49], v[46:47], off nt
	v_add_u32_e32 v2, 24, v25
	v_mad_i64_i32 v[50:51], s[24:25], v2, s1, v[86:87]
	global_load_dwordx4 v[50:53], v[50:51], off nt
	v_add_u32_e32 v2, 28, v25
	v_mad_i64_i32 v[54:55], s[24:25], v2, s1, v[86:87]
	global_load_dwordx4 v[54:57], v[54:55], off nt
	v_add_u32_e32 v2, 32, v25
	v_mad_i64_i32 v[58:59], s[24:25], v2, s1, v[86:87]
	global_load_dwordx4 v[58:61], v[58:59], off nt
	v_add_u32_e32 v2, 36, v25
	v_mad_i64_i32 v[62:63], s[24:25], v2, s1, v[86:87]
	global_load_dwordx4 v[62:65], v[62:63], off nt
	v_add_u32_e32 v2, 40, v25
	v_mad_i64_i32 v[66:67], s[24:25], v2, s1, v[86:87]
	global_load_dwordx4 v[66:69], v[66:67], off nt
	v_add_u32_e32 v2, 44, v25
	v_mad_i64_i32 v[70:71], s[24:25], v2, s1, v[86:87]
	global_load_dwordx4 v[70:73], v[70:71], off nt
	v_add_u32_e32 v2, 48, v25
	v_mad_i64_i32 v[74:75], s[24:25], v2, s1, v[86:87]
	global_load_dwordx4 v[74:77], v[74:75], off nt
	v_add_u32_e32 v2, 52, v25
	v_mad_i64_i32 v[78:79], s[24:25], v2, s1, v[86:87]
	global_load_dwordx4 v[78:81], v[78:79], off nt
	v_add_u32_e32 v2, 56, v25
	v_mad_i64_i32 v[82:83], s[24:25], v2, s1, v[86:87]
	global_load_dwordx4 v[82:85], v[82:83], off nt
	v_add_u32_e32 v2, 60, v25
	v_mad_i64_i32 v[86:87], s[24:25], v2, s1, v[86:87]
	global_load_dwordx4 v[86:89], v[86:87], off nt
	v_add_u32_e32 v2, 0x410, v7
	s_movk_i32 s3, 0x800
	s_lshl_b32 s0, s0, 15
	s_add_u32 s0, s16, s0
	s_addc_u32 s1, s17, 0
	s_waitcnt vmcnt(0)
	ds_write2_b32 v7, v26, v27 offset1:1
	ds_write2_b32 v7, v28, v29 offset0:2 offset1:3
	ds_write2_b32 v2, v30, v31 offset1:1
	v_add_u32_e32 v2, 0x418, v7
	ds_write2_b32 v2, v32, v33 offset1:1
	v_add_u32_e32 v2, 0x820, v7
	ds_write2_b32 v2, v34, v35 offset1:1
	v_add_u32_e32 v2, 0x828, v7
	ds_write2_b32 v2, v36, v37 offset1:1
	v_add_u32_e32 v2, 0xc30, v7
	ds_write2_b32 v2, v38, v39 offset1:1
	v_add_u32_e32 v2, 0xc38, v7
	ds_write2_b32 v2, v40, v41 offset1:1
	v_add_u32_e32 v2, 0x1040, v7
	ds_write2_b32 v2, v42, v43 offset1:1
	v_add_u32_e32 v2, 0x1048, v7
	ds_write2_b32 v2, v44, v45 offset1:1
	v_add_u32_e32 v2, 0x1450, v7
	ds_write2_b32 v2, v46, v47 offset1:1
	v_add_u32_e32 v2, 0x1458, v7
	ds_write2_b32 v2, v48, v49 offset1:1
	v_add_u32_e32 v2, 0x1860, v7
	ds_write2_b32 v2, v50, v51 offset1:1
	v_add_u32_e32 v2, 0x1868, v7
	ds_write2_b32 v2, v52, v53 offset1:1
	v_add_u32_e32 v2, 0x1c70, v7
	ds_write2_b32 v2, v54, v55 offset1:1
	v_add_u32_e32 v2, 0x1c78, v7
	ds_write2_b32 v2, v56, v57 offset1:1
	v_add_u32_e32 v2, 0x2080, v7
	ds_write2_b32 v2, v58, v59 offset1:1
	v_add_u32_e32 v2, 0x2088, v7
	ds_write2_b32 v2, v60, v61 offset1:1
	v_add_u32_e32 v2, 0x2490, v7
	ds_write2_b32 v2, v62, v63 offset1:1
	v_add_u32_e32 v2, 0x2498, v7
	ds_write2_b32 v2, v64, v65 offset1:1
	v_add_u32_e32 v2, 0x28a0, v7
	ds_write2_b32 v2, v66, v67 offset1:1
	v_add_u32_e32 v2, 0x28a8, v7
	ds_write2_b32 v2, v68, v69 offset1:1
	v_add_u32_e32 v2, 0x2cb0, v7
	ds_write2_b32 v2, v70, v71 offset1:1
	v_add_u32_e32 v2, 0x2cb8, v7
	ds_write2_b32 v2, v72, v73 offset1:1
	v_add_u32_e32 v2, 0x30c0, v7
	ds_write2_b32 v2, v74, v75 offset1:1
	v_add_u32_e32 v2, 0x30c8, v7
	ds_write2_b32 v2, v76, v77 offset1:1
	v_add_u32_e32 v2, 0x34d0, v7
	ds_write2_b32 v2, v78, v79 offset1:1
	v_add_u32_e32 v2, 0x34d8, v7
	ds_write2_b32 v2, v80, v81 offset1:1
	v_add_u32_e32 v2, 0x38e0, v7
	ds_write2_b32 v2, v82, v83 offset1:1
	v_add_u32_e32 v2, 0x38e8, v7
	ds_write2_b32 v2, v84, v85 offset1:1
	v_add_u32_e32 v2, 0x3cf0, v7
	ds_write2_b32 v2, v86, v87 offset1:1
	v_add_u32_e32 v2, 0x3cf8, v7
	ds_write2_b32 v2, v88, v89 offset1:1
	s_waitcnt lgkmcnt(0)
	ds_read2_b32 v[30:31], v9 offset0:65 offset1:73
	ds_read2_b32 v[32:33], v9 offset1:8
	ds_read2_b32 v[34:35], v9 offset0:130 offset1:138
	ds_read2_b32 v[36:37], v9 offset0:195 offset1:203
	v_mov_b32_e32 v49, v3
	s_waitcnt lgkmcnt(3)
	v_bfe_u32 v25, v30, 16, 1
	s_waitcnt lgkmcnt(2)
	v_bfe_u32 v2, v32, 16, 1
	v_add3_u32 v2, v32, v2, s81
	v_lshrrev_b32_e32 v2, 16, v2
	v_add3_u32 v25, v30, v25, s81
	v_and_or_b32 v26, v25, s39, v2
	s_waitcnt lgkmcnt(1)
	v_bfe_u32 v2, v34, 16, 1
	v_add3_u32 v2, v34, v2, s81
	s_waitcnt lgkmcnt(0)
	v_bfe_u32 v25, v36, 16, 1
	v_lshrrev_b32_e32 v2, 16, v2
	v_add3_u32 v25, v36, v25, s81
	v_and_or_b32 v27, v25, s39, v2
	v_add_u32_e32 v25, 0x400, v9
	ds_read2_b32 v[38:39], v25 offset0:4 offset1:12
	ds_read2_b32 v[40:41], v25 offset0:69 offset1:77
	ds_read2_b32 v[42:43], v25 offset0:134 offset1:142
	ds_read2_b32 v[44:45], v25 offset0:199 offset1:207
	s_waitcnt lgkmcnt(3)
	v_bfe_u32 v2, v38, 16, 1
	v_add3_u32 v2, v38, v2, s81
	s_waitcnt lgkmcnt(2)
	v_bfe_u32 v28, v40, 16, 1
	v_lshrrev_b32_e32 v2, 16, v2
	v_add3_u32 v28, v40, v28, s81
	v_and_or_b32 v28, v28, s39, v2
	s_waitcnt lgkmcnt(1)
	v_bfe_u32 v2, v42, 16, 1
	v_add3_u32 v2, v42, v2, s81
	s_waitcnt lgkmcnt(0)
	v_bfe_u32 v29, v44, 16, 1
	v_lshrrev_b32_e32 v2, 16, v2
	v_add3_u32 v29, v44, v29, s81
	v_and_or_b32 v29, v29, s39, v2
	v_add_u32_e32 v2, s2, v8
	v_and_b32_e32 v30, 0xffffffc0, v2
	v_cmp_gt_i32_e32 vcc, s3, v2
	v_add_u32_e32 v30, v30, v17
	s_nop 0
	v_cndmask_b32_e32 v2, v2, v30, vcc
	v_ashrrev_i32_e32 v46, 8, v2
	v_ashrrev_i32_e32 v47, 31, v46
	v_lshlrev_b64 v[46:47], 20, v[46:47]
	v_lshlrev_b32_e32 v2, 7, v2
	v_lshl_add_u64 v[46:47], s[0:1], 0, v[46:47]
	v_and_b32_e32 v2, 0x7f80, v2
	v_lshl_add_u64 v[46:47], v[46:47], 0, v[2:3]
	v_lshlrev_b32_e32 v2, 1, v6
	v_lshl_add_u64 v[46:47], v[46:47], 0, v[2:3]
	global_store_dwordx4 v[46:47], v[26:29], off
	v_bfe_u32 v30, v45, 16, 1
	v_add3_u32 v30, v45, v30, s81
	v_bfe_u32 v26, v33, 16, 1
	v_add3_u32 v26, v33, v26, s81
	v_bfe_u32 v27, v31, 16, 1
	v_lshrrev_b32_e32 v26, 16, v26
	v_add3_u32 v27, v31, v27, s81
	v_and_or_b32 v26, v27, s39, v26
	v_bfe_u32 v27, v35, 16, 1
	v_add3_u32 v27, v35, v27, s81
	v_bfe_u32 v28, v37, 16, 1
	v_lshrrev_b32_e32 v27, 16, v27
	v_add3_u32 v28, v37, v28, s81
	v_and_or_b32 v27, v28, s39, v27
	v_bfe_u32 v28, v39, 16, 1
	v_add3_u32 v28, v39, v28, s81
	v_bfe_u32 v29, v41, 16, 1
	v_lshrrev_b32_e32 v28, 16, v28
	v_add3_u32 v29, v41, v29, s81
	v_and_or_b32 v28, v29, s39, v28
	v_bfe_u32 v29, v43, 16, 1
	v_add3_u32 v29, v43, v29, s81
	v_lshrrev_b32_e32 v29, 16, v29
	v_and_or_b32 v29, v30, s39, v29
	v_add_u32_e32 v30, s2, v10
	v_and_b32_e32 v31, 0xffffffc0, v30
	v_cmp_gt_i32_e32 vcc, s3, v30
	v_add_u32_e32 v31, v31, v18
	v_mov_b32_e32 v33, v3
	v_cndmask_b32_e32 v32, v30, v31, vcc
	v_ashrrev_i32_e32 v30, 8, v32
	v_ashrrev_i32_e32 v31, 31, v30
	v_lshlrev_b64 v[30:31], 20, v[30:31]
	v_lshlrev_b32_e32 v32, 7, v32
	v_lshl_add_u64 v[30:31], s[0:1], 0, v[30:31]
	v_and_b32_e32 v32, 0x7f80, v32
	v_lshl_add_u64 v[30:31], v[30:31], 0, v[32:33]
	v_lshl_add_u64 v[30:31], v[30:31], 0, v[2:3]
	global_store_dwordx4 v[30:31], v[26:29], off
	ds_read2_b32 v[30:31], v9 offset0:16 offset1:24
	ds_read2_b32 v[32:33], v9 offset0:81 offset1:89
	ds_read2_b32 v[34:35], v9 offset0:146 offset1:154
	ds_read2_b32 v[36:37], v9 offset0:211 offset1:219
	ds_read2_b32 v[38:39], v25 offset0:20 offset1:28
	ds_read2_b32 v[40:41], v25 offset0:85 offset1:93
	ds_read2_b32 v[42:43], v25 offset0:150 offset1:158
	ds_read2_b32 v[44:45], v25 offset0:215 offset1:223
	s_waitcnt lgkmcnt(7)
	v_bfe_u32 v26, v30, 16, 1
	v_add3_u32 v26, v30, v26, s81
	s_waitcnt lgkmcnt(6)
	v_bfe_u32 v27, v32, 16, 1
	v_lshrrev_b32_e32 v26, 16, v26
	v_add3_u32 v27, v32, v27, s81
	v_and_or_b32 v26, v27, s39, v26
	s_waitcnt lgkmcnt(5)
	v_bfe_u32 v27, v34, 16, 1
	v_add3_u32 v27, v34, v27, s81
	s_waitcnt lgkmcnt(4)
	v_bfe_u32 v28, v36, 16, 1
	v_lshrrev_b32_e32 v27, 16, v27
	v_add3_u32 v28, v36, v28, s81
	v_and_or_b32 v27, v28, s39, v27
	s_waitcnt lgkmcnt(3)
	v_bfe_u32 v28, v38, 16, 1
	v_add3_u32 v28, v38, v28, s81
	s_waitcnt lgkmcnt(2)
	v_bfe_u32 v29, v40, 16, 1
	v_lshrrev_b32_e32 v28, 16, v28
	v_add3_u32 v29, v40, v29, s81
	v_and_or_b32 v28, v29, s39, v28
	s_waitcnt lgkmcnt(1)
	v_bfe_u32 v29, v42, 16, 1
	v_add3_u32 v29, v42, v29, s81
	s_waitcnt lgkmcnt(0)
	v_bfe_u32 v30, v44, 16, 1
	v_lshrrev_b32_e32 v29, 16, v29
	v_add3_u32 v30, v44, v30, s81
	v_and_or_b32 v29, v30, s39, v29
	v_add_u32_e32 v30, s2, v11
	v_and_b32_e32 v32, 0xffffffc0, v30
	v_cmp_gt_i32_e32 vcc, s3, v30
	v_add_u32_e32 v32, v32, v19
	s_nop 0
	v_cndmask_b32_e32 v30, v30, v32, vcc
	v_ashrrev_i32_e32 v46, 8, v30
	v_ashrrev_i32_e32 v47, 31, v46
	v_lshlrev_b64 v[46:47], 20, v[46:47]
	v_lshlrev_b32_e32 v30, 7, v30
	v_lshl_add_u64 v[46:47], s[0:1], 0, v[46:47]
	v_and_b32_e32 v48, 0x7f80, v30
	v_lshl_add_u64 v[46:47], v[46:47], 0, v[48:49]
	v_lshl_add_u64 v[46:47], v[46:47], 0, v[2:3]
	global_store_dwordx4 v[46:47], v[26:29], off
	v_bfe_u32 v30, v45, 16, 1
	v_add3_u32 v30, v45, v30, s81
	v_bfe_u32 v26, v31, 16, 1
	v_add3_u32 v26, v31, v26, s81
	v_bfe_u32 v27, v33, 16, 1
	v_lshrrev_b32_e32 v26, 16, v26
	v_add3_u32 v27, v33, v27, s81
	v_and_or_b32 v26, v27, s39, v26
	v_bfe_u32 v27, v35, 16, 1
	v_add3_u32 v27, v35, v27, s81
	v_bfe_u32 v28, v37, 16, 1
	v_lshrrev_b32_e32 v27, 16, v27
	v_add3_u32 v28, v37, v28, s81
	v_and_or_b32 v27, v28, s39, v27
	v_bfe_u32 v28, v39, 16, 1
	v_add3_u32 v28, v39, v28, s81
	v_bfe_u32 v29, v41, 16, 1
	v_lshrrev_b32_e32 v28, 16, v28
	v_add3_u32 v29, v41, v29, s81
	v_and_or_b32 v28, v29, s39, v28
	v_bfe_u32 v29, v43, 16, 1
	v_add3_u32 v29, v43, v29, s81
	v_lshrrev_b32_e32 v29, 16, v29
	v_and_or_b32 v29, v30, s39, v29
	v_add_u32_e32 v30, s2, v12
	v_and_b32_e32 v31, 0xffffffc0, v30
	v_cmp_gt_i32_e32 vcc, s3, v30
	v_add_u32_e32 v31, v31, v20
	v_mov_b32_e32 v33, v3
	v_cndmask_b32_e32 v32, v30, v31, vcc
	v_ashrrev_i32_e32 v30, 8, v32
	v_ashrrev_i32_e32 v31, 31, v30
	v_lshlrev_b64 v[30:31], 20, v[30:31]
	v_lshlrev_b32_e32 v32, 7, v32
	v_lshl_add_u64 v[30:31], s[0:1], 0, v[30:31]
	v_and_b32_e32 v32, 0x7f80, v32
	v_lshl_add_u64 v[30:31], v[30:31], 0, v[32:33]
	v_lshl_add_u64 v[30:31], v[30:31], 0, v[2:3]
	global_store_dwordx4 v[30:31], v[26:29], off
	ds_read2_b32 v[30:31], v9 offset0:32 offset1:40
	ds_read2_b32 v[32:33], v9 offset0:97 offset1:105
	ds_read2_b32 v[34:35], v9 offset0:162 offset1:170
	ds_read2_b32 v[36:37], v9 offset0:227 offset1:235
	ds_read2_b32 v[38:39], v25 offset0:36 offset1:44
	ds_read2_b32 v[40:41], v25 offset0:101 offset1:109
	ds_read2_b32 v[42:43], v25 offset0:166 offset1:174
	ds_read2_b32 v[44:45], v25 offset0:231 offset1:239
	s_waitcnt lgkmcnt(7)
	v_bfe_u32 v26, v30, 16, 1
	v_add3_u32 v26, v30, v26, s81
	s_waitcnt lgkmcnt(6)
	v_bfe_u32 v27, v32, 16, 1
	v_lshrrev_b32_e32 v26, 16, v26
	v_add3_u32 v27, v32, v27, s81
	v_and_or_b32 v26, v27, s39, v26
	s_waitcnt lgkmcnt(5)
	v_bfe_u32 v27, v34, 16, 1
	v_add3_u32 v27, v34, v27, s81
	s_waitcnt lgkmcnt(4)
	v_bfe_u32 v28, v36, 16, 1
	v_lshrrev_b32_e32 v27, 16, v27
	v_add3_u32 v28, v36, v28, s81
	v_and_or_b32 v27, v28, s39, v27
	s_waitcnt lgkmcnt(3)
	v_bfe_u32 v28, v38, 16, 1
	v_add3_u32 v28, v38, v28, s81
	s_waitcnt lgkmcnt(2)
	v_bfe_u32 v29, v40, 16, 1
	v_lshrrev_b32_e32 v28, 16, v28
	v_add3_u32 v29, v40, v29, s81
	v_and_or_b32 v28, v29, s39, v28
	s_waitcnt lgkmcnt(1)
	v_bfe_u32 v29, v42, 16, 1
	v_add3_u32 v29, v42, v29, s81
	s_waitcnt lgkmcnt(0)
	v_bfe_u32 v30, v44, 16, 1
	v_lshrrev_b32_e32 v29, 16, v29
	v_add3_u32 v30, v44, v30, s81
	v_and_or_b32 v29, v30, s39, v29
	v_add_u32_e32 v30, s2, v13
	v_and_b32_e32 v32, 0xffffffc0, v30
	v_cmp_gt_i32_e32 vcc, s3, v30
	v_add_u32_e32 v32, v32, v21
	s_nop 0
	v_cndmask_b32_e32 v30, v30, v32, vcc
	v_ashrrev_i32_e32 v46, 8, v30
	v_ashrrev_i32_e32 v47, 31, v46
	v_lshlrev_b64 v[46:47], 20, v[46:47]
	v_lshlrev_b32_e32 v30, 7, v30
	v_lshl_add_u64 v[46:47], s[0:1], 0, v[46:47]
	v_and_b32_e32 v48, 0x7f80, v30
	v_lshl_add_u64 v[46:47], v[46:47], 0, v[48:49]
	v_lshl_add_u64 v[46:47], v[46:47], 0, v[2:3]
	global_store_dwordx4 v[46:47], v[26:29], off
	v_bfe_u32 v30, v45, 16, 1
	v_add3_u32 v30, v45, v30, s81
	v_bfe_u32 v26, v31, 16, 1
	v_add3_u32 v26, v31, v26, s81
	v_bfe_u32 v27, v33, 16, 1
	v_lshrrev_b32_e32 v26, 16, v26
	v_add3_u32 v27, v33, v27, s81
	v_and_or_b32 v26, v27, s39, v26
	v_bfe_u32 v27, v35, 16, 1
	v_add3_u32 v27, v35, v27, s81
	v_bfe_u32 v28, v37, 16, 1
	v_lshrrev_b32_e32 v27, 16, v27
	v_add3_u32 v28, v37, v28, s81
	v_and_or_b32 v27, v28, s39, v27
	v_bfe_u32 v28, v39, 16, 1
	v_add3_u32 v28, v39, v28, s81
	v_bfe_u32 v29, v41, 16, 1
	v_lshrrev_b32_e32 v28, 16, v28
	v_add3_u32 v29, v41, v29, s81
	v_and_or_b32 v28, v29, s39, v28
	v_bfe_u32 v29, v43, 16, 1
	v_add3_u32 v29, v43, v29, s81
	v_lshrrev_b32_e32 v29, 16, v29
	v_and_or_b32 v29, v30, s39, v29
	v_add_u32_e32 v30, s2, v14
	v_and_b32_e32 v31, 0xffffffc0, v30
	v_cmp_gt_i32_e32 vcc, s3, v30
	v_add_u32_e32 v31, v31, v22
	v_mov_b32_e32 v33, v3
	v_cndmask_b32_e32 v32, v30, v31, vcc
	v_ashrrev_i32_e32 v30, 8, v32
	v_ashrrev_i32_e32 v31, 31, v30
	v_lshlrev_b64 v[30:31], 20, v[30:31]
	v_lshlrev_b32_e32 v32, 7, v32
	v_lshl_add_u64 v[30:31], s[0:1], 0, v[30:31]
	v_and_b32_e32 v32, 0x7f80, v32
	v_lshl_add_u64 v[30:31], v[30:31], 0, v[32:33]
	v_lshl_add_u64 v[30:31], v[30:31], 0, v[2:3]
	global_store_dwordx4 v[30:31], v[26:29], off
	ds_read2_b32 v[30:31], v9 offset0:48 offset1:56
	ds_read2_b32 v[32:33], v9 offset0:113 offset1:121
	ds_read2_b32 v[34:35], v9 offset0:178 offset1:186
	ds_read2_b32 v[36:37], v9 offset0:243 offset1:251
	ds_read2_b32 v[38:39], v25 offset0:52 offset1:60
	ds_read2_b32 v[40:41], v25 offset0:117 offset1:125
	ds_read2_b32 v[42:43], v25 offset0:182 offset1:190
	ds_read2_b32 v[44:45], v25 offset0:247 offset1:255
	s_waitcnt lgkmcnt(7)
	v_bfe_u32 v26, v30, 16, 1
	v_add3_u32 v26, v30, v26, s81
	s_waitcnt lgkmcnt(6)
	v_bfe_u32 v27, v32, 16, 1
	v_lshrrev_b32_e32 v26, 16, v26
	v_add3_u32 v27, v32, v27, s81
	v_and_or_b32 v26, v27, s39, v26
	s_waitcnt lgkmcnt(5)
	v_bfe_u32 v27, v34, 16, 1
	v_add3_u32 v27, v34, v27, s81
	s_waitcnt lgkmcnt(4)
	v_bfe_u32 v28, v36, 16, 1
	v_lshrrev_b32_e32 v27, 16, v27
	v_add3_u32 v28, v36, v28, s81
	v_and_or_b32 v27, v28, s39, v27
	s_waitcnt lgkmcnt(3)
	v_bfe_u32 v28, v38, 16, 1
	v_add3_u32 v28, v38, v28, s81
	s_waitcnt lgkmcnt(2)
	v_bfe_u32 v29, v40, 16, 1
	v_lshrrev_b32_e32 v28, 16, v28
	v_add3_u32 v29, v40, v29, s81
	s_waitcnt lgkmcnt(1)
	v_bfe_u32 v25, v42, 16, 1
	v_and_or_b32 v28, v29, s39, v28
	v_add3_u32 v25, v42, v25, s81
	s_waitcnt lgkmcnt(0)
	v_bfe_u32 v29, v44, 16, 1
	v_lshrrev_b32_e32 v25, 16, v25
	v_add3_u32 v29, v44, v29, s81
	v_and_or_b32 v29, v29, s39, v25
	v_add_u32_e32 v25, s2, v15
	v_and_b32_e32 v30, 0xffffffc0, v25
	v_cmp_gt_i32_e32 vcc, s3, v25
	v_add_u32_e32 v30, v30, v23
	s_nop 0
	v_cndmask_b32_e32 v25, v25, v30, vcc
	v_ashrrev_i32_e32 v46, 8, v25
	v_ashrrev_i32_e32 v47, 31, v46
	v_lshlrev_b64 v[46:47], 20, v[46:47]
	v_lshlrev_b32_e32 v25, 7, v25
	v_lshl_add_u64 v[46:47], s[0:1], 0, v[46:47]
	v_and_b32_e32 v48, 0x7f80, v25
	v_lshl_add_u64 v[46:47], v[46:47], 0, v[48:49]
	v_lshl_add_u64 v[46:47], v[46:47], 0, v[2:3]
	v_bfe_u32 v25, v31, 16, 1
	global_store_dwordx4 v[46:47], v[26:29], off
	v_add3_u32 v25, v31, v25, s81
	v_lshrrev_b32_e32 v25, 16, v25
	v_bfe_u32 v26, v33, 16, 1
	v_add3_u32 v26, v33, v26, s81
	v_and_or_b32 v26, v26, s39, v25
	v_bfe_u32 v25, v35, 16, 1
	v_add3_u32 v25, v35, v25, s81
	v_bfe_u32 v27, v37, 16, 1
	v_lshrrev_b32_e32 v25, 16, v25
	v_add3_u32 v27, v37, v27, s81
	v_and_or_b32 v27, v27, s39, v25
	v_bfe_u32 v25, v39, 16, 1
	v_add3_u32 v25, v39, v25, s81
	v_bfe_u32 v28, v41, 16, 1
	v_lshrrev_b32_e32 v25, 16, v25
	v_add3_u32 v28, v41, v28, s81
	v_and_or_b32 v28, v28, s39, v25
	v_bfe_u32 v25, v43, 16, 1
	v_add3_u32 v25, v43, v25, s81
	v_bfe_u32 v29, v45, 16, 1
	v_lshrrev_b32_e32 v25, 16, v25
	v_add3_u32 v29, v45, v29, s81
	v_and_or_b32 v29, v29, s39, v25
	v_add_u32_e32 v25, s2, v16
	v_and_b32_e32 v30, 0xffffffc0, v25
	v_cmp_gt_i32_e32 vcc, s3, v25
	v_add_u32_e32 v30, v30, v24
	v_mov_b32_e32 v33, v3
	v_cndmask_b32_e32 v25, v25, v30, vcc
	v_ashrrev_i32_e32 v30, 8, v25
	v_ashrrev_i32_e32 v31, 31, v30
	v_lshlrev_b64 v[30:31], 20, v[30:31]
	v_lshlrev_b32_e32 v25, 7, v25
	v_lshl_add_u64 v[30:31], s[0:1], 0, v[30:31]
	v_and_b32_e32 v32, 0x7f80, v25
	v_lshl_add_u64 v[30:31], v[30:31], 0, v[32:33]
	v_lshl_add_u64 v[30:31], v[30:31], 0, v[2:3]
	global_store_dwordx4 v[30:31], v[26:29], off
	s_waitcnt lgkmcnt(0)

.LBB0_960:
	s_andn2_b64 vcc, exec, s[0:1]
	s_cbranch_vccnz .LBB0_962
	s_load_dwordx2 s[2:3], s[6:7], 0x48
	s_add_i32 s0, s20, 0x6200
	s_and_b32 s23, s0, 0x1fc0
	s_add_i32 s0, s18, 0xfffa8000
	s_and_b32 s0, s0, 0x7c0
	s_add_i32 s1, s22, 0xffffea00
	v_add_u32_e32 v26, s23, v5
	s_lshl_b32 s23, s0, 2
	s_waitcnt lgkmcnt(0)
	s_add_u32 s2, s2, s23
	s_addc_u32 s3, s3, 0
	v_lshlrev_b32_e32 v2, 2, v4
	v_ashrrev_i32_e32 v27, 31, v26
	v_lshl_add_u64 v[28:29], s[2:3], 0, v[2:3]
	v_lshlrev_b64 v[26:27], 13, v[26:27]
	v_lshl_add_u64 v[86:87], v[28:29], 0, v[26:27]
	v_add_co_u32_e32 v26, vcc, s42, v86
	v_add_u32_e32 v2, 0x410, v7
	s_nop 0
	v_addc_co_u32_e32 v27, vcc, 0, v87, vcc
	v_add_co_u32_e32 v30, vcc, s43, v86
	s_lshr_b32 s72, s1, 5
	s_nop 0
	v_addc_co_u32_e32 v31, vcc, 0, v87, vcc
	v_add_co_u32_e32 v34, vcc, s44, v86
	global_load_dwordx4 v[26:29], v[26:27], off nt
	s_nop 0
	global_load_dwordx4 v[30:33], v[30:31], off nt
	v_addc_co_u32_e32 v35, vcc, 0, v87, vcc
	v_add_co_u32_e32 v38, vcc, s46, v86
	s_nop 1
	v_addc_co_u32_e32 v39, vcc, 0, v87, vcc
	global_load_dwordx4 v[34:37], v[34:35], off nt
	s_nop 0
	global_load_dwordx4 v[38:41], v[38:39], off nt
	v_add_co_u32_e32 v42, vcc, s49, v86
	s_nop 1
	v_addc_co_u32_e32 v43, vcc, 0, v87, vcc
	v_add_co_u32_e32 v46, vcc, s50, v86
	s_nop 1
	v_addc_co_u32_e32 v47, vcc, 0, v87, vcc
	global_load_dwordx4 v[42:45], v[42:43], off nt
	s_nop 0
	global_load_dwordx4 v[46:49], v[46:47], off nt
	v_add_co_u32_e32 v50, vcc, s53, v86
	s_nop 1
	v_addc_co_u32_e32 v51, vcc, 0, v87, vcc
	v_add_co_u32_e32 v54, vcc, s55, v86
	s_nop 1
	v_addc_co_u32_e32 v55, vcc, 0, v87, vcc
	global_load_dwordx4 v[50:53], v[50:51], off nt
	s_nop 0
	global_load_dwordx4 v[54:57], v[54:55], off nt
	v_add_co_u32_e32 v58, vcc, s56, v86
	s_nop 1
	v_addc_co_u32_e32 v59, vcc, 0, v87, vcc
	v_add_co_u32_e32 v62, vcc, s57, v86
	s_nop 1
	v_addc_co_u32_e32 v63, vcc, 0, v87, vcc
	global_load_dwordx4 v[58:61], v[58:59], off nt
	s_nop 0
	global_load_dwordx4 v[62:65], v[62:63], off nt
	v_add_co_u32_e32 v66, vcc, s58, v86
	s_nop 1
	v_addc_co_u32_e32 v67, vcc, 0, v87, vcc
	v_add_co_u32_e32 v70, vcc, s61, v86
	s_nop 1
	v_addc_co_u32_e32 v71, vcc, 0, v87, vcc
	global_load_dwordx4 v[66:69], v[66:67], off nt
	s_nop 0
	global_load_dwordx4 v[70:73], v[70:71], off nt
	v_add_co_u32_e32 v74, vcc, s62, v86
	s_nop 1
	v_addc_co_u32_e32 v75, vcc, 0, v87, vcc
	global_load_dwordx4 v[74:77], v[74:75], off nt
	v_add_co_u32_e32 v78, vcc, s63, v86
	s_nop 1
	v_addc_co_u32_e32 v79, vcc, 0, v87, vcc
	global_load_dwordx4 v[78:81], v[78:79], off nt
	v_add_co_u32_e32 v82, vcc, s64, v86
	s_nop 1
	v_addc_co_u32_e32 v83, vcc, 0, v87, vcc
	global_load_dwordx4 v[82:85], v[82:83], off nt
	v_add_co_u32_e32 v86, vcc, s65, v86
	s_nop 1
	v_addc_co_u32_e32 v87, vcc, 0, v87, vcc
	global_load_dwordx4 v[86:89], v[86:87], off nt
	s_waitcnt vmcnt(0)
	ds_write2_b32 v7, v26, v27 offset1:1
	ds_write2_b32 v7, v28, v29 offset0:2 offset1:3
	ds_write2_b32 v2, v30, v31 offset1:1
	v_add_u32_e32 v2, 0x418, v7
	ds_write2_b32 v2, v32, v33 offset1:1
	v_add_u32_e32 v2, 0x820, v7
	ds_write2_b32 v2, v34, v35 offset1:1
	v_add_u32_e32 v2, 0x828, v7
	ds_write2_b32 v2, v36, v37 offset1:1
	v_add_u32_e32 v2, 0xc30, v7
	ds_write2_b32 v2, v38, v39 offset1:1
	v_add_u32_e32 v2, 0xc38, v7
	ds_write2_b32 v2, v40, v41 offset1:1
	v_add_u32_e32 v2, 0x1040, v7
	ds_write2_b32 v2, v42, v43 offset1:1
	v_add_u32_e32 v2, 0x1048, v7
	ds_write2_b32 v2, v44, v45 offset1:1
	v_add_u32_e32 v2, 0x1450, v7
	ds_write2_b32 v2, v46, v47 offset1:1
	v_add_u32_e32 v2, 0x1458, v7
	ds_write2_b32 v2, v48, v49 offset1:1
	v_add_u32_e32 v2, 0x1860, v7
	v_mov_b32_e32 v49, v3
	ds_write2_b32 v2, v50, v51 offset1:1
	v_add_u32_e32 v2, 0x1868, v7
	ds_write2_b32 v2, v52, v53 offset1:1
	v_add_u32_e32 v2, 0x1c70, v7
	ds_write2_b32 v2, v54, v55 offset1:1
	v_add_u32_e32 v2, 0x1c78, v7
	ds_write2_b32 v2, v56, v57 offset1:1
	v_add_u32_e32 v2, 0x2080, v7
	ds_write2_b32 v2, v58, v59 offset1:1
	v_add_u32_e32 v2, 0x2088, v7
	ds_write2_b32 v2, v60, v61 offset1:1
	v_add_u32_e32 v2, 0x2490, v7
	ds_write2_b32 v2, v62, v63 offset1:1
	v_add_u32_e32 v2, 0x2498, v7
	ds_write2_b32 v2, v64, v65 offset1:1
	v_add_u32_e32 v2, 0x28a0, v7
	ds_write2_b32 v2, v66, v67 offset1:1
	v_add_u32_e32 v2, 0x28a8, v7
	ds_write2_b32 v2, v68, v69 offset1:1
	v_add_u32_e32 v2, 0x2cb0, v7
	ds_write2_b32 v2, v70, v71 offset1:1
	v_add_u32_e32 v2, 0x2cb8, v7
	ds_write2_b32 v2, v72, v73 offset1:1
	v_add_u32_e32 v2, 0x30c0, v7
	ds_write2_b32 v2, v74, v75 offset1:1
	v_add_u32_e32 v2, 0x30c8, v7
	ds_write2_b32 v2, v76, v77 offset1:1
	v_add_u32_e32 v2, 0x34d0, v7
	ds_write2_b32 v2, v78, v79 offset1:1
	v_add_u32_e32 v2, 0x34d8, v7
	ds_write2_b32 v2, v80, v81 offset1:1
	v_add_u32_e32 v2, 0x38e0, v7
	ds_write2_b32 v2, v82, v83 offset1:1
	v_add_u32_e32 v2, 0x38e8, v7
	ds_write2_b32 v2, v84, v85 offset1:1
	v_add_u32_e32 v2, 0x3cf0, v7
	ds_write2_b32 v2, v86, v87 offset1:1
	v_add_u32_e32 v2, 0x3cf8, v7
	ds_write2_b32 v2, v88, v89 offset1:1
	s_waitcnt lgkmcnt(0)
	ds_read2_b32 v[30:31], v9 offset1:8
	ds_read2_b32 v[32:33], v9 offset0:65 offset1:73
	ds_read2_b32 v[34:35], v9 offset0:130 offset1:138
	ds_read2_b32 v[36:37], v9 offset0:195 offset1:203
	s_waitcnt lgkmcnt(3)
	v_bfe_u32 v2, v30, 16, 1
	v_add3_u32 v2, v30, v2, s81
	s_waitcnt lgkmcnt(2)
	v_bfe_u32 v25, v32, 16, 1
	v_lshrrev_b32_e32 v2, 16, v2
	v_add3_u32 v25, v32, v25, s81
	v_and_or_b32 v26, v25, s39, v2
	v_add_u32_e32 v25, 0x400, v9
	ds_read2_b32 v[38:39], v25 offset0:4 offset1:12
	ds_read2_b32 v[40:41], v25 offset0:69 offset1:77
	s_waitcnt lgkmcnt(3)
	v_bfe_u32 v2, v34, 16, 1
	v_add3_u32 v2, v34, v2, s81
	s_waitcnt lgkmcnt(2)
	v_bfe_u32 v27, v36, 16, 1
	ds_read2_b32 v[42:43], v25 offset0:134 offset1:142
	v_lshrrev_b32_e32 v2, 16, v2
	v_add3_u32 v27, v36, v27, s81
	ds_read2_b32 v[44:45], v25 offset0:199 offset1:207
	v_and_or_b32 v27, v27, s39, v2
	s_waitcnt lgkmcnt(3)
	v_bfe_u32 v2, v38, 16, 1
	v_add3_u32 v2, v38, v2, s81
	s_waitcnt lgkmcnt(2)
	v_bfe_u32 v28, v40, 16, 1
	v_lshrrev_b32_e32 v2, 16, v2
	v_add3_u32 v28, v40, v28, s81
	v_and_or_b32 v28, v28, s39, v2
	s_waitcnt lgkmcnt(1)
	v_bfe_u32 v2, v42, 16, 1
	v_add3_u32 v2, v42, v2, s81
	s_waitcnt lgkmcnt(0)
	v_bfe_u32 v29, v44, 16, 1
	v_lshrrev_b32_e32 v2, 16, v2
	v_add3_u32 v29, v44, v29, s81
	v_and_or_b32 v29, v29, s39, v2
	v_add_u32_e32 v2, s0, v8
	v_lshrrev_b32_e32 v30, 8, v2
	v_mul_i32_i24_e32 v46, 0x58, v30
	v_ashrrev_i32_e32 v47, 31, v46
	v_lshl_add_u64 v[46:47], v[46:47], 0, s[72:73]
	v_lshlrev_b64 v[46:47], 15, v[46:47]
	v_lshlrev_b32_e32 v2, 7, v2
	v_lshl_add_u64 v[46:47], s[12:13], 0, v[46:47]
	v_and_b32_e32 v2, 0x7f80, v2
	v_lshl_add_u64 v[46:47], v[46:47], 0, v[2:3]
	v_lshlrev_b32_e32 v2, 1, v6
	v_lshl_add_u64 v[46:47], v[46:47], 0, v[2:3]
	global_store_dwordx4 v[46:47], v[26:29], off
	v_bfe_u32 v30, v45, 16, 1
	v_add3_u32 v30, v45, v30, s81
	v_bfe_u32 v26, v31, 16, 1
	v_add3_u32 v26, v31, v26, s81
	v_bfe_u32 v27, v33, 16, 1
	v_lshrrev_b32_e32 v26, 16, v26
	v_add3_u32 v27, v33, v27, s81
	v_and_or_b32 v26, v27, s39, v26
	v_bfe_u32 v27, v35, 16, 1
	v_add3_u32 v27, v35, v27, s81
	v_bfe_u32 v28, v37, 16, 1
	v_lshrrev_b32_e32 v27, 16, v27
	v_add3_u32 v28, v37, v28, s81
	v_and_or_b32 v27, v28, s39, v27
	v_bfe_u32 v28, v39, 16, 1
	v_add3_u32 v28, v39, v28, s81
	v_bfe_u32 v29, v41, 16, 1
	v_lshrrev_b32_e32 v28, 16, v28
	v_add3_u32 v29, v41, v29, s81
	v_and_or_b32 v28, v29, s39, v28
	v_bfe_u32 v29, v43, 16, 1
	v_add3_u32 v29, v43, v29, s81
	v_lshrrev_b32_e32 v29, 16, v29
	v_add_u32_e32 v32, s0, v10
	v_and_or_b32 v29, v30, s39, v29
	v_lshrrev_b32_e32 v30, 8, v32
	v_mul_i32_i24_e32 v30, 0x58, v30
	v_ashrrev_i32_e32 v31, 31, v30
	v_lshl_add_u64 v[30:31], v[30:31], 0, s[72:73]
	v_lshlrev_b64 v[30:31], 15, v[30:31]
	v_lshlrev_b32_e32 v32, 7, v32
	v_lshl_add_u64 v[30:31], s[12:13], 0, v[30:31]
	v_and_b32_e32 v32, 0x7f80, v32
	v_mov_b32_e32 v33, v3
	v_lshl_add_u64 v[30:31], v[30:31], 0, v[32:33]
	ds_read2_b32 v[34:35], v9 offset0:16 offset1:24
	v_lshl_add_u64 v[30:31], v[30:31], 0, v[2:3]
	global_store_dwordx4 v[30:31], v[26:29], off
	ds_read2_b32 v[30:31], v9 offset0:81 offset1:89
	ds_read2_b32 v[32:33], v9 offset0:146 offset1:154
	ds_read2_b32 v[36:37], v9 offset0:211 offset1:219
	s_waitcnt lgkmcnt(3)
	v_bfe_u32 v26, v34, 16, 1
	v_add3_u32 v26, v34, v26, s81
	s_waitcnt lgkmcnt(2)
	v_bfe_u32 v27, v30, 16, 1
	ds_read2_b32 v[38:39], v25 offset0:20 offset1:28
	v_lshrrev_b32_e32 v26, 16, v26
	v_add3_u32 v27, v30, v27, s81
	ds_read2_b32 v[40:41], v25 offset0:85 offset1:93
	v_and_or_b32 v26, v27, s39, v26
	s_waitcnt lgkmcnt(3)
	v_bfe_u32 v27, v32, 16, 1
	v_add3_u32 v27, v32, v27, s81
	s_waitcnt lgkmcnt(2)
	v_bfe_u32 v28, v36, 16, 1
	ds_read2_b32 v[42:43], v25 offset0:150 offset1:158
	v_lshrrev_b32_e32 v27, 16, v27
	v_add3_u32 v28, v36, v28, s81
	ds_read2_b32 v[44:45], v25 offset0:215 offset1:223
	v_and_or_b32 v27, v28, s39, v27
	s_waitcnt lgkmcnt(3)
	v_bfe_u32 v28, v38, 16, 1
	v_add3_u32 v28, v38, v28, s81
	s_waitcnt lgkmcnt(2)
	v_bfe_u32 v29, v40, 16, 1
	v_lshrrev_b32_e32 v28, 16, v28
	v_add3_u32 v29, v40, v29, s81
	v_and_or_b32 v28, v29, s39, v28
	s_waitcnt lgkmcnt(1)
	v_bfe_u32 v29, v42, 16, 1
	v_add3_u32 v29, v42, v29, s81
	s_waitcnt lgkmcnt(0)
	v_bfe_u32 v30, v44, 16, 1
	v_lshrrev_b32_e32 v29, 16, v29
	v_add3_u32 v30, v44, v30, s81
	v_and_or_b32 v29, v30, s39, v29
	v_add_u32_e32 v30, s0, v11
	v_lshrrev_b32_e32 v32, 8, v30
	v_mul_i32_i24_e32 v46, 0x58, v32
	v_ashrrev_i32_e32 v47, 31, v46
	v_lshl_add_u64 v[46:47], v[46:47], 0, s[72:73]
	v_lshlrev_b64 v[46:47], 15, v[46:47]
	v_lshlrev_b32_e32 v30, 7, v30
	v_lshl_add_u64 v[46:47], s[12:13], 0, v[46:47]
	v_and_b32_e32 v48, 0x7f80, v30
	v_lshl_add_u64 v[46:47], v[46:47], 0, v[48:49]
	v_lshl_add_u64 v[46:47], v[46:47], 0, v[2:3]
	global_store_dwordx4 v[46:47], v[26:29], off
	v_bfe_u32 v30, v45, 16, 1
	v_add3_u32 v30, v45, v30, s81
	v_bfe_u32 v26, v35, 16, 1
	v_add3_u32 v26, v35, v26, s81
	v_bfe_u32 v27, v31, 16, 1
	v_lshrrev_b32_e32 v26, 16, v26
	v_add3_u32 v27, v31, v27, s81
	v_and_or_b32 v26, v27, s39, v26
	v_bfe_u32 v27, v33, 16, 1
	v_add3_u32 v27, v33, v27, s81
	v_bfe_u32 v28, v37, 16, 1
	v_lshrrev_b32_e32 v27, 16, v27
	v_add3_u32 v28, v37, v28, s81
	v_and_or_b32 v27, v28, s39, v27
	v_bfe_u32 v28, v39, 16, 1
	v_add3_u32 v28, v39, v28, s81
	v_bfe_u32 v29, v41, 16, 1
	v_lshrrev_b32_e32 v28, 16, v28
	v_add3_u32 v29, v41, v29, s81
	v_and_or_b32 v28, v29, s39, v28
	v_bfe_u32 v29, v43, 16, 1
	v_add3_u32 v29, v43, v29, s81
	v_lshrrev_b32_e32 v29, 16, v29
	v_add_u32_e32 v32, s0, v12
	v_and_or_b32 v29, v30, s39, v29
	v_lshrrev_b32_e32 v30, 8, v32
	v_mul_i32_i24_e32 v30, 0x58, v30
	v_ashrrev_i32_e32 v31, 31, v30
	v_lshl_add_u64 v[30:31], v[30:31], 0, s[72:73]
	v_lshlrev_b64 v[30:31], 15, v[30:31]
	v_lshlrev_b32_e32 v32, 7, v32
	v_lshl_add_u64 v[30:31], s[12:13], 0, v[30:31]
	v_and_b32_e32 v32, 0x7f80, v32
	v_mov_b32_e32 v33, v3
	v_lshl_add_u64 v[30:31], v[30:31], 0, v[32:33]
	ds_read2_b32 v[34:35], v9 offset0:32 offset1:40
	v_lshl_add_u64 v[30:31], v[30:31], 0, v[2:3]
	global_store_dwordx4 v[30:31], v[26:29], off
	ds_read2_b32 v[30:31], v9 offset0:97 offset1:105
	ds_read2_b32 v[32:33], v9 offset0:162 offset1:170
	ds_read2_b32 v[36:37], v9 offset0:227 offset1:235
	s_waitcnt lgkmcnt(3)
	v_bfe_u32 v26, v34, 16, 1
	v_add3_u32 v26, v34, v26, s81
	s_waitcnt lgkmcnt(2)
	v_bfe_u32 v27, v30, 16, 1
	ds_read2_b32 v[38:39], v25 offset0:36 offset1:44
	v_lshrrev_b32_e32 v26, 16, v26
	v_add3_u32 v27, v30, v27, s81
	ds_read2_b32 v[40:41], v25 offset0:101 offset1:109
	v_and_or_b32 v26, v27, s39, v26
	s_waitcnt lgkmcnt(3)
	v_bfe_u32 v27, v32, 16, 1
	v_add3_u32 v27, v32, v27, s81
	s_waitcnt lgkmcnt(2)
	v_bfe_u32 v28, v36, 16, 1
	ds_read2_b32 v[42:43], v25 offset0:166 offset1:174
	v_lshrrev_b32_e32 v27, 16, v27
	v_add3_u32 v28, v36, v28, s81
	ds_read2_b32 v[44:45], v25 offset0:231 offset1:239
	v_and_or_b32 v27, v28, s39, v27
	s_waitcnt lgkmcnt(3)
	v_bfe_u32 v28, v38, 16, 1
	v_add3_u32 v28, v38, v28, s81
	s_waitcnt lgkmcnt(2)
	v_bfe_u32 v29, v40, 16, 1
	v_lshrrev_b32_e32 v28, 16, v28
	v_add3_u32 v29, v40, v29, s81
	v_and_or_b32 v28, v29, s39, v28
	s_waitcnt lgkmcnt(1)
	v_bfe_u32 v29, v42, 16, 1
	v_add3_u32 v29, v42, v29, s81
	s_waitcnt lgkmcnt(0)
	v_bfe_u32 v30, v44, 16, 1
	v_lshrrev_b32_e32 v29, 16, v29
	v_add3_u32 v30, v44, v30, s81
	v_and_or_b32 v29, v30, s39, v29
	v_add_u32_e32 v30, s0, v13
	v_lshrrev_b32_e32 v32, 8, v30
	v_mul_i32_i24_e32 v46, 0x58, v32
	v_ashrrev_i32_e32 v47, 31, v46
	v_lshl_add_u64 v[46:47], v[46:47], 0, s[72:73]
	v_lshlrev_b64 v[46:47], 15, v[46:47]
	v_lshlrev_b32_e32 v30, 7, v30
	v_lshl_add_u64 v[46:47], s[12:13], 0, v[46:47]
	v_and_b32_e32 v48, 0x7f80, v30
	v_lshl_add_u64 v[46:47], v[46:47], 0, v[48:49]
	v_lshl_add_u64 v[46:47], v[46:47], 0, v[2:3]
	global_store_dwordx4 v[46:47], v[26:29], off
	v_bfe_u32 v30, v45, 16, 1
	v_add3_u32 v30, v45, v30, s81
	v_bfe_u32 v26, v35, 16, 1
	v_add3_u32 v26, v35, v26, s81
	v_bfe_u32 v27, v31, 16, 1
	v_lshrrev_b32_e32 v26, 16, v26
	v_add3_u32 v27, v31, v27, s81
	v_and_or_b32 v26, v27, s39, v26
	v_bfe_u32 v27, v33, 16, 1
	v_add3_u32 v27, v33, v27, s81
	v_bfe_u32 v28, v37, 16, 1
	v_lshrrev_b32_e32 v27, 16, v27
	v_add3_u32 v28, v37, v28, s81
	v_and_or_b32 v27, v28, s39, v27
	v_bfe_u32 v28, v39, 16, 1
	v_add3_u32 v28, v39, v28, s81
	v_bfe_u32 v29, v41, 16, 1
	v_lshrrev_b32_e32 v28, 16, v28
	v_add3_u32 v29, v41, v29, s81
	v_and_or_b32 v28, v29, s39, v28
	v_bfe_u32 v29, v43, 16, 1
	v_add3_u32 v29, v43, v29, s81
	v_lshrrev_b32_e32 v29, 16, v29
	v_add_u32_e32 v32, s0, v14
	v_and_or_b32 v29, v30, s39, v29
	v_lshrrev_b32_e32 v30, 8, v32
	v_mul_i32_i24_e32 v30, 0x58, v30
	v_ashrrev_i32_e32 v31, 31, v30
	v_lshl_add_u64 v[30:31], v[30:31], 0, s[72:73]
	v_lshlrev_b64 v[30:31], 15, v[30:31]
	v_lshlrev_b32_e32 v32, 7, v32
	v_lshl_add_u64 v[30:31], s[12:13], 0, v[30:31]
	v_and_b32_e32 v32, 0x7f80, v32
	v_mov_b32_e32 v33, v3
	v_lshl_add_u64 v[30:31], v[30:31], 0, v[32:33]
	ds_read2_b32 v[34:35], v9 offset0:48 offset1:56
	v_lshl_add_u64 v[30:31], v[30:31], 0, v[2:3]
	global_store_dwordx4 v[30:31], v[26:29], off
	ds_read2_b32 v[30:31], v9 offset0:113 offset1:121
	ds_read2_b32 v[32:33], v9 offset0:178 offset1:186
	ds_read2_b32 v[36:37], v9 offset0:243 offset1:251
	s_waitcnt lgkmcnt(3)
	v_bfe_u32 v26, v34, 16, 1
	v_add3_u32 v26, v34, v26, s81
	s_waitcnt lgkmcnt(2)
	v_bfe_u32 v27, v30, 16, 1
	ds_read2_b32 v[38:39], v25 offset0:52 offset1:60
	v_lshrrev_b32_e32 v26, 16, v26
	v_add3_u32 v27, v30, v27, s81
	ds_read2_b32 v[40:41], v25 offset0:117 offset1:125
	v_and_or_b32 v26, v27, s39, v26
	s_waitcnt lgkmcnt(3)
	v_bfe_u32 v27, v32, 16, 1
	ds_read2_b32 v[42:43], v25 offset0:182 offset1:190
	v_add3_u32 v27, v32, v27, s81
	s_waitcnt lgkmcnt(3)
	v_bfe_u32 v28, v36, 16, 1
	ds_read2_b32 v[44:45], v25 offset0:247 offset1:255
	v_lshrrev_b32_e32 v27, 16, v27
	v_add3_u32 v28, v36, v28, s81
	v_and_or_b32 v27, v28, s39, v27
	s_waitcnt lgkmcnt(3)
	v_bfe_u32 v28, v38, 16, 1
	v_add3_u32 v28, v38, v28, s81
	s_waitcnt lgkmcnt(2)
	v_bfe_u32 v29, v40, 16, 1
	v_lshrrev_b32_e32 v28, 16, v28
	v_add3_u32 v29, v40, v29, s81
	s_waitcnt lgkmcnt(1)
	v_bfe_u32 v25, v42, 16, 1
	v_and_or_b32 v28, v29, s39, v28
	v_add3_u32 v25, v42, v25, s81
	s_waitcnt lgkmcnt(0)
	v_bfe_u32 v29, v44, 16, 1
	v_lshrrev_b32_e32 v25, 16, v25
	v_add3_u32 v29, v44, v29, s81
	v_and_or_b32 v29, v29, s39, v25
	v_add_u32_e32 v25, s0, v15
	v_lshrrev_b32_e32 v30, 8, v25
	v_mul_i32_i24_e32 v46, 0x58, v30
	v_ashrrev_i32_e32 v47, 31, v46
	v_lshl_add_u64 v[46:47], v[46:47], 0, s[72:73]
	v_lshlrev_b64 v[46:47], 15, v[46:47]
	v_lshlrev_b32_e32 v25, 7, v25
	v_lshl_add_u64 v[46:47], s[12:13], 0, v[46:47]
	v_and_b32_e32 v48, 0x7f80, v25
	v_lshl_add_u64 v[46:47], v[46:47], 0, v[48:49]
	v_lshl_add_u64 v[46:47], v[46:47], 0, v[2:3]
	v_bfe_u32 v25, v35, 16, 1
	global_store_dwordx4 v[46:47], v[26:29], off
	v_add3_u32 v25, v35, v25, s81
	v_lshrrev_b32_e32 v25, 16, v25
	v_bfe_u32 v26, v31, 16, 1
	v_add3_u32 v26, v31, v26, s81
	v_and_or_b32 v26, v26, s39, v25
	v_bfe_u32 v25, v33, 16, 1
	v_add3_u32 v25, v33, v25, s81
	v_bfe_u32 v27, v37, 16, 1
	v_lshrrev_b32_e32 v25, 16, v25
	v_add3_u32 v27, v37, v27, s81
	v_and_or_b32 v27, v27, s39, v25
	v_bfe_u32 v25, v39, 16, 1
	v_add3_u32 v25, v39, v25, s81
	v_bfe_u32 v28, v41, 16, 1
	v_lshrrev_b32_e32 v25, 16, v25
	v_add3_u32 v28, v41, v28, s81
	v_and_or_b32 v28, v28, s39, v25
	v_bfe_u32 v25, v43, 16, 1
	v_add3_u32 v25, v43, v25, s81
	v_bfe_u32 v29, v45, 16, 1
	v_lshrrev_b32_e32 v25, 16, v25
	v_add3_u32 v29, v45, v29, s81
	v_and_or_b32 v29, v29, s39, v25
	v_add_u32_e32 v25, s0, v16
	v_lshrrev_b32_e32 v30, 8, v25
	v_mul_i32_i24_e32 v30, 0x58, v30
	v_ashrrev_i32_e32 v31, 31, v30
	v_lshl_add_u64 v[30:31], v[30:31], 0, s[72:73]
	v_lshlrev_b64 v[30:31], 15, v[30:31]
	v_lshlrev_b32_e32 v25, 7, v25
	v_lshl_add_u64 v[30:31], s[12:13], 0, v[30:31]
	v_and_b32_e32 v32, 0x7f80, v25
	v_mov_b32_e32 v33, v3
	v_lshl_add_u64 v[30:31], v[30:31], 0, v[32:33]
	v_lshl_add_u64 v[30:31], v[30:31], 0, v[2:3]
	global_store_dwordx4 v[30:31], v[26:29], off
	s_waitcnt lgkmcnt(0)

.LBB0_963:
	s_andn2_b64 vcc, exec, s[0:1]
	s_cbranch_vccnz .LBB0_944
	s_mul_hi_i32 s2, s22, 0x2e8ba2e9
	s_lshr_b32 s3, s2, 31
	s_ashr_i32 s2, s2, 5
	s_load_dwordx2 s[0:1], s[6:7], 0x40
	s_add_i32 s2, s2, s3
	s_mul_i32 s23, s2, 0xffffd400
	s_add_i32 s24, s18, s23
	s_ashr_i32 s25, s24, 31
	s_lshl_b64 s[24:25], s[24:25], 2
	s_waitcnt lgkmcnt(0)
	s_add_u32 s0, s0, s24
	s_addc_u32 s1, s1, s25
	v_lshlrev_b32_e32 v2, 2, v4
	v_lshl_add_u32 v25, s2, 6, v5
	v_lshl_add_u64 v[26:27], s[0:1], 0, v[2:3]
	s_mov_b64 s[0:1], 0x5800000
	v_lshl_add_u64 v[86:87], v[26:27], 0, s[0:1]
	v_add_u32_e32 v2, 4, v25
	v_mad_i64_i32 v[26:27], s[0:1], v25, s59, v[86:87]
	v_mad_i64_i32 v[30:31], s[0:1], v2, s59, v[86:87]
	global_load_dwordx4 v[26:29], v[26:27], off nt
	v_add_u32_e32 v2, 8, v25
	global_load_dwordx4 v[30:33], v[30:31], off nt
	v_mad_i64_i32 v[34:35], s[0:1], v2, s59, v[86:87]
	global_load_dwordx4 v[34:37], v[34:35], off nt
	v_add_u32_e32 v2, 12, v25
	v_mad_i64_i32 v[38:39], s[0:1], v2, s59, v[86:87]
	global_load_dwordx4 v[38:41], v[38:39], off nt
	v_add_u32_e32 v2, 16, v25
	v_mad_i64_i32 v[42:43], s[0:1], v2, s59, v[86:87]
	global_load_dwordx4 v[42:45], v[42:43], off nt
	v_add_u32_e32 v2, 20, v25
	v_mad_i64_i32 v[46:47], s[0:1], v2, s59, v[86:87]
	global_load_dwordx4 v[46:49], v[46:47], off nt
	v_add_u32_e32 v2, 24, v25
	v_mad_i64_i32 v[50:51], s[0:1], v2, s59, v[86:87]
	global_load_dwordx4 v[50:53], v[50:51], off nt
	v_add_u32_e32 v2, 28, v25
	v_mad_i64_i32 v[54:55], s[0:1], v2, s59, v[86:87]
	global_load_dwordx4 v[54:57], v[54:55], off nt
	v_add_u32_e32 v2, 32, v25
	v_mad_i64_i32 v[58:59], s[0:1], v2, s59, v[86:87]
	global_load_dwordx4 v[58:61], v[58:59], off nt
	v_add_u32_e32 v2, 36, v25
	v_mad_i64_i32 v[62:63], s[0:1], v2, s59, v[86:87]
	global_load_dwordx4 v[62:65], v[62:63], off nt
	v_add_u32_e32 v2, 40, v25
	v_mad_i64_i32 v[66:67], s[0:1], v2, s59, v[86:87]
	global_load_dwordx4 v[66:69], v[66:67], off nt
	v_add_u32_e32 v2, 44, v25
	v_mad_i64_i32 v[70:71], s[0:1], v2, s59, v[86:87]
	global_load_dwordx4 v[70:73], v[70:71], off nt
	v_add_u32_e32 v2, 48, v25
	v_mad_i64_i32 v[74:75], s[0:1], v2, s59, v[86:87]
	global_load_dwordx4 v[74:77], v[74:75], off nt
	v_add_u32_e32 v2, 52, v25
	v_mad_i64_i32 v[78:79], s[0:1], v2, s59, v[86:87]
	global_load_dwordx4 v[78:81], v[78:79], off nt
	v_add_u32_e32 v2, 56, v25
	v_mad_i64_i32 v[82:83], s[0:1], v2, s59, v[86:87]
	global_load_dwordx4 v[82:85], v[82:83], off nt
	v_add_u32_e32 v2, 60, v25
	v_mad_i64_i32 v[86:87], s[0:1], v2, s59, v[86:87]
	global_load_dwordx4 v[86:89], v[86:87], off nt
	v_add_u32_e32 v2, 0x410, v7
	s_ashr_i32 s3, s2, 31
	s_lshl_b64 s[0:1], s[2:3], 15
	s_mulk_i32 s2, 0x2c00
	s_add_u32 s0, s4, s0
	s_addc_u32 s1, s5, s1
	s_waitcnt vmcnt(0)
	ds_write2_b32 v7, v26, v27 offset1:1
	ds_write2_b32 v7, v28, v29 offset0:2 offset1:3
	v_add_u32_e32 v27, 0x400, v9
	ds_write2_b32 v2, v30, v31 offset1:1
	v_add_u32_e32 v2, 0x418, v7
	ds_write2_b32 v2, v32, v33 offset1:1
	v_add_u32_e32 v2, 0x820, v7
	ds_write2_b32 v2, v34, v35 offset1:1
	v_add_u32_e32 v2, 0x828, v7
	ds_write2_b32 v2, v36, v37 offset1:1
	v_add_u32_e32 v2, 0xc30, v7
	ds_write2_b32 v2, v38, v39 offset1:1
	v_add_u32_e32 v2, 0xc38, v7
	ds_write2_b32 v2, v40, v41 offset1:1
	v_add_u32_e32 v2, 0x1040, v7
	ds_write2_b32 v2, v42, v43 offset1:1
	v_add_u32_e32 v2, 0x1048, v7
	ds_write2_b32 v2, v44, v45 offset1:1
	v_add_u32_e32 v2, 0x1450, v7
	ds_write2_b32 v2, v46, v47 offset1:1
	v_add_u32_e32 v2, 0x1458, v7
	ds_write2_b32 v2, v48, v49 offset1:1
	v_add_u32_e32 v2, 0x1860, v7
	ds_write2_b32 v2, v50, v51 offset1:1
	v_add_u32_e32 v2, 0x1868, v7
	ds_write2_b32 v2, v52, v53 offset1:1
	v_add_u32_e32 v2, 0x1c70, v7
	ds_write2_b32 v2, v54, v55 offset1:1
	v_add_u32_e32 v2, 0x1c78, v7
	ds_write2_b32 v2, v56, v57 offset1:1
	v_add_u32_e32 v2, 0x2080, v7
	ds_write2_b32 v2, v58, v59 offset1:1
	v_add_u32_e32 v2, 0x2088, v7
	ds_write2_b32 v2, v60, v61 offset1:1
	v_add_u32_e32 v2, 0x2490, v7
	ds_write2_b32 v2, v62, v63 offset1:1
	v_add_u32_e32 v2, 0x2498, v7
	ds_write2_b32 v2, v64, v65 offset1:1
	v_add_u32_e32 v2, 0x28a0, v7
	ds_write2_b32 v2, v66, v67 offset1:1
	v_add_u32_e32 v2, 0x28a8, v7
	ds_write2_b32 v2, v68, v69 offset1:1
	v_add_u32_e32 v2, 0x2cb0, v7
	ds_write2_b32 v2, v70, v71 offset1:1
	v_add_u32_e32 v2, 0x2cb8, v7
	ds_write2_b32 v2, v72, v73 offset1:1
	v_add_u32_e32 v2, 0x30c0, v7
	ds_write2_b32 v2, v74, v75 offset1:1
	v_add_u32_e32 v2, 0x30c8, v7
	ds_write2_b32 v2, v76, v77 offset1:1
	v_add_u32_e32 v2, 0x34d0, v7
	ds_write2_b32 v2, v78, v79 offset1:1
	v_add_u32_e32 v2, 0x34d8, v7
	ds_write2_b32 v2, v80, v81 offset1:1
	v_add_u32_e32 v2, 0x38e0, v7
	ds_write2_b32 v2, v82, v83 offset1:1
	v_add_u32_e32 v2, 0x38e8, v7
	ds_write2_b32 v2, v84, v85 offset1:1
	v_add_u32_e32 v2, 0x3cf0, v7
	ds_write2_b32 v2, v86, v87 offset1:1
	v_add_u32_e32 v2, 0x3cf8, v7
	ds_write2_b32 v2, v88, v89 offset1:1
	s_waitcnt lgkmcnt(0)
	ds_read2_b32 v[32:33], v9 offset0:65 offset1:73
	ds_read2_b32 v[34:35], v9 offset1:8
	ds_read2_b32 v[36:37], v9 offset0:130 offset1:138
	ds_read2_b32 v[38:39], v9 offset0:195 offset1:203
	ds_read2_b32 v[40:41], v27 offset0:4 offset1:12
	ds_read2_b32 v[42:43], v27 offset0:69 offset1:77
	ds_read2_b32 v[44:45], v27 offset0:134 offset1:142
	ds_read2_b32 v[46:47], v27 offset0:199 offset1:207
	s_waitcnt lgkmcnt(7)
	v_bfe_u32 v25, v32, 16, 1
	s_waitcnt lgkmcnt(6)
	v_bfe_u32 v2, v34, 16, 1
	v_add3_u32 v2, v34, v2, s81
	v_lshrrev_b32_e32 v2, 16, v2
	v_add3_u32 v25, v32, v25, s81
	v_and_or_b32 v28, v25, s39, v2
	s_waitcnt lgkmcnt(5)
	v_bfe_u32 v2, v36, 16, 1
	v_add3_u32 v2, v36, v2, s81
	s_waitcnt lgkmcnt(4)
	v_bfe_u32 v25, v38, 16, 1
	v_lshrrev_b32_e32 v2, 16, v2
	v_add3_u32 v25, v38, v25, s81
	v_and_or_b32 v29, v25, s39, v2
	s_waitcnt lgkmcnt(3)
	v_bfe_u32 v2, v40, 16, 1
	v_add3_u32 v2, v40, v2, s81
	s_waitcnt lgkmcnt(2)
	v_bfe_u32 v25, v42, 16, 1
	v_lshrrev_b32_e32 v2, 16, v2
	v_add3_u32 v25, v42, v25, s81
	v_and_or_b32 v30, v25, s39, v2
	s_waitcnt lgkmcnt(1)
	v_bfe_u32 v2, v44, 16, 1
	v_add3_u32 v2, v44, v2, s81
	s_waitcnt lgkmcnt(0)
	v_bfe_u32 v25, v46, 16, 1
	v_lshrrev_b32_e32 v2, 16, v2
	v_add3_u32 v25, v46, v25, s81
	v_and_or_b32 v31, v25, s39, v2
	v_add_u32_e32 v25, s18, v8
	v_add_u32_e32 v26, s23, v25
	v_cmp_lt_i32_e32 vcc, s41, v26
	v_mov_b32_e32 v51, v3
	s_nop 0
	v_cndmask_b32_e32 v2, 0, v247, vcc
	v_subrev_u32_e32 v2, s2, v2
	v_add_u32_e32 v2, v25, v2
	v_ashrrev_i32_e32 v48, 7, v2
	v_cndmask_b32_e32 v32, 0, v248, vcc
	v_ashrrev_i32_e32 v49, 31, v48
	v_and_or_b32 v32, v26, s40, v32
	v_lshlrev_b64 v[48:49], 20, v[48:49]
	v_lshl_add_u64 v[48:49], s[0:1], 0, v[48:49]
	v_lshlrev_b32_e32 v2, 7, v32
	v_lshl_add_u64 v[48:49], v[48:49], 0, v[2:3]
	v_lshlrev_b32_e32 v2, 1, v6
	v_lshl_add_u64 v[48:49], v[48:49], 0, v[2:3]
	global_store_dwordx4 v[48:49], v[28:31], off
	v_bfe_u32 v32, v47, 16, 1
	v_add3_u32 v32, v47, v32, s81
	v_bfe_u32 v28, v35, 16, 1
	v_add3_u32 v28, v35, v28, s81
	v_bfe_u32 v29, v33, 16, 1
	v_lshrrev_b32_e32 v28, 16, v28
	v_add3_u32 v29, v33, v29, s81
	v_and_or_b32 v28, v29, s39, v28
	v_bfe_u32 v29, v37, 16, 1
	v_add3_u32 v29, v37, v29, s81
	v_bfe_u32 v30, v39, 16, 1
	v_lshrrev_b32_e32 v29, 16, v29
	v_add3_u32 v30, v39, v30, s81
	v_and_or_b32 v29, v30, s39, v29
	v_bfe_u32 v30, v41, 16, 1
	v_add3_u32 v30, v41, v30, s81
	v_bfe_u32 v31, v43, 16, 1
	v_lshrrev_b32_e32 v30, 16, v30
	v_add3_u32 v31, v43, v31, s81
	v_and_or_b32 v30, v31, s39, v30
	v_bfe_u32 v31, v45, 16, 1
	v_add3_u32 v31, v45, v31, s81
	v_lshrrev_b32_e32 v31, 16, v31
	v_and_or_b32 v31, v32, s39, v31
	v_add_u32_e32 v32, 8, v26
	v_cmp_lt_i32_e32 vcc, s41, v32
	v_mov_b32_e32 v35, v3
	s_nop 0
	v_cndmask_b32_e32 v33, 0, v247, vcc
	v_subrev_u32_e32 v33, s2, v33
	v_add3_u32 v33, v25, v33, 8
	v_cndmask_b32_e32 v34, 0, v248, vcc
	v_and_or_b32 v34, v32, s40, v34
	v_ashrrev_i32_e32 v32, 7, v33
	v_ashrrev_i32_e32 v33, 31, v32
	v_lshlrev_b64 v[32:33], 20, v[32:33]
	v_lshl_add_u64 v[32:33], s[0:1], 0, v[32:33]
	v_lshlrev_b32_e32 v34, 7, v34
	v_lshl_add_u64 v[32:33], v[32:33], 0, v[34:35]
	v_lshl_add_u64 v[32:33], v[32:33], 0, v[2:3]
	global_store_dwordx4 v[32:33], v[28:31], off
	ds_read2_b32 v[32:33], v9 offset0:16 offset1:24
	ds_read2_b32 v[34:35], v9 offset0:81 offset1:89
	ds_read2_b32 v[36:37], v9 offset0:146 offset1:154
	ds_read2_b32 v[38:39], v9 offset0:211 offset1:219
	ds_read2_b32 v[40:41], v27 offset0:20 offset1:28
	ds_read2_b32 v[42:43], v27 offset0:85 offset1:93
	ds_read2_b32 v[44:45], v27 offset0:150 offset1:158
	ds_read2_b32 v[46:47], v27 offset0:215 offset1:223
	s_waitcnt lgkmcnt(7)
	v_bfe_u32 v28, v32, 16, 1
	v_add3_u32 v28, v32, v28, s81
	s_waitcnt lgkmcnt(6)
	v_bfe_u32 v29, v34, 16, 1
	v_lshrrev_b32_e32 v28, 16, v28
	v_add3_u32 v29, v34, v29, s81
	v_and_or_b32 v28, v29, s39, v28
	s_waitcnt lgkmcnt(5)
	v_bfe_u32 v29, v36, 16, 1
	v_add3_u32 v29, v36, v29, s81
	s_waitcnt lgkmcnt(4)
	v_bfe_u32 v30, v38, 16, 1
	v_lshrrev_b32_e32 v29, 16, v29
	v_add3_u32 v30, v38, v30, s81
	v_and_or_b32 v29, v30, s39, v29
	s_waitcnt lgkmcnt(3)
	v_bfe_u32 v30, v40, 16, 1
	v_add3_u32 v30, v40, v30, s81
	s_waitcnt lgkmcnt(2)
	v_bfe_u32 v31, v42, 16, 1
	v_lshrrev_b32_e32 v30, 16, v30
	v_add3_u32 v31, v42, v31, s81
	v_and_or_b32 v30, v31, s39, v30
	s_waitcnt lgkmcnt(1)
	v_bfe_u32 v31, v44, 16, 1
	v_add3_u32 v31, v44, v31, s81
	s_waitcnt lgkmcnt(0)
	v_bfe_u32 v32, v46, 16, 1
	v_lshrrev_b32_e32 v31, 16, v31
	v_add3_u32 v32, v46, v32, s81
	v_and_or_b32 v31, v32, s39, v31
	v_add_u32_e32 v32, 16, v26
	v_cmp_lt_i32_e32 vcc, s41, v32
	s_nop 1
	v_cndmask_b32_e32 v34, 0, v247, vcc
	v_subrev_u32_e32 v34, s2, v34
	v_add3_u32 v34, v25, v34, 16
	v_ashrrev_i32_e32 v48, 7, v34
	v_cndmask_b32_e32 v36, 0, v248, vcc
	v_ashrrev_i32_e32 v49, 31, v48
	v_and_or_b32 v32, v32, s40, v36
	v_lshlrev_b64 v[48:49], 20, v[48:49]
	v_lshl_add_u64 v[48:49], s[0:1], 0, v[48:49]
	v_lshlrev_b32_e32 v50, 7, v32
	v_lshl_add_u64 v[48:49], v[48:49], 0, v[50:51]
	v_lshl_add_u64 v[48:49], v[48:49], 0, v[2:3]
	global_store_dwordx4 v[48:49], v[28:31], off
	v_bfe_u32 v32, v47, 16, 1
	v_add3_u32 v32, v47, v32, s81
	v_bfe_u32 v28, v33, 16, 1
	v_add3_u32 v28, v33, v28, s81
	v_bfe_u32 v29, v35, 16, 1
	v_lshrrev_b32_e32 v28, 16, v28
	v_add3_u32 v29, v35, v29, s81
	v_and_or_b32 v28, v29, s39, v28
	v_bfe_u32 v29, v37, 16, 1
	v_add3_u32 v29, v37, v29, s81
	v_bfe_u32 v30, v39, 16, 1
	v_lshrrev_b32_e32 v29, 16, v29
	v_add3_u32 v30, v39, v30, s81
	v_and_or_b32 v29, v30, s39, v29
	v_bfe_u32 v30, v41, 16, 1
	v_add3_u32 v30, v41, v30, s81
	v_bfe_u32 v31, v43, 16, 1
	v_lshrrev_b32_e32 v30, 16, v30
	v_add3_u32 v31, v43, v31, s81
	v_and_or_b32 v30, v31, s39, v30
	v_bfe_u32 v31, v45, 16, 1
	v_add3_u32 v31, v45, v31, s81
	v_lshrrev_b32_e32 v31, 16, v31
	v_and_or_b32 v31, v32, s39, v31
	v_add_u32_e32 v32, 24, v26
	v_cmp_lt_i32_e32 vcc, s41, v32
	v_mov_b32_e32 v35, v3
	s_nop 0
	v_cndmask_b32_e32 v33, 0, v247, vcc
	v_subrev_u32_e32 v33, s2, v33
	v_add3_u32 v33, v25, v33, 24
	v_cndmask_b32_e32 v34, 0, v248, vcc
	v_and_or_b32 v34, v32, s40, v34
	v_ashrrev_i32_e32 v32, 7, v33
	v_ashrrev_i32_e32 v33, 31, v32
	v_lshlrev_b64 v[32:33], 20, v[32:33]
	v_lshl_add_u64 v[32:33], s[0:1], 0, v[32:33]
	v_lshlrev_b32_e32 v34, 7, v34
	v_lshl_add_u64 v[32:33], v[32:33], 0, v[34:35]
	v_lshl_add_u64 v[32:33], v[32:33], 0, v[2:3]
	global_store_dwordx4 v[32:33], v[28:31], off
	ds_read2_b32 v[32:33], v9 offset0:32 offset1:40
	ds_read2_b32 v[34:35], v9 offset0:97 offset1:105
	ds_read2_b32 v[36:37], v9 offset0:162 offset1:170
	ds_read2_b32 v[38:39], v9 offset0:227 offset1:235
	ds_read2_b32 v[40:41], v27 offset0:36 offset1:44
	ds_read2_b32 v[42:43], v27 offset0:101 offset1:109
	ds_read2_b32 v[44:45], v27 offset0:166 offset1:174
	ds_read2_b32 v[46:47], v27 offset0:231 offset1:239
	s_waitcnt lgkmcnt(7)
	v_bfe_u32 v28, v32, 16, 1
	v_add3_u32 v28, v32, v28, s81
	s_waitcnt lgkmcnt(6)
	v_bfe_u32 v29, v34, 16, 1
	v_lshrrev_b32_e32 v28, 16, v28
	v_add3_u32 v29, v34, v29, s81
	v_and_or_b32 v28, v29, s39, v28
	s_waitcnt lgkmcnt(5)
	v_bfe_u32 v29, v36, 16, 1
	v_add3_u32 v29, v36, v29, s81
	s_waitcnt lgkmcnt(4)
	v_bfe_u32 v30, v38, 16, 1
	v_lshrrev_b32_e32 v29, 16, v29
	v_add3_u32 v30, v38, v30, s81
	v_and_or_b32 v29, v30, s39, v29
	s_waitcnt lgkmcnt(3)
	v_bfe_u32 v30, v40, 16, 1
	v_add3_u32 v30, v40, v30, s81
	s_waitcnt lgkmcnt(2)
	v_bfe_u32 v31, v42, 16, 1
	v_lshrrev_b32_e32 v30, 16, v30
	v_add3_u32 v31, v42, v31, s81
	v_and_or_b32 v30, v31, s39, v30
	s_waitcnt lgkmcnt(1)
	v_bfe_u32 v31, v44, 16, 1
	v_add3_u32 v31, v44, v31, s81
	s_waitcnt lgkmcnt(0)
	v_bfe_u32 v32, v46, 16, 1
	v_lshrrev_b32_e32 v31, 16, v31
	v_add3_u32 v32, v46, v32, s81
	v_and_or_b32 v31, v32, s39, v31
	v_add_u32_e32 v32, 32, v26
	v_cmp_lt_i32_e32 vcc, s41, v32
	s_nop 1
	v_cndmask_b32_e32 v34, 0, v247, vcc
	v_subrev_u32_e32 v34, s2, v34
	v_add3_u32 v34, v25, v34, 32
	v_ashrrev_i32_e32 v48, 7, v34
	v_cndmask_b32_e32 v36, 0, v248, vcc
	v_ashrrev_i32_e32 v49, 31, v48
	v_and_or_b32 v32, v32, s40, v36
	v_lshlrev_b64 v[48:49], 20, v[48:49]
	v_lshl_add_u64 v[48:49], s[0:1], 0, v[48:49]
	v_lshlrev_b32_e32 v50, 7, v32
	v_lshl_add_u64 v[48:49], v[48:49], 0, v[50:51]
	v_lshl_add_u64 v[48:49], v[48:49], 0, v[2:3]
	global_store_dwordx4 v[48:49], v[28:31], off
	v_bfe_u32 v32, v47, 16, 1
	v_add3_u32 v32, v47, v32, s81
	v_bfe_u32 v28, v33, 16, 1
	v_add3_u32 v28, v33, v28, s81
	v_bfe_u32 v29, v35, 16, 1
	v_lshrrev_b32_e32 v28, 16, v28
	v_add3_u32 v29, v35, v29, s81
	v_and_or_b32 v28, v29, s39, v28
	v_bfe_u32 v29, v37, 16, 1
	v_add3_u32 v29, v37, v29, s81
	v_bfe_u32 v30, v39, 16, 1
	v_lshrrev_b32_e32 v29, 16, v29
	v_add3_u32 v30, v39, v30, s81
	v_and_or_b32 v29, v30, s39, v29
	v_bfe_u32 v30, v41, 16, 1
	v_add3_u32 v30, v41, v30, s81
	v_bfe_u32 v31, v43, 16, 1
	v_lshrrev_b32_e32 v30, 16, v30
	v_add3_u32 v31, v43, v31, s81
	v_and_or_b32 v30, v31, s39, v30
	v_bfe_u32 v31, v45, 16, 1
	v_add3_u32 v31, v45, v31, s81
	v_lshrrev_b32_e32 v31, 16, v31
	v_and_or_b32 v31, v32, s39, v31
	v_add_u32_e32 v32, 40, v26
	v_cmp_lt_i32_e32 vcc, s41, v32
	v_mov_b32_e32 v35, v3
	s_nop 0
	v_cndmask_b32_e32 v33, 0, v247, vcc
	v_subrev_u32_e32 v33, s2, v33
	v_add3_u32 v33, v25, v33, 40
	v_cndmask_b32_e32 v34, 0, v248, vcc
	v_and_or_b32 v34, v32, s40, v34
	v_ashrrev_i32_e32 v32, 7, v33
	v_ashrrev_i32_e32 v33, 31, v32
	v_lshlrev_b64 v[32:33], 20, v[32:33]
	v_lshl_add_u64 v[32:33], s[0:1], 0, v[32:33]
	v_lshlrev_b32_e32 v34, 7, v34
	v_lshl_add_u64 v[32:33], v[32:33], 0, v[34:35]
	v_lshl_add_u64 v[32:33], v[32:33], 0, v[2:3]
	global_store_dwordx4 v[32:33], v[28:31], off
	ds_read2_b32 v[32:33], v9 offset0:48 offset1:56
	ds_read2_b32 v[34:35], v9 offset0:113 offset1:121
	ds_read2_b32 v[36:37], v9 offset0:178 offset1:186
	ds_read2_b32 v[38:39], v9 offset0:243 offset1:251
	ds_read2_b32 v[40:41], v27 offset0:52 offset1:60
	ds_read2_b32 v[42:43], v27 offset0:117 offset1:125
	ds_read2_b32 v[44:45], v27 offset0:182 offset1:190
	ds_read2_b32 v[46:47], v27 offset0:247 offset1:255
	s_waitcnt lgkmcnt(7)
	v_bfe_u32 v28, v32, 16, 1
	v_add3_u32 v28, v32, v28, s81
	s_waitcnt lgkmcnt(6)
	v_bfe_u32 v29, v34, 16, 1
	v_lshrrev_b32_e32 v28, 16, v28
	v_add3_u32 v29, v34, v29, s81
	v_and_or_b32 v28, v29, s39, v28
	s_waitcnt lgkmcnt(5)
	v_bfe_u32 v29, v36, 16, 1
	v_add3_u32 v29, v36, v29, s81
	s_waitcnt lgkmcnt(4)
	v_bfe_u32 v30, v38, 16, 1
	v_lshrrev_b32_e32 v29, 16, v29
	v_add3_u32 v30, v38, v30, s81
	v_and_or_b32 v29, v30, s39, v29
	s_waitcnt lgkmcnt(3)
	v_bfe_u32 v30, v40, 16, 1
	v_add3_u32 v30, v40, v30, s81
	s_waitcnt lgkmcnt(2)
	v_bfe_u32 v31, v42, 16, 1
	v_lshrrev_b32_e32 v30, 16, v30
	v_add3_u32 v31, v42, v31, s81
	s_waitcnt lgkmcnt(1)
	v_bfe_u32 v27, v44, 16, 1
	v_and_or_b32 v30, v31, s39, v30
	v_add3_u32 v27, v44, v27, s81
	s_waitcnt lgkmcnt(0)
	v_bfe_u32 v31, v46, 16, 1
	v_lshrrev_b32_e32 v27, 16, v27
	v_add3_u32 v31, v46, v31, s81
	v_and_or_b32 v31, v31, s39, v27
	v_add_u32_e32 v27, 48, v26
	v_cmp_lt_i32_e32 vcc, s41, v27
	v_add_u32_e32 v26, 56, v26
	s_nop 0
	v_cndmask_b32_e32 v32, 0, v247, vcc
	v_subrev_u32_e32 v32, s2, v32
	v_add3_u32 v32, v25, v32, 48
	v_ashrrev_i32_e32 v48, 7, v32
	v_cndmask_b32_e32 v34, 0, v248, vcc
	v_ashrrev_i32_e32 v49, 31, v48
	v_and_or_b32 v27, v27, s40, v34
	v_lshlrev_b64 v[48:49], 20, v[48:49]
	v_lshl_add_u64 v[48:49], s[0:1], 0, v[48:49]
	v_lshlrev_b32_e32 v50, 7, v27
	v_lshl_add_u64 v[48:49], v[48:49], 0, v[50:51]
	v_lshl_add_u64 v[48:49], v[48:49], 0, v[2:3]
	v_bfe_u32 v27, v33, 16, 1
	global_store_dwordx4 v[48:49], v[28:31], off
	v_add3_u32 v27, v33, v27, s81
	v_lshrrev_b32_e32 v27, 16, v27
	v_bfe_u32 v28, v35, 16, 1
	v_add3_u32 v28, v35, v28, s81
	v_and_or_b32 v28, v28, s39, v27
	v_bfe_u32 v27, v37, 16, 1
	v_add3_u32 v27, v37, v27, s81
	v_bfe_u32 v29, v39, 16, 1
	v_lshrrev_b32_e32 v27, 16, v27
	v_add3_u32 v29, v39, v29, s81
	v_and_or_b32 v29, v29, s39, v27
	v_bfe_u32 v27, v41, 16, 1
	v_add3_u32 v27, v41, v27, s81
	v_bfe_u32 v30, v43, 16, 1
	v_lshrrev_b32_e32 v27, 16, v27
	v_add3_u32 v30, v43, v30, s81
	v_and_or_b32 v30, v30, s39, v27
	v_bfe_u32 v27, v45, 16, 1
	v_add3_u32 v27, v45, v27, s81
	v_bfe_u32 v31, v47, 16, 1
	v_lshrrev_b32_e32 v27, 16, v27
	v_add3_u32 v31, v47, v31, s81
	v_cmp_lt_i32_e32 vcc, s41, v26
	v_and_or_b32 v31, v31, s39, v27
	v_mov_b32_e32 v33, v3
	v_cndmask_b32_e32 v27, 0, v247, vcc
	v_subrev_u32_e32 v27, s2, v27
	v_add3_u32 v25, v25, v27, 56
	v_cndmask_b32_e32 v27, 0, v248, vcc
	v_and_or_b32 v32, v26, s40, v27
	v_ashrrev_i32_e32 v26, 7, v25
	v_ashrrev_i32_e32 v27, 31, v26
	v_lshlrev_b64 v[26:27], 20, v[26:27]
	v_lshl_add_u64 v[26:27], s[0:1], 0, v[26:27]
	v_lshlrev_b32_e32 v32, 7, v32
	v_lshl_add_u64 v[26:27], v[26:27], 0, v[32:33]
	v_lshl_add_u64 v[26:27], v[26:27], 0, v[2:3]
	global_store_dwordx4 v[26:27], v[28:31], off
	s_waitcnt lgkmcnt(0)
	s_branch .LBB0_944
